# main loops (except in-projection): the four B-side fragment reads of phase 5 issued one phase earlier (phase 4 had none, phase 5 twelve), guarded by a vmcnt(10) landing wait before the phase-3 barrier
# speedup vs baseline: 1.0125x; 1.0013x over previous
.LBB0_940:
	s_add_u32 s20, s14, 0x100
	s_addc_u32 s21, s15, 0
	s_add_i32 s40, 0, 0x10000
	v_add_u32_e32 v32, s40, v209
	ds_read_b128 v[132:135], v32
	ds_read_b128 v[140:143], v32 offset:2048
	ds_read_b128 v[136:139], v32 offset:1024
	ds_read_b128 v[144:147], v32 offset:3072
	s_cmp_eq_u32 s11, 12
	s_cselect_b32 s25, s17, s21
	s_cselect_b32 s24, s16, s20
	s_cselect_b32 s23, s19, s3
	s_cselect_b32 s22, s18, s1
	v_lshl_add_u64 v[34:35], s[14:15], 0, v[200:201]
	s_add_i32 m0, s30, 0xc000
	ds_read_b128 v[148:151], v211
	ds_read_b128 v[156:159], v211 offset:2048
	ds_read_b128 v[164:167], v211 offset:4096
	ds_read_b128 v[172:175], v211 offset:6144
	ds_read_b128 v[152:155], v211 offset:1024
	ds_read_b128 v[160:163], v211 offset:3072
	ds_read_b128 v[168:171], v211 offset:5120
	ds_read_b128 v[176:179], v211 offset:7168
	global_load_lds_dwordx4 v[34:35], off
	v_lshl_add_u64 v[34:35], s[14:15], 0, v[202:203]
	s_add_i32 m0, s30, 0xe000
	s_nop 0
	global_load_lds_dwordx4 v[34:35], off
	s_waitcnt lgkmcnt(8)
	s_barrier
	s_waitcnt lgkmcnt(7)
	s_setprio 1
	v_mfma_f32_16x16x32_f16 v[128:131], v[132:135], v[148:151], v[128:131]
	v_mfma_f32_16x16x32_f16 v[124:127], v[140:143], v[148:151], v[124:127]
	s_waitcnt lgkmcnt(6)
	v_mfma_f32_16x16x32_f16 v[120:123], v[132:135], v[156:159], v[120:123]
	v_mfma_f32_16x16x32_f16 v[116:119], v[140:143], v[156:159], v[116:119]
	s_waitcnt lgkmcnt(5)
	v_mfma_f32_16x16x32_f16 v[112:115], v[132:135], v[164:167], v[112:115]
	v_mfma_f32_16x16x32_f16 v[108:111], v[140:143], v[164:167], v[108:111]
	s_waitcnt lgkmcnt(4)
	v_mfma_f32_16x16x32_f16 v[104:107], v[132:135], v[172:175], v[104:107]
	v_mfma_f32_16x16x32_f16 v[100:103], v[140:143], v[172:175], v[100:103]
	s_waitcnt lgkmcnt(3)
	v_mfma_f32_16x16x32_f16 v[128:131], v[136:139], v[152:155], v[128:131]
	v_mfma_f32_16x16x32_f16 v[124:127], v[144:147], v[152:155], v[124:127]
	s_waitcnt lgkmcnt(2)
	v_mfma_f32_16x16x32_f16 v[120:123], v[136:139], v[160:163], v[120:123]
	v_mfma_f32_16x16x32_f16 v[116:119], v[144:147], v[160:163], v[116:119]
	s_waitcnt lgkmcnt(1)
	v_mfma_f32_16x16x32_f16 v[112:115], v[136:139], v[168:171], v[112:115]
	v_mfma_f32_16x16x32_f16 v[108:111], v[144:147], v[168:171], v[108:111]
	s_waitcnt lgkmcnt(0)
	v_mfma_f32_16x16x32_f16 v[104:107], v[136:139], v[176:179], v[104:107]
	v_mfma_f32_16x16x32_f16 v[100:103], v[144:147], v[176:179], v[100:103]
	s_setprio 0
	s_barrier
	s_add_i32 s41, 0, 0x14000
	s_add_i32 s14, s40, s29
	v_add_u32_e32 v32, s41, v209
	v_lshl_add_u64 v[204:205], s[22:23], 0, v[196:197]
	s_mov_b32 m0, s14
	ds_read_b128 v[180:183], v32
	ds_read_b128 v[188:191], v32 offset:2048
	ds_read_b128 v[184:187], v32 offset:1024
	ds_read_b128 v[192:195], v32 offset:3072
	global_load_lds_dwordx4 v[204:205], off
	v_lshl_add_u64 v[206:207], s[22:23], 0, v[198:199]
	s_add_i32 m0, s14, 0x2000
	s_nop 0
	global_load_lds_dwordx4 v[206:207], off
	s_barrier
	s_waitcnt lgkmcnt(2)
	s_setprio 1
	v_mfma_f32_16x16x32_f16 v[96:99], v[180:183], v[148:151], v[96:99]
	v_mfma_f32_16x16x32_f16 v[92:95], v[188:191], v[148:151], v[92:95]
	v_mfma_f32_16x16x32_f16 v[88:91], v[180:183], v[156:159], v[88:91]
	v_mfma_f32_16x16x32_f16 v[84:87], v[188:191], v[156:159], v[84:87]
	v_mfma_f32_16x16x32_f16 v[80:83], v[180:183], v[164:167], v[80:83]
	v_mfma_f32_16x16x32_f16 v[76:79], v[188:191], v[164:167], v[76:79]
	v_mfma_f32_16x16x32_f16 v[72:75], v[180:183], v[172:175], v[72:75]
	v_mfma_f32_16x16x32_f16 v[68:71], v[188:191], v[172:175], v[68:71]
	s_waitcnt lgkmcnt(0)
	v_mfma_f32_16x16x32_f16 v[96:99], v[184:187], v[152:155], v[96:99]
	v_mfma_f32_16x16x32_f16 v[92:95], v[192:195], v[152:155], v[92:95]
	v_mfma_f32_16x16x32_f16 v[88:91], v[184:187], v[160:163], v[88:91]
	v_mfma_f32_16x16x32_f16 v[84:87], v[192:195], v[160:163], v[84:87]
	v_mfma_f32_16x16x32_f16 v[80:83], v[184:187], v[168:171], v[80:83]
	v_mfma_f32_16x16x32_f16 v[76:79], v[192:195], v[168:171], v[76:79]
	v_mfma_f32_16x16x32_f16 v[72:75], v[184:187], v[176:179], v[72:75]
	v_mfma_f32_16x16x32_f16 v[68:71], v[192:195], v[176:179], v[68:71]
	s_setprio 0
	s_mov_b32 m0, s30
	v_lshl_add_u64 v[212:213], s[24:25], 0, v[196:197]
	s_barrier
	ds_read_b128 v[148:151], v211 offset:16384
	ds_read_b128 v[156:159], v211 offset:18432
	ds_read_b128 v[164:167], v211 offset:20480
	ds_read_b128 v[172:175], v211 offset:22528
	ds_read_b128 v[152:155], v211 offset:17408
	ds_read_b128 v[160:163], v211 offset:19456
	ds_read_b128 v[168:171], v211 offset:21504
	ds_read_b128 v[176:179], v211 offset:23552
	global_load_lds_dwordx4 v[212:213], off
	v_lshl_add_u64 v[214:215], s[24:25], 0, v[198:199]
	s_mov_b32 m0, s31
	s_nop 0
	global_load_lds_dwordx4 v[214:215], off
	s_waitcnt vmcnt(10)
	s_barrier
	s_waitcnt lgkmcnt(7)
	s_setprio 1
	v_mfma_f32_16x16x32_f16 v[64:67], v[132:135], v[148:151], v[64:67]
	v_mfma_f32_16x16x32_f16 v[60:63], v[140:143], v[148:151], v[60:63]
	s_waitcnt lgkmcnt(6)
	v_mfma_f32_16x16x32_f16 v[56:59], v[132:135], v[156:159], v[56:59]
	v_mfma_f32_16x16x32_f16 v[52:55], v[140:143], v[156:159], v[52:55]
	s_waitcnt lgkmcnt(5)
	v_mfma_f32_16x16x32_f16 v[48:51], v[132:135], v[164:167], v[48:51]
	v_mfma_f32_16x16x32_f16 v[44:47], v[140:143], v[164:167], v[44:47]
	s_waitcnt lgkmcnt(4)
	v_mfma_f32_16x16x32_f16 v[40:43], v[132:135], v[172:175], v[40:43]
	v_mfma_f32_16x16x32_f16 v[34:37], v[140:143], v[172:175], v[36:39]
	s_waitcnt lgkmcnt(3)
	v_mfma_f32_16x16x32_f16 v[64:67], v[136:139], v[152:155], v[64:67]
	v_mfma_f32_16x16x32_f16 v[60:63], v[144:147], v[152:155], v[60:63]
	s_waitcnt lgkmcnt(2)
	v_mfma_f32_16x16x32_f16 v[56:59], v[136:139], v[160:163], v[56:59]
	v_mfma_f32_16x16x32_f16 v[52:55], v[144:147], v[160:163], v[52:55]
	s_waitcnt lgkmcnt(1)
	v_mfma_f32_16x16x32_f16 v[48:51], v[136:139], v[168:171], v[48:51]
	v_mfma_f32_16x16x32_f16 v[44:47], v[144:147], v[168:171], v[44:47]
	s_waitcnt lgkmcnt(0)
	v_mfma_f32_16x16x32_f16 v[40:43], v[136:139], v[176:179], v[40:43]
	v_mfma_f32_16x16x32_f16 v[34:37], v[144:147], v[176:179], v[34:37]
	s_setprio 0
	s_barrier
	s_add_u32 s14, s22, 0x40000
	s_addc_u32 s15, s23, 0
	s_add_i32 s40, s41, s29
	v_lshl_add_u64 v[38:39], s[14:15], 0, v[196:197]
	s_mov_b32 m0, s40
	s_nop 0
	global_load_lds_dwordx4 v[38:39], off
	v_lshl_add_u64 v[38:39], s[14:15], 0, v[198:199]
	s_add_i32 m0, s40, 0x2000
	s_nop 0
	global_load_lds_dwordx4 v[38:39], off
	v_add_u32_e32 v32, 0x18000, v209
	ds_read_b128 v[132:135], v32
	ds_read_b128 v[140:143], v32 offset:2048
	ds_read_b128 v[136:139], v32 offset:1024
	ds_read_b128 v[144:147], v32 offset:3072
	s_waitcnt vmcnt(6)
	s_barrier
	s_setprio 1
	v_mfma_f32_16x16x32_f16 v[28:31], v[180:183], v[148:151], v[28:31]
	v_mfma_f32_16x16x32_f16 v[24:27], v[188:191], v[148:151], v[24:27]
	v_mfma_f32_16x16x32_f16 v[20:23], v[180:183], v[156:159], v[20:23]
	v_mfma_f32_16x16x32_f16 v[16:19], v[188:191], v[156:159], v[16:19]
	v_mfma_f32_16x16x32_f16 v[12:15], v[180:183], v[164:167], v[12:15]
	v_mfma_f32_16x16x32_f16 v[8:11], v[188:191], v[164:167], v[8:11]
	v_mfma_f32_16x16x32_f16 v[4:7], v[180:183], v[172:175], v[4:7]
	v_mfma_f32_16x16x32_f16 v[0:3], v[188:191], v[172:175], v[0:3]
	v_mfma_f32_16x16x32_f16 v[28:31], v[184:187], v[152:155], v[28:31]
	v_mfma_f32_16x16x32_f16 v[24:27], v[192:195], v[152:155], v[24:27]
	v_mfma_f32_16x16x32_f16 v[20:23], v[184:187], v[160:163], v[20:23]
	v_mfma_f32_16x16x32_f16 v[16:19], v[192:195], v[160:163], v[16:19]
	v_mfma_f32_16x16x32_f16 v[12:15], v[184:187], v[168:171], v[12:15]
	v_mfma_f32_16x16x32_f16 v[8:11], v[192:195], v[168:171], v[8:11]
	v_mfma_f32_16x16x32_f16 v[4:7], v[184:187], v[176:179], v[4:7]
	v_mfma_f32_16x16x32_f16 v[0:3], v[192:195], v[176:179], v[0:3]
	s_setprio 0
	s_add_i32 s40, 0, 0x18000
	s_barrier
	s_add_u32 s14, s24, 0x40000
	s_addc_u32 s15, s25, 0
	s_mov_b32 m0, s34
	v_lshl_add_u64 v[38:39], s[14:15], 0, v[196:197]
	ds_read_b128 v[148:151], v211 offset:32768
	ds_read_b128 v[156:159], v211 offset:34816
	ds_read_b128 v[164:167], v211 offset:36864
	ds_read_b128 v[172:175], v211 offset:38912
	ds_read_b128 v[152:155], v211 offset:33792
	ds_read_b128 v[160:163], v211 offset:35840
	ds_read_b128 v[168:171], v211 offset:37888
	ds_read_b128 v[176:179], v211 offset:39936
	global_load_lds_dwordx4 v[38:39], off
	v_lshl_add_u64 v[38:39], s[14:15], 0, v[198:199]
	s_mov_b32 m0, s35
	s_nop 0
	global_load_lds_dwordx4 v[38:39], off
	s_waitcnt lgkmcnt(8)
	s_barrier
	s_waitcnt lgkmcnt(7)
	s_setprio 1
	v_mfma_f32_16x16x32_f16 v[128:131], v[132:135], v[148:151], v[128:131]
	v_mfma_f32_16x16x32_f16 v[124:127], v[140:143], v[148:151], v[124:127]
	s_waitcnt lgkmcnt(6)
	v_mfma_f32_16x16x32_f16 v[120:123], v[132:135], v[156:159], v[120:123]
	v_mfma_f32_16x16x32_f16 v[116:119], v[140:143], v[156:159], v[116:119]
	s_waitcnt lgkmcnt(5)
	v_mfma_f32_16x16x32_f16 v[112:115], v[132:135], v[164:167], v[112:115]
	v_mfma_f32_16x16x32_f16 v[108:111], v[140:143], v[164:167], v[108:111]
	s_waitcnt lgkmcnt(4)
	v_mfma_f32_16x16x32_f16 v[104:107], v[132:135], v[172:175], v[104:107]
	v_mfma_f32_16x16x32_f16 v[100:103], v[140:143], v[172:175], v[100:103]
	s_waitcnt lgkmcnt(3)
	v_mfma_f32_16x16x32_f16 v[128:131], v[136:139], v[152:155], v[128:131]
	v_mfma_f32_16x16x32_f16 v[124:127], v[144:147], v[152:155], v[124:127]
	s_waitcnt lgkmcnt(2)
	v_mfma_f32_16x16x32_f16 v[120:123], v[136:139], v[160:163], v[120:123]
	v_mfma_f32_16x16x32_f16 v[116:119], v[144:147], v[160:163], v[116:119]
	s_waitcnt lgkmcnt(1)
	v_mfma_f32_16x16x32_f16 v[112:115], v[136:139], v[168:171], v[112:115]
	v_mfma_f32_16x16x32_f16 v[108:111], v[144:147], v[168:171], v[108:111]
	s_waitcnt lgkmcnt(0)
	v_mfma_f32_16x16x32_f16 v[104:107], v[136:139], v[176:179], v[104:107]
	v_mfma_f32_16x16x32_f16 v[100:103], v[144:147], v[176:179], v[100:103]
	s_setprio 0
	s_barrier
	s_add_i32 s24, 0, 0x1c000
	s_add_i32 s14, s40, s29
	v_add_u32_e32 v32, s24, v209
	v_lshl_add_u64 v[38:39], v[204:205], 0, s[84:85]
	s_mov_b32 m0, s14
	ds_read_b128 v[180:183], v32
	ds_read_b128 v[188:191], v32 offset:2048
	ds_read_b128 v[184:187], v32 offset:1024
	ds_read_b128 v[192:195], v32 offset:3072
	global_load_lds_dwordx4 v[38:39], off
	v_lshl_add_u64 v[38:39], v[206:207], 0, s[84:85]
	s_add_i32 m0, s14, 0x2000
	s_nop 0
	global_load_lds_dwordx4 v[38:39], off
	s_barrier
	s_waitcnt lgkmcnt(2)
	s_setprio 1
	v_mfma_f32_16x16x32_f16 v[96:99], v[180:183], v[148:151], v[96:99]
	v_mfma_f32_16x16x32_f16 v[92:95], v[188:191], v[148:151], v[92:95]
	v_mfma_f32_16x16x32_f16 v[88:91], v[180:183], v[156:159], v[88:91]
	v_mfma_f32_16x16x32_f16 v[84:87], v[188:191], v[156:159], v[84:87]
	v_mfma_f32_16x16x32_f16 v[80:83], v[180:183], v[164:167], v[80:83]
	v_mfma_f32_16x16x32_f16 v[76:79], v[188:191], v[164:167], v[76:79]
	v_mfma_f32_16x16x32_f16 v[72:75], v[180:183], v[172:175], v[72:75]
	v_mfma_f32_16x16x32_f16 v[68:71], v[188:191], v[172:175], v[68:71]
	s_waitcnt lgkmcnt(0)
	v_mfma_f32_16x16x32_f16 v[96:99], v[184:187], v[152:155], v[96:99]
	v_mfma_f32_16x16x32_f16 v[92:95], v[192:195], v[152:155], v[92:95]
	v_mfma_f32_16x16x32_f16 v[88:91], v[184:187], v[160:163], v[88:91]
	v_mfma_f32_16x16x32_f16 v[84:87], v[192:195], v[160:163], v[84:87]
	v_mfma_f32_16x16x32_f16 v[80:83], v[184:187], v[168:171], v[80:83]
	v_mfma_f32_16x16x32_f16 v[76:79], v[192:195], v[168:171], v[76:79]
	v_mfma_f32_16x16x32_f16 v[72:75], v[184:187], v[176:179], v[72:75]
	v_mfma_f32_16x16x32_f16 v[68:71], v[192:195], v[176:179], v[68:71]
	s_setprio 0
	s_mov_b32 m0, s36
	v_lshl_add_u64 v[38:39], v[212:213], 0, s[84:85]
	s_barrier
	ds_read_b128 v[148:151], v211 offset:49152
	ds_read_b128 v[156:159], v211 offset:51200
	ds_read_b128 v[164:167], v211 offset:53248
	ds_read_b128 v[172:175], v211 offset:55296
	ds_read_b128 v[152:155], v211 offset:50176
	ds_read_b128 v[160:163], v211 offset:52224
	ds_read_b128 v[168:171], v211 offset:54272
	ds_read_b128 v[176:179], v211 offset:56320
	global_load_lds_dwordx4 v[38:39], off
	v_lshl_add_u64 v[38:39], v[214:215], 0, s[84:85]
	s_mov_b32 m0, s37
	s_nop 0
	global_load_lds_dwordx4 v[38:39], off
	s_barrier
	s_waitcnt lgkmcnt(7)
	s_setprio 1
	v_mfma_f32_16x16x32_f16 v[64:67], v[132:135], v[148:151], v[64:67]
	v_mfma_f32_16x16x32_f16 v[60:63], v[140:143], v[148:151], v[60:63]
	s_waitcnt lgkmcnt(6)
	v_mfma_f32_16x16x32_f16 v[56:59], v[132:135], v[156:159], v[56:59]
	v_mfma_f32_16x16x32_f16 v[52:55], v[140:143], v[156:159], v[52:55]
	s_waitcnt lgkmcnt(5)
	v_mfma_f32_16x16x32_f16 v[48:51], v[132:135], v[164:167], v[48:51]
	v_mfma_f32_16x16x32_f16 v[44:47], v[140:143], v[164:167], v[44:47]
	s_waitcnt lgkmcnt(4)
	v_mfma_f32_16x16x32_f16 v[38:41], v[132:135], v[172:175], v[40:43]
	v_mfma_f32_16x16x32_f16 v[34:37], v[140:143], v[172:175], v[34:37]
	s_waitcnt lgkmcnt(3)
	v_mfma_f32_16x16x32_f16 v[64:67], v[136:139], v[152:155], v[64:67]
	v_mfma_f32_16x16x32_f16 v[60:63], v[144:147], v[152:155], v[60:63]
	s_waitcnt lgkmcnt(2)
	v_mfma_f32_16x16x32_f16 v[56:59], v[136:139], v[160:163], v[56:59]
	v_mfma_f32_16x16x32_f16 v[52:55], v[144:147], v[160:163], v[52:55]
	s_waitcnt lgkmcnt(1)
	v_mfma_f32_16x16x32_f16 v[48:51], v[136:139], v[168:171], v[48:51]
	v_mfma_f32_16x16x32_f16 v[44:47], v[144:147], v[168:171], v[44:47]
	s_waitcnt lgkmcnt(0)
	v_mfma_f32_16x16x32_f16 v[40:43], v[136:139], v[176:179], v[38:41]
	v_mfma_f32_16x16x32_f16 v[36:39], v[144:147], v[176:179], v[34:37]
	s_setprio 0
	s_barrier
	s_add_u32 s14, s22, 0x40080
	s_addc_u32 s15, s23, 0
	s_add_i32 s22, s24, s29
	v_lshl_add_u64 v[34:35], s[14:15], 0, v[196:197]
	s_mov_b32 m0, s22
	s_nop 0
	global_load_lds_dwordx4 v[34:35], off
	v_lshl_add_u64 v[34:35], s[14:15], 0, v[198:199]
	s_add_i32 m0, s22, 0x2000
	s_nop 0
	global_load_lds_dwordx4 v[34:35], off
	s_waitcnt vmcnt(6)
	s_barrier
	s_setprio 1
	v_mfma_f32_16x16x32_f16 v[28:31], v[180:183], v[148:151], v[28:31]
	v_mfma_f32_16x16x32_f16 v[24:27], v[188:191], v[148:151], v[24:27]
	v_mfma_f32_16x16x32_f16 v[20:23], v[180:183], v[156:159], v[20:23]
	v_mfma_f32_16x16x32_f16 v[16:19], v[188:191], v[156:159], v[16:19]
	v_mfma_f32_16x16x32_f16 v[12:15], v[180:183], v[164:167], v[12:15]
	v_mfma_f32_16x16x32_f16 v[8:11], v[188:191], v[164:167], v[8:11]
	v_mfma_f32_16x16x32_f16 v[4:7], v[180:183], v[172:175], v[4:7]
	v_mfma_f32_16x16x32_f16 v[0:3], v[188:191], v[172:175], v[0:3]
	v_mfma_f32_16x16x32_f16 v[28:31], v[184:187], v[152:155], v[28:31]
	v_mfma_f32_16x16x32_f16 v[24:27], v[192:195], v[152:155], v[24:27]
	v_mfma_f32_16x16x32_f16 v[20:23], v[184:187], v[160:163], v[20:23]
	v_mfma_f32_16x16x32_f16 v[16:19], v[192:195], v[160:163], v[16:19]
	v_mfma_f32_16x16x32_f16 v[12:15], v[184:187], v[168:171], v[12:15]
	v_mfma_f32_16x16x32_f16 v[8:11], v[192:195], v[168:171], v[8:11]
	v_mfma_f32_16x16x32_f16 v[4:7], v[184:187], v[176:179], v[4:7]
	v_mfma_f32_16x16x32_f16 v[0:3], v[192:195], v[176:179], v[0:3]
	s_setprio 0
	s_add_i32 s11, s11, 2
	s_add_u32 s1, s1, 0x100
	s_addc_u32 s3, s3, 0
	s_cmp_gt_u32 s11, 13
	s_mov_b64 s[14:15], s[20:21]
	s_barrier
	s_cbranch_scc0 .LBB0_940
	v_lshl_add_u32 v34, s12, 8, v208
	v_lshl_or_b32 v156, s10, 8, v210
	s_cmp_lg_u32 s13, 0
	s_cselect_b64 s[10:11], -1, 0
	s_cmp_eq_u32 s13, 0
	v_ashrrev_i32_e32 v157, 31, v156
	v_ashrrev_i32_e32 v35, 31, v34
	v_mad_i64_i32 v[158:159], s[12:13], v34, s33, 0
	v_or_b32_e32 v160, 16, v34
	v_or_b32_e32 v162, 32, v34
	v_or_b32_e32 v164, 48, v34
	s_cbranch_scc1 .LBB0_946
	v_lshl_add_u64 v[132:133], s[70:71], 0, v[158:159]
	v_lshlrev_b64 v[166:167], 1, v[156:157]
	v_lshl_add_u64 v[132:133], v[132:133], 0, v[166:167]
	s_mov_b64 s[16:17], 0x2800
	v_mov_b64_e32 v[168:169], s[70:71]
	s_movk_i32 s1, 0x2000
	v_lshl_add_u64 v[134:135], v[132:133], 0, s[16:17]
	v_mad_i64_i32 v[136:137], s[12:13], v160, s33, v[168:169]
	v_add_co_u32_e32 v132, vcc, s1, v132
	v_lshl_add_u64 v[136:137], v[136:137], 0, v[166:167]
	s_nop 0
	v_addc_co_u32_e32 v133, vcc, 0, v133, vcc
	v_lshl_add_u64 v[138:139], v[136:137], 0, s[16:17]
	v_mad_i64_i32 v[140:141], s[12:13], v162, s33, v[168:169]
	v_add_co_u32_e32 v136, vcc, s1, v136
	v_lshl_add_u64 v[140:141], v[140:141], 0, v[166:167]
	s_nop 0
	v_addc_co_u32_e32 v137, vcc, 0, v137, vcc
	v_mad_i64_i32 v[144:145], s[12:13], v164, s33, v[168:169]
	global_load_dwordx4 v[170:173], v[132:133], off offset:2048
	global_load_dwordx4 v[152:155], v[136:137], off offset:2048
	global_load_dwordx4 v[174:177], v[134:135], off offset:256
	global_load_dwordx4 v[148:151], v[138:139], off offset:256
	v_add_co_u32_e32 v132, vcc, s1, v140
	v_lshl_add_u64 v[144:145], v[144:145], 0, v[166:167]
	s_nop 0
	v_addc_co_u32_e32 v133, vcc, 0, v141, vcc
	v_add_co_u32_e32 v134, vcc, s1, v144
	v_lshl_add_u64 v[142:143], v[140:141], 0, s[16:17]
	s_nop 0
	v_addc_co_u32_e32 v135, vcc, 0, v145, vcc
	v_lshl_add_u64 v[178:179], v[144:145], 0, s[16:17]
	global_load_dwordx4 v[144:147], v[132:133], off offset:2048
	global_load_dwordx4 v[136:139], v[134:135], off offset:2048
	s_nop 0
	global_load_dwordx4 v[140:143], v[142:143], off offset:256
	s_nop 0
	global_load_dwordx4 v[132:135], v[178:179], off offset:256
	v_ashrrev_i32_e32 v161, 31, v160
	v_ashrrev_i32_e32 v163, 31, v162
	v_ashrrev_i32_e32 v165, 31, v164
	s_waitcnt vmcnt(0)
	v_cvt_f32_f16_e32 v32, v170
	v_cvt_f32_f16_sdwa v170, v170 dst_sel:DWORD dst_unused:UNUSED_PAD src0_sel:WORD_1
	v_lshlrev_b64 v[178:179], 11, v[34:35]
	v_readlane_b32 s14, v252, 9
	v_max_f32_e32 v32, 0xc1f00000, v32
	v_max_f32_e32 v35, 0xc1f00000, v170
	v_cvt_f32_f16_e32 v170, v171
	v_cvt_f32_f16_sdwa v171, v171 dst_sel:DWORD dst_unused:UNUSED_PAD src0_sel:WORD_1
	v_mul_f32_e32 v35, 0xbfb8aa3b, v35
	v_exp_f32_e32 v35, v35
	v_max_f32_e32 v170, 0xc1f00000, v170
	v_mul_f32_e32 v170, 0xbfb8aa3b, v170
	v_exp_f32_e32 v180, v170
	v_max_f32_e32 v170, 0xc1f00000, v171
	v_mul_f32_e32 v170, 0xbfb8aa3b, v170
	v_cvt_f32_f16_e32 v171, v172
	v_exp_f32_e32 v181, v170
	v_cvt_f32_f16_sdwa v170, v172 dst_sel:DWORD dst_unused:UNUSED_PAD src0_sel:WORD_1
	v_mul_f32_e32 v32, 0xbfb8aa3b, v32
	v_max_f32_e32 v171, 0xc1f00000, v171
	v_mul_f32_e32 v171, 0xbfb8aa3b, v171
	v_max_f32_e32 v170, 0xc1f00000, v170
	v_mul_f32_e32 v170, 0xbfb8aa3b, v170
	v_exp_f32_e32 v182, v171
	v_cvt_f32_f16_e32 v171, v173
	v_exp_f32_e32 v183, v170
	v_cvt_f32_f16_sdwa v170, v173 dst_sel:DWORD dst_unused:UNUSED_PAD src0_sel:WORD_1
	v_exp_f32_e32 v32, v32
	v_max_f32_e32 v171, 0xc1f00000, v171
	v_mul_f32_e32 v171, 0xbfb8aa3b, v171
	v_max_f32_e32 v170, 0xc1f00000, v170
	v_mul_f32_e32 v170, 0xbfb8aa3b, v170
	v_add_f32_e32 v35, 1.0, v35
	v_exp_f32_e32 v184, v171
	v_exp_f32_e32 v185, v170
	v_rcp_f32_e32 v170, v35
	v_add_f32_e32 v35, 1.0, v180
	v_rcp_f32_e32 v171, v35
	v_add_f32_e32 v35, 1.0, v181
	v_add_f32_e32 v32, 1.0, v32
	v_rcp_f32_e32 v172, v35
	v_add_f32_e32 v35, 1.0, v182
	v_rcp_f32_e32 v32, v32
	v_rcp_f32_e32 v173, v35
	v_add_f32_e32 v35, 1.0, v183
	v_rcp_f32_e32 v180, v35
	v_add_f32_e32 v35, 1.0, v184
	v_rcp_f32_e32 v181, v35
	v_mov_b32_e32 v182, v129
	v_mov_b32_e32 v183, v130
	v_pk_mul_f32 v[170:171], v[182:183], v[170:171]
	v_pk_mov_b32 v[182:183], v[130:131], v[124:125] op_sel:[1,0]
	v_add_f32_e32 v35, 1.0, v185
	v_fma_mixlo_f16 v32, v128, v32, 0
	v_cvt_pk_f16_f32 v171, v170, v171
	v_pk_mul_f32 v[172:173], v[182:183], v[172:173]
	v_rcp_f32_e32 v35, v35
	v_pack_b32_f16 v170, v32, v171
	v_cvt_pk_f16_f32 v32, v172, v173
	v_mov_b32_e32 v172, v125
	v_mov_b32_e32 v173, v126
	v_pk_mul_f32 v[172:173], v[172:173], v[180:181]
	v_readlane_b32 s15, v252, 10
	v_cvt_pk_f16_f32 v173, v172, v173
	v_alignbit_b32 v172, v173, v32, 16
	v_lshrrev_b32_e32 v173, 16, v173
	v_lshl_add_u64 v[178:179], s[14:15], 0, v[178:179]
	v_alignbit_b32 v171, v32, v171, 16
	v_fma_mixhi_f16 v173, v127, v35, 0
	v_lshl_add_u64 v[178:179], v[178:179], 0, v[166:167]
	global_store_dwordx4 v[178:179], v[170:173], off
	v_cvt_f32_f16_sdwa v35, v174 dst_sel:DWORD dst_unused:UNUSED_PAD src0_sel:WORD_1
	v_cvt_f32_f16_e32 v32, v174
	v_cvt_f32_f16_e32 v170, v175
	v_cvt_f32_f16_sdwa v171, v175 dst_sel:DWORD dst_unused:UNUSED_PAD src0_sel:WORD_1
	v_max_f32_e32 v35, 0xc1f00000, v35
	v_mul_f32_e32 v35, 0xbfb8aa3b, v35
	v_max_f32_e32 v170, 0xc1f00000, v170
	v_mul_f32_e32 v170, 0xbfb8aa3b, v170
	v_exp_f32_e32 v172, v170
	v_max_f32_e32 v170, 0xc1f00000, v171
	v_mul_f32_e32 v170, 0xbfb8aa3b, v170
	v_cvt_f32_f16_e32 v171, v176
	v_exp_f32_e32 v173, v170
	v_cvt_f32_f16_sdwa v170, v176 dst_sel:DWORD dst_unused:UNUSED_PAD src0_sel:WORD_1
	v_exp_f32_e32 v35, v35
	v_max_f32_e32 v171, 0xc1f00000, v171
	v_mul_f32_e32 v171, 0xbfb8aa3b, v171
	v_max_f32_e32 v170, 0xc1f00000, v170
	v_mul_f32_e32 v170, 0xbfb8aa3b, v170
	v_exp_f32_e32 v174, v171
	v_cvt_f32_f16_e32 v171, v177
	v_exp_f32_e32 v175, v170
	v_cvt_f32_f16_sdwa v170, v177 dst_sel:DWORD dst_unused:UNUSED_PAD src0_sel:WORD_1
	v_max_f32_e32 v32, 0xc1f00000, v32
	v_mul_f32_e32 v32, 0xbfb8aa3b, v32
	v_exp_f32_e32 v32, v32
	v_max_f32_e32 v171, 0xc1f00000, v171
	v_max_f32_e32 v170, 0xc1f00000, v170
	v_mul_f32_e32 v171, 0xbfb8aa3b, v171
	v_mul_f32_e32 v170, 0xbfb8aa3b, v170
	v_add_f32_e32 v35, 1.0, v35
	v_exp_f32_e32 v176, v171
	v_exp_f32_e32 v177, v170
	v_rcp_f32_e32 v170, v35
	v_add_f32_e32 v35, 1.0, v172
	v_rcp_f32_e32 v171, v35
	v_add_f32_e32 v35, 1.0, v173
	v_add_f32_e32 v32, 1.0, v32
	v_rcp_f32_e32 v172, v35
	v_add_f32_e32 v35, 1.0, v174
	v_rcp_f32_e32 v32, v32
	v_rcp_f32_e32 v173, v35
	v_add_f32_e32 v35, 1.0, v175
	v_rcp_f32_e32 v174, v35
	v_add_f32_e32 v35, 1.0, v176
	v_rcp_f32_e32 v175, v35
	v_add_f32_e32 v35, 1.0, v177
	v_mov_b32_e32 v176, v97
	v_mov_b32_e32 v177, v98
	v_pk_mul_f32 v[170:171], v[176:177], v[170:171]
	v_pk_mov_b32 v[176:177], v[98:99], v[92:93] op_sel:[1,0]
	v_fma_mixlo_f16 v32, v96, v32, 0
	v_cvt_pk_f16_f32 v171, v170, v171
	v_pk_mul_f32 v[172:173], v[176:177], v[172:173]
	v_rcp_f32_e32 v35, v35
	v_pack_b32_f16 v170, v32, v171
	v_cvt_pk_f16_f32 v32, v172, v173
	v_mov_b32_e32 v172, v93
	v_mov_b32_e32 v173, v94
	v_pk_mul_f32 v[172:173], v[172:173], v[174:175]
	v_alignbit_b32 v171, v32, v171, 16
	v_cvt_pk_f16_f32 v173, v172, v173
	v_alignbit_b32 v172, v173, v32, 16
	v_lshrrev_b32_e32 v173, 16, v173
	v_fma_mixhi_f16 v173, v95, v35, 0
	v_cvt_f32_f16_e32 v32, v152
	v_cvt_f32_f16_sdwa v35, v152 dst_sel:DWORD dst_unused:UNUSED_PAD src0_sel:WORD_1
	v_cvt_f32_f16_e32 v152, v153
	v_cvt_f32_f16_sdwa v153, v153 dst_sel:DWORD dst_unused:UNUSED_PAD src0_sel:WORD_1
	global_store_dwordx4 v[178:179], v[170:173], off offset:256
	v_max_f32_e32 v35, 0xc1f00000, v35
	v_max_f32_e32 v152, 0xc1f00000, v152
	v_mul_f32_e32 v152, 0xbfb8aa3b, v152
	v_lshlrev_b64 v[170:171], 11, v[160:161]
	v_exp_f32_e32 v161, v152
	v_max_f32_e32 v152, 0xc1f00000, v153
	v_mul_f32_e32 v152, 0xbfb8aa3b, v152
	v_cvt_f32_f16_e32 v153, v154
	v_exp_f32_e32 v172, v152
	v_cvt_f32_f16_sdwa v152, v154 dst_sel:DWORD dst_unused:UNUSED_PAD src0_sel:WORD_1
	v_mul_f32_e32 v35, 0xbfb8aa3b, v35
	v_max_f32_e32 v153, 0xc1f00000, v153
	v_mul_f32_e32 v153, 0xbfb8aa3b, v153
	v_max_f32_e32 v152, 0xc1f00000, v152
	v_mul_f32_e32 v152, 0xbfb8aa3b, v152
	v_exp_f32_e32 v173, v153
	v_cvt_f32_f16_e32 v153, v155
	v_exp_f32_e32 v174, v152
	v_cvt_f32_f16_sdwa v152, v155 dst_sel:DWORD dst_unused:UNUSED_PAD src0_sel:WORD_1
	v_exp_f32_e32 v35, v35
	v_max_f32_e32 v32, 0xc1f00000, v32
	v_mul_f32_e32 v32, 0xbfb8aa3b, v32
	v_exp_f32_e32 v32, v32
	v_max_f32_e32 v153, 0xc1f00000, v153
	v_max_f32_e32 v152, 0xc1f00000, v152
	v_mul_f32_e32 v153, 0xbfb8aa3b, v153
	v_mul_f32_e32 v152, 0xbfb8aa3b, v152
	v_add_f32_e32 v35, 1.0, v35
	v_exp_f32_e32 v175, v153
	v_exp_f32_e32 v176, v152
	v_rcp_f32_e32 v152, v35
	v_add_f32_e32 v35, 1.0, v161
	v_rcp_f32_e32 v153, v35
	v_add_f32_e32 v35, 1.0, v172
	v_add_f32_e32 v32, 1.0, v32
	v_rcp_f32_e32 v154, v35
	v_add_f32_e32 v35, 1.0, v173
	v_rcp_f32_e32 v32, v32
	v_rcp_f32_e32 v155, v35
	v_add_f32_e32 v35, 1.0, v174
	v_rcp_f32_e32 v172, v35
	v_add_f32_e32 v35, 1.0, v175
	v_rcp_f32_e32 v173, v35
	v_mov_b32_e32 v174, v121
	v_mov_b32_e32 v175, v122
	v_pk_mul_f32 v[152:153], v[174:175], v[152:153]
	v_pk_mov_b32 v[174:175], v[122:123], v[116:117] op_sel:[1,0]
	v_add_f32_e32 v35, 1.0, v176
	v_fma_mixlo_f16 v32, v120, v32, 0
	v_cvt_pk_f16_f32 v153, v152, v153
	v_pk_mul_f32 v[154:155], v[174:175], v[154:155]
	v_rcp_f32_e32 v35, v35
	v_pack_b32_f16 v152, v32, v153
	v_cvt_pk_f16_f32 v32, v154, v155
	v_mov_b32_e32 v154, v117
	v_mov_b32_e32 v155, v118
	v_pk_mul_f32 v[154:155], v[154:155], v[172:173]
	v_alignbit_b32 v153, v32, v153, 16
	v_cvt_pk_f16_f32 v155, v154, v155
	v_alignbit_b32 v154, v155, v32, 16
	v_lshrrev_b32_e32 v155, 16, v155
	v_fma_mixhi_f16 v155, v119, v35, 0
	v_cvt_f32_f16_e32 v32, v148
	v_cvt_f32_f16_sdwa v35, v148 dst_sel:DWORD dst_unused:UNUSED_PAD src0_sel:WORD_1
	v_cvt_f32_f16_e32 v148, v149
	v_cvt_f32_f16_sdwa v149, v149 dst_sel:DWORD dst_unused:UNUSED_PAD src0_sel:WORD_1
	v_lshl_add_u64 v[170:171], s[14:15], 0, v[170:171]
	v_lshl_add_u64 v[170:171], v[170:171], 0, v[166:167]
	v_max_f32_e32 v148, 0xc1f00000, v148
	v_mul_f32_e32 v148, 0xbfb8aa3b, v148
	global_store_dwordx4 v[170:171], v[152:155], off
	v_max_f32_e32 v35, 0xc1f00000, v35
	v_mul_f32_e32 v35, 0xbfb8aa3b, v35
	v_exp_f32_e32 v152, v148
	v_max_f32_e32 v148, 0xc1f00000, v149
	v_mul_f32_e32 v148, 0xbfb8aa3b, v148
	v_cvt_f32_f16_e32 v149, v150
	v_exp_f32_e32 v153, v148
	v_cvt_f32_f16_sdwa v148, v150 dst_sel:DWORD dst_unused:UNUSED_PAD src0_sel:WORD_1
	v_exp_f32_e32 v35, v35
	v_max_f32_e32 v149, 0xc1f00000, v149
	v_mul_f32_e32 v149, 0xbfb8aa3b, v149
	v_max_f32_e32 v148, 0xc1f00000, v148
	v_mul_f32_e32 v148, 0xbfb8aa3b, v148
	v_exp_f32_e32 v154, v149
	v_cvt_f32_f16_e32 v149, v151
	v_exp_f32_e32 v155, v148
	v_cvt_f32_f16_sdwa v148, v151 dst_sel:DWORD dst_unused:UNUSED_PAD src0_sel:WORD_1
	v_max_f32_e32 v32, 0xc1f00000, v32
	v_mul_f32_e32 v32, 0xbfb8aa3b, v32
	v_exp_f32_e32 v32, v32
	v_max_f32_e32 v149, 0xc1f00000, v149
	v_max_f32_e32 v148, 0xc1f00000, v148
	v_mul_f32_e32 v149, 0xbfb8aa3b, v149
	v_mul_f32_e32 v148, 0xbfb8aa3b, v148
	v_add_f32_e32 v35, 1.0, v35
	v_exp_f32_e32 v161, v149
	v_exp_f32_e32 v172, v148
	v_rcp_f32_e32 v148, v35
	v_add_f32_e32 v35, 1.0, v152
	v_rcp_f32_e32 v149, v35
	v_add_f32_e32 v35, 1.0, v153
	v_add_f32_e32 v32, 1.0, v32
	v_rcp_f32_e32 v150, v35
	v_add_f32_e32 v35, 1.0, v154
	v_rcp_f32_e32 v32, v32
	v_rcp_f32_e32 v151, v35
	v_add_f32_e32 v35, 1.0, v155
	v_rcp_f32_e32 v152, v35
	v_add_f32_e32 v35, 1.0, v161
	v_rcp_f32_e32 v153, v35
	v_mov_b32_e32 v154, v89
	v_mov_b32_e32 v155, v90
	v_pk_mul_f32 v[148:149], v[154:155], v[148:149]
	v_pk_mov_b32 v[154:155], v[90:91], v[84:85] op_sel:[1,0]
	v_add_f32_e32 v35, 1.0, v172
	v_fma_mixlo_f16 v32, v88, v32, 0
	v_cvt_pk_f16_f32 v149, v148, v149
	v_pk_mul_f32 v[150:151], v[154:155], v[150:151]
	v_rcp_f32_e32 v35, v35
	v_pack_b32_f16 v148, v32, v149
	v_cvt_pk_f16_f32 v32, v150, v151
	v_mov_b32_e32 v150, v85
	v_mov_b32_e32 v151, v86
	v_pk_mul_f32 v[150:151], v[150:151], v[152:153]
	v_alignbit_b32 v149, v32, v149, 16
	v_cvt_pk_f16_f32 v151, v150, v151
	v_alignbit_b32 v150, v151, v32, 16
	v_lshrrev_b32_e32 v151, 16, v151
	v_fma_mixhi_f16 v151, v87, v35, 0
	v_cvt_f32_f16_e32 v32, v144
	v_cvt_f32_f16_sdwa v35, v144 dst_sel:DWORD dst_unused:UNUSED_PAD src0_sel:WORD_1
	v_cvt_f32_f16_e32 v144, v145
	v_cvt_f32_f16_sdwa v145, v145 dst_sel:DWORD dst_unused:UNUSED_PAD src0_sel:WORD_1
	global_store_dwordx4 v[170:171], v[148:151], off offset:256
	v_max_f32_e32 v35, 0xc1f00000, v35
	v_max_f32_e32 v144, 0xc1f00000, v144
	v_mul_f32_e32 v144, 0xbfb8aa3b, v144
	v_exp_f32_e32 v150, v144
	v_max_f32_e32 v144, 0xc1f00000, v145
	v_mul_f32_e32 v144, 0xbfb8aa3b, v144
	v_cvt_f32_f16_e32 v145, v146
	v_exp_f32_e32 v151, v144
	v_cvt_f32_f16_sdwa v144, v146 dst_sel:DWORD dst_unused:UNUSED_PAD src0_sel:WORD_1
	v_mul_f32_e32 v35, 0xbfb8aa3b, v35
	v_max_f32_e32 v145, 0xc1f00000, v145
	v_mul_f32_e32 v145, 0xbfb8aa3b, v145
	v_max_f32_e32 v144, 0xc1f00000, v144
	v_mul_f32_e32 v144, 0xbfb8aa3b, v144
	v_exp_f32_e32 v152, v145
	v_cvt_f32_f16_e32 v145, v147
	v_exp_f32_e32 v153, v144
	v_cvt_f32_f16_sdwa v144, v147 dst_sel:DWORD dst_unused:UNUSED_PAD src0_sel:WORD_1
	v_exp_f32_e32 v35, v35
	v_max_f32_e32 v32, 0xc1f00000, v32
	v_mul_f32_e32 v32, 0xbfb8aa3b, v32
	v_exp_f32_e32 v32, v32
	v_max_f32_e32 v145, 0xc1f00000, v145
	v_max_f32_e32 v144, 0xc1f00000, v144
	v_mul_f32_e32 v145, 0xbfb8aa3b, v145
	v_mul_f32_e32 v144, 0xbfb8aa3b, v144
	v_add_f32_e32 v35, 1.0, v35
	v_exp_f32_e32 v154, v145
	v_exp_f32_e32 v155, v144
	v_rcp_f32_e32 v144, v35
	v_add_f32_e32 v35, 1.0, v150
	v_rcp_f32_e32 v145, v35
	v_add_f32_e32 v35, 1.0, v151
	v_add_f32_e32 v32, 1.0, v32
	v_rcp_f32_e32 v146, v35
	v_add_f32_e32 v35, 1.0, v152
	v_rcp_f32_e32 v32, v32
	v_rcp_f32_e32 v147, v35
	v_add_f32_e32 v35, 1.0, v153
	v_rcp_f32_e32 v150, v35
	v_add_f32_e32 v35, 1.0, v154
	v_rcp_f32_e32 v151, v35
	v_mov_b32_e32 v152, v113
	v_mov_b32_e32 v153, v114
	v_pk_mul_f32 v[144:145], v[152:153], v[144:145]
	v_pk_mov_b32 v[152:153], v[114:115], v[108:109] op_sel:[1,0]
	v_add_f32_e32 v35, 1.0, v155
	v_fma_mixlo_f16 v32, v112, v32, 0
	v_cvt_pk_f16_f32 v145, v144, v145
	v_pk_mul_f32 v[146:147], v[152:153], v[146:147]
	v_rcp_f32_e32 v35, v35
	v_pack_b32_f16 v144, v32, v145
	v_cvt_pk_f16_f32 v32, v146, v147
	v_mov_b32_e32 v146, v109
	v_mov_b32_e32 v147, v110
	v_pk_mul_f32 v[146:147], v[146:147], v[150:151]
	v_alignbit_b32 v145, v32, v145, 16
	v_cvt_pk_f16_f32 v147, v146, v147
	v_alignbit_b32 v146, v147, v32, 16
	v_lshrrev_b32_e32 v147, 16, v147
	v_fma_mixhi_f16 v147, v111, v35, 0
	v_cvt_f32_f16_e32 v32, v140
	v_cvt_f32_f16_sdwa v35, v140 dst_sel:DWORD dst_unused:UNUSED_PAD src0_sel:WORD_1
	v_cvt_f32_f16_e32 v140, v141
	v_cvt_f32_f16_sdwa v141, v141 dst_sel:DWORD dst_unused:UNUSED_PAD src0_sel:WORD_1
	v_lshlrev_b64 v[148:149], 11, v[162:163]
	v_lshl_add_u64 v[148:149], s[14:15], 0, v[148:149]
	v_max_f32_e32 v140, 0xc1f00000, v140
	v_lshl_add_u64 v[148:149], v[148:149], 0, v[166:167]
	v_mul_f32_e32 v140, 0xbfb8aa3b, v140
	global_store_dwordx4 v[148:149], v[144:147], off
	v_max_f32_e32 v35, 0xc1f00000, v35
	v_mul_f32_e32 v35, 0xbfb8aa3b, v35
	v_exp_f32_e32 v144, v140
	v_max_f32_e32 v140, 0xc1f00000, v141
	v_mul_f32_e32 v140, 0xbfb8aa3b, v140
	v_cvt_f32_f16_e32 v141, v142
	v_exp_f32_e32 v145, v140
	v_cvt_f32_f16_sdwa v140, v142 dst_sel:DWORD dst_unused:UNUSED_PAD src0_sel:WORD_1
	v_exp_f32_e32 v35, v35
	v_max_f32_e32 v141, 0xc1f00000, v141
	v_mul_f32_e32 v141, 0xbfb8aa3b, v141
	v_max_f32_e32 v140, 0xc1f00000, v140
	v_mul_f32_e32 v140, 0xbfb8aa3b, v140
	v_exp_f32_e32 v146, v141
	v_cvt_f32_f16_e32 v141, v143
	v_exp_f32_e32 v147, v140
	v_cvt_f32_f16_sdwa v140, v143 dst_sel:DWORD dst_unused:UNUSED_PAD src0_sel:WORD_1
	v_max_f32_e32 v32, 0xc1f00000, v32
	v_mul_f32_e32 v32, 0xbfb8aa3b, v32
	v_exp_f32_e32 v32, v32
	v_max_f32_e32 v141, 0xc1f00000, v141
	v_max_f32_e32 v140, 0xc1f00000, v140
	v_mul_f32_e32 v141, 0xbfb8aa3b, v141
	v_mul_f32_e32 v140, 0xbfb8aa3b, v140
	v_add_f32_e32 v35, 1.0, v35
	v_exp_f32_e32 v150, v141
	v_exp_f32_e32 v151, v140
	v_rcp_f32_e32 v140, v35
	v_add_f32_e32 v35, 1.0, v144
	v_rcp_f32_e32 v141, v35
	v_add_f32_e32 v35, 1.0, v145
	v_add_f32_e32 v32, 1.0, v32
	v_rcp_f32_e32 v142, v35
	v_add_f32_e32 v35, 1.0, v146
	v_rcp_f32_e32 v32, v32
	v_rcp_f32_e32 v143, v35
	v_add_f32_e32 v35, 1.0, v147
	v_rcp_f32_e32 v144, v35
	v_add_f32_e32 v35, 1.0, v150
	v_rcp_f32_e32 v145, v35
	v_mov_b32_e32 v146, v81
	v_mov_b32_e32 v147, v82
	v_pk_mul_f32 v[140:141], v[146:147], v[140:141]
	v_pk_mov_b32 v[146:147], v[82:83], v[76:77] op_sel:[1,0]
	v_add_f32_e32 v35, 1.0, v151
	v_fma_mixlo_f16 v32, v80, v32, 0
	v_cvt_pk_f16_f32 v141, v140, v141
	v_pk_mul_f32 v[142:143], v[146:147], v[142:143]
	v_rcp_f32_e32 v35, v35
	v_pack_b32_f16 v140, v32, v141
	v_cvt_pk_f16_f32 v32, v142, v143
	v_mov_b32_e32 v142, v77
	v_mov_b32_e32 v143, v78
	v_pk_mul_f32 v[142:143], v[142:143], v[144:145]
	v_alignbit_b32 v141, v32, v141, 16
	v_cvt_pk_f16_f32 v143, v142, v143
	v_alignbit_b32 v142, v143, v32, 16
	v_lshrrev_b32_e32 v143, 16, v143
	v_fma_mixhi_f16 v143, v79, v35, 0
	v_cvt_f32_f16_e32 v32, v136
	v_cvt_f32_f16_sdwa v35, v136 dst_sel:DWORD dst_unused:UNUSED_PAD src0_sel:WORD_1
	v_cvt_f32_f16_e32 v136, v137
	v_cvt_f32_f16_sdwa v137, v137 dst_sel:DWORD dst_unused:UNUSED_PAD src0_sel:WORD_1
	global_store_dwordx4 v[148:149], v[140:143], off offset:256
	v_max_f32_e32 v35, 0xc1f00000, v35
	v_max_f32_e32 v136, 0xc1f00000, v136
	v_mul_f32_e32 v136, 0xbfb8aa3b, v136
	v_exp_f32_e32 v142, v136
	v_max_f32_e32 v136, 0xc1f00000, v137
	v_mul_f32_e32 v136, 0xbfb8aa3b, v136
	v_cvt_f32_f16_e32 v137, v138
	v_exp_f32_e32 v143, v136
	v_cvt_f32_f16_sdwa v136, v138 dst_sel:DWORD dst_unused:UNUSED_PAD src0_sel:WORD_1
	v_mul_f32_e32 v35, 0xbfb8aa3b, v35
	v_max_f32_e32 v137, 0xc1f00000, v137
	v_mul_f32_e32 v137, 0xbfb8aa3b, v137
	v_max_f32_e32 v136, 0xc1f00000, v136
	v_mul_f32_e32 v136, 0xbfb8aa3b, v136
	v_exp_f32_e32 v144, v137
	v_cvt_f32_f16_e32 v137, v139
	v_exp_f32_e32 v145, v136
	v_cvt_f32_f16_sdwa v136, v139 dst_sel:DWORD dst_unused:UNUSED_PAD src0_sel:WORD_1
	v_exp_f32_e32 v35, v35
	v_max_f32_e32 v32, 0xc1f00000, v32
	v_mul_f32_e32 v32, 0xbfb8aa3b, v32
	v_exp_f32_e32 v32, v32
	v_max_f32_e32 v137, 0xc1f00000, v137
	v_max_f32_e32 v136, 0xc1f00000, v136
	v_mul_f32_e32 v137, 0xbfb8aa3b, v137
	v_mul_f32_e32 v136, 0xbfb8aa3b, v136
	v_add_f32_e32 v35, 1.0, v35
	v_exp_f32_e32 v146, v137
	v_exp_f32_e32 v147, v136
	v_rcp_f32_e32 v136, v35
	v_add_f32_e32 v35, 1.0, v142
	v_rcp_f32_e32 v137, v35
	v_add_f32_e32 v35, 1.0, v143
	v_add_f32_e32 v32, 1.0, v32
	v_rcp_f32_e32 v138, v35
	v_add_f32_e32 v35, 1.0, v144
	v_rcp_f32_e32 v32, v32
	v_rcp_f32_e32 v139, v35
	v_add_f32_e32 v35, 1.0, v145
	v_rcp_f32_e32 v142, v35
	v_add_f32_e32 v35, 1.0, v146
	v_rcp_f32_e32 v143, v35
	v_mov_b32_e32 v144, v105
	v_mov_b32_e32 v145, v106
	v_pk_mul_f32 v[136:137], v[144:145], v[136:137]
	v_pk_mov_b32 v[144:145], v[106:107], v[100:101] op_sel:[1,0]
	v_add_f32_e32 v35, 1.0, v147
	v_fma_mixlo_f16 v32, v104, v32, 0
	v_cvt_pk_f16_f32 v137, v136, v137
	v_pk_mul_f32 v[138:139], v[144:145], v[138:139]
	v_rcp_f32_e32 v35, v35
	v_pack_b32_f16 v136, v32, v137
	v_cvt_pk_f16_f32 v32, v138, v139
	v_mov_b32_e32 v138, v101
	v_mov_b32_e32 v139, v102
	v_pk_mul_f32 v[138:139], v[138:139], v[142:143]
	v_alignbit_b32 v137, v32, v137, 16
	v_cvt_pk_f16_f32 v139, v138, v139
	v_alignbit_b32 v138, v139, v32, 16
	v_lshrrev_b32_e32 v139, 16, v139
	v_fma_mixhi_f16 v139, v103, v35, 0
	v_cvt_f32_f16_e32 v32, v132
	v_cvt_f32_f16_sdwa v35, v132 dst_sel:DWORD dst_unused:UNUSED_PAD src0_sel:WORD_1
	v_cvt_f32_f16_e32 v132, v133
	v_cvt_f32_f16_sdwa v133, v133 dst_sel:DWORD dst_unused:UNUSED_PAD src0_sel:WORD_1
	v_lshlrev_b64 v[140:141], 11, v[164:165]
	v_lshl_add_u64 v[140:141], s[14:15], 0, v[140:141]
	v_max_f32_e32 v132, 0xc1f00000, v132
	v_lshl_add_u64 v[140:141], v[140:141], 0, v[166:167]
	v_mul_f32_e32 v132, 0xbfb8aa3b, v132
	global_store_dwordx4 v[140:141], v[136:139], off
	v_max_f32_e32 v35, 0xc1f00000, v35
	v_mul_f32_e32 v35, 0xbfb8aa3b, v35
	v_exp_f32_e32 v136, v132
	v_max_f32_e32 v132, 0xc1f00000, v133
	v_mul_f32_e32 v132, 0xbfb8aa3b, v132
	v_cvt_f32_f16_e32 v133, v134
	v_exp_f32_e32 v137, v132
	v_cvt_f32_f16_sdwa v132, v134 dst_sel:DWORD dst_unused:UNUSED_PAD src0_sel:WORD_1
	v_exp_f32_e32 v35, v35
	v_max_f32_e32 v133, 0xc1f00000, v133
	v_mul_f32_e32 v133, 0xbfb8aa3b, v133
	v_max_f32_e32 v132, 0xc1f00000, v132
	v_mul_f32_e32 v132, 0xbfb8aa3b, v132
	v_exp_f32_e32 v138, v133
	v_cvt_f32_f16_e32 v133, v135
	v_exp_f32_e32 v139, v132
	v_cvt_f32_f16_sdwa v132, v135 dst_sel:DWORD dst_unused:UNUSED_PAD src0_sel:WORD_1
	v_max_f32_e32 v32, 0xc1f00000, v32
	v_mul_f32_e32 v32, 0xbfb8aa3b, v32
	v_exp_f32_e32 v32, v32
	v_max_f32_e32 v133, 0xc1f00000, v133
	v_max_f32_e32 v132, 0xc1f00000, v132
	v_mul_f32_e32 v133, 0xbfb8aa3b, v133
	v_mul_f32_e32 v132, 0xbfb8aa3b, v132
	v_add_f32_e32 v35, 1.0, v35
	v_exp_f32_e32 v142, v133
	v_exp_f32_e32 v143, v132
	v_rcp_f32_e32 v132, v35
	v_add_f32_e32 v35, 1.0, v136
	v_rcp_f32_e32 v133, v35
	v_add_f32_e32 v35, 1.0, v137
	v_add_f32_e32 v32, 1.0, v32
	v_rcp_f32_e32 v134, v35
	v_add_f32_e32 v35, 1.0, v138
	v_rcp_f32_e32 v32, v32
	v_rcp_f32_e32 v135, v35
	v_add_f32_e32 v35, 1.0, v139
	v_rcp_f32_e32 v136, v35
	v_add_f32_e32 v35, 1.0, v142
	v_rcp_f32_e32 v137, v35
	v_mov_b32_e32 v138, v73
	v_mov_b32_e32 v139, v74
	v_pk_mul_f32 v[132:133], v[138:139], v[132:133]
	v_pk_mov_b32 v[138:139], v[74:75], v[68:69] op_sel:[1,0]
	v_add_f32_e32 v35, 1.0, v143
	v_fma_mixlo_f16 v32, v72, v32, 0
	v_cvt_pk_f16_f32 v133, v132, v133
	v_pk_mul_f32 v[134:135], v[138:139], v[134:135]
	v_rcp_f32_e32 v35, v35
	v_pack_b32_f16 v132, v32, v133
	v_cvt_pk_f16_f32 v32, v134, v135
	v_mov_b32_e32 v134, v69
	v_mov_b32_e32 v135, v70
	v_pk_mul_f32 v[134:135], v[134:135], v[136:137]
	v_alignbit_b32 v133, v32, v133, 16
	v_cvt_pk_f16_f32 v135, v134, v135
	v_alignbit_b32 v134, v135, v32, 16
	v_lshrrev_b32_e32 v135, 16, v135
	v_fma_mixhi_f16 v135, v71, v35, 0
	global_store_dwordx4 v[140:141], v[132:135], off offset:256
	v_add_u32_e32 v184, 0x80, v34
	s_nop 0
	v_mad_i64_i32 v[132:133], s[12:13], v184, s33, v[168:169]
	v_lshl_add_u64 v[132:133], v[132:133], 0, v[166:167]
	v_add_u32_e32 v174, 0x90, v34
	v_lshl_add_u64 v[134:135], v[132:133], 0, s[16:17]
	v_mad_i64_i32 v[136:137], s[12:13], v174, s33, v[168:169]
	v_add_co_u32_e32 v132, vcc, s1, v132
	v_lshl_add_u64 v[136:137], v[136:137], 0, v[166:167]
	v_add_u32_e32 v172, 0xa0, v34
	v_addc_co_u32_e32 v133, vcc, 0, v133, vcc
	v_lshl_add_u64 v[138:139], v[136:137], 0, s[16:17]
	v_mad_i64_i32 v[140:141], s[12:13], v172, s33, v[168:169]
	v_add_co_u32_e32 v136, vcc, s1, v136
	v_lshl_add_u64 v[140:141], v[140:141], 0, v[166:167]
	v_add_u32_e32 v170, 0xb0, v34
	v_addc_co_u32_e32 v137, vcc, 0, v137, vcc
	v_mad_i64_i32 v[144:145], s[12:13], v170, s33, v[168:169]
	global_load_dwordx4 v[176:179], v[132:133], off offset:2048
	global_load_dwordx4 v[152:155], v[136:137], off offset:2048
	global_load_dwordx4 v[180:183], v[134:135], off offset:256
	global_load_dwordx4 v[148:151], v[138:139], off offset:256
	v_add_co_u32_e32 v132, vcc, s1, v140
	v_lshl_add_u64 v[144:145], v[144:145], 0, v[166:167]
	s_nop 0
	v_addc_co_u32_e32 v133, vcc, 0, v141, vcc
	v_add_co_u32_e32 v134, vcc, s1, v144
	v_lshl_add_u64 v[142:143], v[140:141], 0, s[16:17]
	s_nop 0
	v_addc_co_u32_e32 v135, vcc, 0, v145, vcc
	v_lshl_add_u64 v[168:169], v[144:145], 0, s[16:17]
	global_load_dwordx4 v[144:147], v[132:133], off offset:2048
	global_load_dwordx4 v[136:139], v[134:135], off offset:2048
	s_nop 0
	global_load_dwordx4 v[140:143], v[142:143], off offset:256
	s_nop 0
	global_load_dwordx4 v[132:135], v[168:169], off offset:256
	v_ashrrev_i32_e32 v185, 31, v184
	v_ashrrev_i32_e32 v175, 31, v174
	v_ashrrev_i32_e32 v173, 31, v172
	v_ashrrev_i32_e32 v171, 31, v170
	s_waitcnt vmcnt(0)
	v_cvt_f32_f16_e32 v32, v176
	v_cvt_f32_f16_sdwa v35, v176 dst_sel:DWORD dst_unused:UNUSED_PAD src0_sel:WORD_1
	v_cvt_f32_f16_sdwa v176, v178 dst_sel:DWORD dst_unused:UNUSED_PAD src0_sel:WORD_1
	v_cvt_f32_f16_e32 v161, v177
	v_cvt_f32_f16_sdwa v163, v177 dst_sel:DWORD dst_unused:UNUSED_PAD src0_sel:WORD_1
	v_cvt_f32_f16_e32 v165, v178
	v_max_f32_e32 v176, 0xc1f00000, v176
	v_max_f32_e32 v35, 0xc1f00000, v35
	v_mul_f32_e32 v176, 0xbfb8aa3b, v176
	v_lshlrev_b64 v[168:169], 11, v[184:185]
	v_mul_f32_e32 v35, 0xbfb8aa3b, v35
	v_max_f32_e32 v161, 0xc1f00000, v161
	v_cvt_f32_f16_e32 v177, v179
	v_exp_f32_e32 v184, v176
	v_cvt_f32_f16_sdwa v176, v179 dst_sel:DWORD dst_unused:UNUSED_PAD src0_sel:WORD_1
	v_exp_f32_e32 v35, v35
	v_mul_f32_e32 v161, 0xbfb8aa3b, v161
	v_max_f32_e32 v163, 0xc1f00000, v163
	v_max_f32_e32 v32, 0xc1f00000, v32
	v_exp_f32_e32 v161, v161
	v_mul_f32_e32 v163, 0xbfb8aa3b, v163
	v_max_f32_e32 v165, 0xc1f00000, v165
	v_mul_f32_e32 v32, 0xbfb8aa3b, v32
	v_exp_f32_e32 v163, v163
	v_mul_f32_e32 v165, 0xbfb8aa3b, v165
	v_exp_f32_e32 v32, v32
	v_exp_f32_e32 v165, v165
	v_max_f32_e32 v177, 0xc1f00000, v177
	v_max_f32_e32 v176, 0xc1f00000, v176
	v_mul_f32_e32 v177, 0xbfb8aa3b, v177
	v_mul_f32_e32 v176, 0xbfb8aa3b, v176
	v_add_f32_e32 v35, 1.0, v35
	v_exp_f32_e32 v185, v177
	v_exp_f32_e32 v186, v176
	v_rcp_f32_e32 v176, v35
	v_add_f32_e32 v35, 1.0, v161
	v_rcp_f32_e32 v177, v35
	v_add_f32_e32 v35, 1.0, v163
	v_add_f32_e32 v32, 1.0, v32
	v_rcp_f32_e32 v178, v35
	v_add_f32_e32 v35, 1.0, v165
	v_rcp_f32_e32 v32, v32
	v_rcp_f32_e32 v179, v35
	v_add_f32_e32 v35, 1.0, v184
	v_rcp_f32_e32 v184, v35
	v_add_f32_e32 v35, 1.0, v185
	v_rcp_f32_e32 v185, v35
	v_add_f32_e32 v35, 1.0, v186
	v_mov_b32_e32 v186, v65
	v_mov_b32_e32 v187, v66
	v_pk_mul_f32 v[176:177], v[186:187], v[176:177]
	v_pk_mov_b32 v[186:187], v[66:67], v[60:61] op_sel:[1,0]
	v_fma_mixlo_f16 v32, v64, v32, 0
	v_cvt_pk_f16_f32 v161, v176, v177
	v_pk_mul_f32 v[178:179], v[186:187], v[178:179]
	v_rcp_f32_e32 v35, v35
	v_pack_b32_f16 v176, v32, v161
	v_cvt_pk_f16_f32 v32, v178, v179
	v_mov_b32_e32 v178, v61
	v_mov_b32_e32 v179, v62
	v_pk_mul_f32 v[178:179], v[178:179], v[184:185]
	v_alignbit_b32 v177, v32, v161, 16
	v_cvt_pk_f16_f32 v161, v178, v179
	v_lshrrev_b32_e32 v179, 16, v161
	v_lshl_add_u64 v[168:169], s[14:15], 0, v[168:169]
	v_alignbit_b32 v178, v161, v32, 16
	v_fma_mixhi_f16 v179, v63, v35, 0
	v_lshl_add_u64 v[168:169], v[168:169], 0, v[166:167]
	global_store_dwordx4 v[168:169], v[176:179], off
	v_cvt_f32_f16_sdwa v35, v180 dst_sel:DWORD dst_unused:UNUSED_PAD src0_sel:WORD_1
	v_cvt_f32_f16_e32 v161, v181
	v_cvt_f32_f16_sdwa v176, v182 dst_sel:DWORD dst_unused:UNUSED_PAD src0_sel:WORD_1
	v_cvt_f32_f16_sdwa v163, v181 dst_sel:DWORD dst_unused:UNUSED_PAD src0_sel:WORD_1
	v_cvt_f32_f16_e32 v32, v180
	v_cvt_f32_f16_e32 v165, v182
	v_max_f32_e32 v176, 0xc1f00000, v176
	v_max_f32_e32 v35, 0xc1f00000, v35
	v_mul_f32_e32 v176, 0xbfb8aa3b, v176
	v_mul_f32_e32 v35, 0xbfb8aa3b, v35
	v_max_f32_e32 v161, 0xc1f00000, v161
	v_cvt_f32_f16_e32 v177, v183
	v_exp_f32_e32 v180, v176
	v_cvt_f32_f16_sdwa v176, v183 dst_sel:DWORD dst_unused:UNUSED_PAD src0_sel:WORD_1
	v_exp_f32_e32 v35, v35
	v_mul_f32_e32 v161, 0xbfb8aa3b, v161
	v_max_f32_e32 v163, 0xc1f00000, v163
	v_max_f32_e32 v32, 0xc1f00000, v32
	v_exp_f32_e32 v161, v161
	v_mul_f32_e32 v163, 0xbfb8aa3b, v163
	v_max_f32_e32 v165, 0xc1f00000, v165
	v_mul_f32_e32 v32, 0xbfb8aa3b, v32
	v_exp_f32_e32 v163, v163
	v_mul_f32_e32 v165, 0xbfb8aa3b, v165
	v_exp_f32_e32 v32, v32
	v_exp_f32_e32 v165, v165
	v_max_f32_e32 v177, 0xc1f00000, v177
	v_max_f32_e32 v176, 0xc1f00000, v176
	v_mul_f32_e32 v177, 0xbfb8aa3b, v177
	v_mul_f32_e32 v176, 0xbfb8aa3b, v176
	v_add_f32_e32 v35, 1.0, v35
	v_exp_f32_e32 v181, v177
	v_exp_f32_e32 v182, v176
	v_rcp_f32_e32 v176, v35
	v_add_f32_e32 v35, 1.0, v161
	v_rcp_f32_e32 v177, v35
	v_add_f32_e32 v35, 1.0, v163
	v_add_f32_e32 v32, 1.0, v32
	v_rcp_f32_e32 v178, v35
	v_add_f32_e32 v35, 1.0, v165
	v_rcp_f32_e32 v32, v32
	v_rcp_f32_e32 v179, v35
	v_add_f32_e32 v35, 1.0, v180
	v_rcp_f32_e32 v180, v35
	v_add_f32_e32 v35, 1.0, v181
	v_rcp_f32_e32 v181, v35
	v_add_f32_e32 v35, 1.0, v182
	v_mov_b32_e32 v182, v29
	v_mov_b32_e32 v183, v30
	v_pk_mul_f32 v[176:177], v[182:183], v[176:177]
	v_pk_mov_b32 v[182:183], v[30:31], v[24:25] op_sel:[1,0]
	v_fma_mixlo_f16 v32, v28, v32, 0
	v_cvt_pk_f16_f32 v161, v176, v177
	v_pk_mul_f32 v[178:179], v[182:183], v[178:179]
	v_rcp_f32_e32 v35, v35
	v_pack_b32_f16 v176, v32, v161
	v_cvt_pk_f16_f32 v32, v178, v179
	v_mov_b32_e32 v178, v25
	v_mov_b32_e32 v179, v26
	v_pk_mul_f32 v[178:179], v[178:179], v[180:181]
	v_alignbit_b32 v177, v32, v161, 16
	v_cvt_pk_f16_f32 v161, v178, v179
	v_lshrrev_b32_e32 v179, 16, v161
	v_alignbit_b32 v178, v161, v32, 16
	v_fma_mixhi_f16 v179, v27, v35, 0
	v_cvt_f32_f16_e32 v32, v152
	v_cvt_f32_f16_sdwa v35, v152 dst_sel:DWORD dst_unused:UNUSED_PAD src0_sel:WORD_1
	v_cvt_f32_f16_e32 v152, v153
	v_cvt_f32_f16_sdwa v153, v153 dst_sel:DWORD dst_unused:UNUSED_PAD src0_sel:WORD_1
	global_store_dwordx4 v[168:169], v[176:179], off offset:256
	v_max_f32_e32 v35, 0xc1f00000, v35
	v_max_f32_e32 v152, 0xc1f00000, v152
	v_mul_f32_e32 v152, 0xbfb8aa3b, v152
	v_exp_f32_e32 v161, v152
	v_max_f32_e32 v152, 0xc1f00000, v153
	v_mul_f32_e32 v152, 0xbfb8aa3b, v152
	v_cvt_f32_f16_e32 v153, v154
	v_exp_f32_e32 v163, v152
	v_cvt_f32_f16_sdwa v152, v154 dst_sel:DWORD dst_unused:UNUSED_PAD src0_sel:WORD_1
	v_lshlrev_b64 v[168:169], 11, v[174:175]
	v_max_f32_e32 v153, 0xc1f00000, v153
	v_mul_f32_e32 v153, 0xbfb8aa3b, v153
	v_max_f32_e32 v152, 0xc1f00000, v152
	v_mul_f32_e32 v152, 0xbfb8aa3b, v152
	v_mul_f32_e32 v35, 0xbfb8aa3b, v35
	v_exp_f32_e32 v165, v153
	v_cvt_f32_f16_e32 v153, v155
	v_exp_f32_e32 v174, v152
	v_cvt_f32_f16_sdwa v152, v155 dst_sel:DWORD dst_unused:UNUSED_PAD src0_sel:WORD_1
	v_exp_f32_e32 v35, v35
	v_max_f32_e32 v32, 0xc1f00000, v32
	v_mul_f32_e32 v32, 0xbfb8aa3b, v32
	v_exp_f32_e32 v32, v32
	v_max_f32_e32 v153, 0xc1f00000, v153
	v_max_f32_e32 v152, 0xc1f00000, v152
	v_mul_f32_e32 v153, 0xbfb8aa3b, v153
	v_mul_f32_e32 v152, 0xbfb8aa3b, v152
	v_add_f32_e32 v35, 1.0, v35
	v_exp_f32_e32 v175, v153
	v_exp_f32_e32 v176, v152
	v_rcp_f32_e32 v152, v35
	v_add_f32_e32 v35, 1.0, v161
	v_rcp_f32_e32 v153, v35
	v_add_f32_e32 v35, 1.0, v163
	v_add_f32_e32 v32, 1.0, v32
	v_rcp_f32_e32 v154, v35
	v_add_f32_e32 v35, 1.0, v165
	v_rcp_f32_e32 v32, v32
	v_rcp_f32_e32 v155, v35
	v_add_f32_e32 v35, 1.0, v174
	v_rcp_f32_e32 v174, v35
	v_add_f32_e32 v35, 1.0, v175
	v_rcp_f32_e32 v175, v35
	v_add_f32_e32 v35, 1.0, v176
	v_mov_b32_e32 v176, v57
	v_mov_b32_e32 v177, v58
	v_pk_mul_f32 v[152:153], v[176:177], v[152:153]
	v_pk_mov_b32 v[176:177], v[58:59], v[52:53] op_sel:[1,0]
	v_fma_mixlo_f16 v32, v56, v32, 0
	v_cvt_pk_f16_f32 v153, v152, v153
	v_pk_mul_f32 v[154:155], v[176:177], v[154:155]
	v_rcp_f32_e32 v35, v35
	v_pack_b32_f16 v152, v32, v153
	v_cvt_pk_f16_f32 v32, v154, v155
	v_mov_b32_e32 v154, v53
	v_mov_b32_e32 v155, v54
	v_pk_mul_f32 v[154:155], v[154:155], v[174:175]
	v_alignbit_b32 v153, v32, v153, 16
	v_cvt_pk_f16_f32 v155, v154, v155
	v_alignbit_b32 v154, v155, v32, 16
	v_lshrrev_b32_e32 v155, 16, v155
	v_fma_mixhi_f16 v155, v55, v35, 0
	v_cvt_f32_f16_e32 v32, v148
	v_cvt_f32_f16_sdwa v35, v148 dst_sel:DWORD dst_unused:UNUSED_PAD src0_sel:WORD_1
	v_cvt_f32_f16_e32 v148, v149
	v_cvt_f32_f16_sdwa v149, v149 dst_sel:DWORD dst_unused:UNUSED_PAD src0_sel:WORD_1
	v_lshl_add_u64 v[168:169], s[14:15], 0, v[168:169]
	v_lshl_add_u64 v[168:169], v[168:169], 0, v[166:167]
	v_max_f32_e32 v148, 0xc1f00000, v148
	v_mul_f32_e32 v148, 0xbfb8aa3b, v148
	global_store_dwordx4 v[168:169], v[152:155], off
	v_max_f32_e32 v35, 0xc1f00000, v35
	v_mul_f32_e32 v35, 0xbfb8aa3b, v35
	v_exp_f32_e32 v152, v148
	v_max_f32_e32 v148, 0xc1f00000, v149
	v_mul_f32_e32 v148, 0xbfb8aa3b, v148
	v_cvt_f32_f16_e32 v149, v150
	v_exp_f32_e32 v153, v148
	v_cvt_f32_f16_sdwa v148, v150 dst_sel:DWORD dst_unused:UNUSED_PAD src0_sel:WORD_1
	v_exp_f32_e32 v35, v35
	v_max_f32_e32 v149, 0xc1f00000, v149
	v_mul_f32_e32 v149, 0xbfb8aa3b, v149
	v_max_f32_e32 v148, 0xc1f00000, v148
	v_mul_f32_e32 v148, 0xbfb8aa3b, v148
	v_exp_f32_e32 v154, v149
	v_cvt_f32_f16_e32 v149, v151
	v_exp_f32_e32 v155, v148
	v_cvt_f32_f16_sdwa v148, v151 dst_sel:DWORD dst_unused:UNUSED_PAD src0_sel:WORD_1
	v_max_f32_e32 v32, 0xc1f00000, v32
	v_mul_f32_e32 v32, 0xbfb8aa3b, v32
	v_exp_f32_e32 v32, v32
	v_max_f32_e32 v149, 0xc1f00000, v149
	v_max_f32_e32 v148, 0xc1f00000, v148
	v_mul_f32_e32 v149, 0xbfb8aa3b, v149
	v_mul_f32_e32 v148, 0xbfb8aa3b, v148
	v_add_f32_e32 v35, 1.0, v35
	v_exp_f32_e32 v161, v149
	v_exp_f32_e32 v163, v148
	v_rcp_f32_e32 v148, v35
	v_add_f32_e32 v35, 1.0, v152
	v_rcp_f32_e32 v149, v35
	v_add_f32_e32 v35, 1.0, v153
	v_add_f32_e32 v32, 1.0, v32
	v_rcp_f32_e32 v150, v35
	v_add_f32_e32 v35, 1.0, v154
	v_rcp_f32_e32 v32, v32
	v_rcp_f32_e32 v151, v35
	v_add_f32_e32 v35, 1.0, v155
	v_rcp_f32_e32 v152, v35
	v_add_f32_e32 v35, 1.0, v161
	v_rcp_f32_e32 v153, v35
	v_mov_b32_e32 v154, v21
	v_mov_b32_e32 v155, v22
	v_pk_mul_f32 v[148:149], v[154:155], v[148:149]
	v_pk_mov_b32 v[154:155], v[22:23], v[16:17] op_sel:[1,0]
	v_add_f32_e32 v35, 1.0, v163
	v_fma_mixlo_f16 v32, v20, v32, 0
	v_cvt_pk_f16_f32 v149, v148, v149
	v_pk_mul_f32 v[150:151], v[154:155], v[150:151]
	v_rcp_f32_e32 v35, v35
	v_pack_b32_f16 v148, v32, v149
	v_cvt_pk_f16_f32 v32, v150, v151
	v_mov_b32_e32 v150, v17
	v_mov_b32_e32 v151, v18
	v_pk_mul_f32 v[150:151], v[150:151], v[152:153]
	v_alignbit_b32 v149, v32, v149, 16
	v_cvt_pk_f16_f32 v151, v150, v151
	v_alignbit_b32 v150, v151, v32, 16
	v_lshrrev_b32_e32 v151, 16, v151
	v_fma_mixhi_f16 v151, v19, v35, 0
	v_cvt_f32_f16_e32 v32, v144
	v_cvt_f32_f16_sdwa v35, v144 dst_sel:DWORD dst_unused:UNUSED_PAD src0_sel:WORD_1
	v_cvt_f32_f16_e32 v144, v145
	v_cvt_f32_f16_sdwa v145, v145 dst_sel:DWORD dst_unused:UNUSED_PAD src0_sel:WORD_1
	global_store_dwordx4 v[168:169], v[148:151], off offset:256
	v_max_f32_e32 v35, 0xc1f00000, v35
	v_max_f32_e32 v144, 0xc1f00000, v144
	v_mul_f32_e32 v144, 0xbfb8aa3b, v144
	v_exp_f32_e32 v150, v144
	v_max_f32_e32 v144, 0xc1f00000, v145
	v_mul_f32_e32 v144, 0xbfb8aa3b, v144
	v_cvt_f32_f16_e32 v145, v146
	v_exp_f32_e32 v151, v144
	v_cvt_f32_f16_sdwa v144, v146 dst_sel:DWORD dst_unused:UNUSED_PAD src0_sel:WORD_1
	v_mul_f32_e32 v35, 0xbfb8aa3b, v35
	v_max_f32_e32 v145, 0xc1f00000, v145
	v_mul_f32_e32 v145, 0xbfb8aa3b, v145
	v_max_f32_e32 v144, 0xc1f00000, v144
	v_mul_f32_e32 v144, 0xbfb8aa3b, v144
	v_exp_f32_e32 v152, v145
	v_cvt_f32_f16_e32 v145, v147
	v_exp_f32_e32 v153, v144
	v_cvt_f32_f16_sdwa v144, v147 dst_sel:DWORD dst_unused:UNUSED_PAD src0_sel:WORD_1
	v_exp_f32_e32 v35, v35
	v_max_f32_e32 v32, 0xc1f00000, v32
	v_mul_f32_e32 v32, 0xbfb8aa3b, v32
	v_exp_f32_e32 v32, v32
	v_max_f32_e32 v145, 0xc1f00000, v145
	v_max_f32_e32 v144, 0xc1f00000, v144
	v_mul_f32_e32 v145, 0xbfb8aa3b, v145
	v_mul_f32_e32 v144, 0xbfb8aa3b, v144
	v_add_f32_e32 v35, 1.0, v35
	v_exp_f32_e32 v154, v145
	v_exp_f32_e32 v155, v144
	v_rcp_f32_e32 v144, v35
	v_add_f32_e32 v35, 1.0, v150
	v_rcp_f32_e32 v145, v35
	v_add_f32_e32 v35, 1.0, v151
	v_add_f32_e32 v32, 1.0, v32
	v_rcp_f32_e32 v146, v35
	v_add_f32_e32 v35, 1.0, v152
	v_rcp_f32_e32 v32, v32
	v_rcp_f32_e32 v147, v35
	v_add_f32_e32 v35, 1.0, v153
	v_rcp_f32_e32 v150, v35
	v_add_f32_e32 v35, 1.0, v154
	v_rcp_f32_e32 v151, v35
	v_mov_b32_e32 v152, v49
	v_mov_b32_e32 v153, v50
	v_pk_mul_f32 v[144:145], v[152:153], v[144:145]
	v_pk_mov_b32 v[152:153], v[50:51], v[44:45] op_sel:[1,0]
	v_add_f32_e32 v35, 1.0, v155
	v_fma_mixlo_f16 v32, v48, v32, 0
	v_cvt_pk_f16_f32 v145, v144, v145
	v_pk_mul_f32 v[146:147], v[152:153], v[146:147]
	v_rcp_f32_e32 v35, v35
	v_pack_b32_f16 v144, v32, v145
	v_cvt_pk_f16_f32 v32, v146, v147
	v_mov_b32_e32 v146, v45
	v_mov_b32_e32 v147, v46
	v_pk_mul_f32 v[146:147], v[146:147], v[150:151]
	v_alignbit_b32 v145, v32, v145, 16
	v_cvt_pk_f16_f32 v147, v146, v147
	v_alignbit_b32 v146, v147, v32, 16
	v_lshrrev_b32_e32 v147, 16, v147
	v_fma_mixhi_f16 v147, v47, v35, 0
	v_cvt_f32_f16_e32 v32, v140
	v_cvt_f32_f16_sdwa v35, v140 dst_sel:DWORD dst_unused:UNUSED_PAD src0_sel:WORD_1
	v_cvt_f32_f16_e32 v140, v141
	v_cvt_f32_f16_sdwa v141, v141 dst_sel:DWORD dst_unused:UNUSED_PAD src0_sel:WORD_1
	v_lshlrev_b64 v[148:149], 11, v[172:173]
	v_lshl_add_u64 v[148:149], s[14:15], 0, v[148:149]
	v_max_f32_e32 v140, 0xc1f00000, v140
	v_lshl_add_u64 v[148:149], v[148:149], 0, v[166:167]
	v_mul_f32_e32 v140, 0xbfb8aa3b, v140
	global_store_dwordx4 v[148:149], v[144:147], off
	v_max_f32_e32 v35, 0xc1f00000, v35
	v_mul_f32_e32 v35, 0xbfb8aa3b, v35
	v_exp_f32_e32 v144, v140
	v_max_f32_e32 v140, 0xc1f00000, v141
	v_mul_f32_e32 v140, 0xbfb8aa3b, v140
	v_cvt_f32_f16_e32 v141, v142
	v_exp_f32_e32 v145, v140
	v_cvt_f32_f16_sdwa v140, v142 dst_sel:DWORD dst_unused:UNUSED_PAD src0_sel:WORD_1
	v_exp_f32_e32 v35, v35
	v_max_f32_e32 v141, 0xc1f00000, v141
	v_mul_f32_e32 v141, 0xbfb8aa3b, v141
	v_max_f32_e32 v140, 0xc1f00000, v140
	v_mul_f32_e32 v140, 0xbfb8aa3b, v140
	v_exp_f32_e32 v146, v141
	v_cvt_f32_f16_e32 v141, v143
	v_exp_f32_e32 v147, v140
	v_cvt_f32_f16_sdwa v140, v143 dst_sel:DWORD dst_unused:UNUSED_PAD src0_sel:WORD_1
	v_max_f32_e32 v32, 0xc1f00000, v32
	v_mul_f32_e32 v32, 0xbfb8aa3b, v32
	v_exp_f32_e32 v32, v32
	v_max_f32_e32 v141, 0xc1f00000, v141
	v_max_f32_e32 v140, 0xc1f00000, v140
	v_mul_f32_e32 v141, 0xbfb8aa3b, v141
	v_mul_f32_e32 v140, 0xbfb8aa3b, v140
	v_add_f32_e32 v35, 1.0, v35
	v_exp_f32_e32 v150, v141
	v_exp_f32_e32 v151, v140
	v_rcp_f32_e32 v140, v35
	v_add_f32_e32 v35, 1.0, v144
	v_rcp_f32_e32 v141, v35
	v_add_f32_e32 v35, 1.0, v145
	v_add_f32_e32 v32, 1.0, v32
	v_rcp_f32_e32 v142, v35
	v_add_f32_e32 v35, 1.0, v146
	v_rcp_f32_e32 v32, v32
	v_rcp_f32_e32 v143, v35
	v_add_f32_e32 v35, 1.0, v147
	v_rcp_f32_e32 v144, v35
	v_add_f32_e32 v35, 1.0, v150
	v_rcp_f32_e32 v145, v35
	v_mov_b32_e32 v146, v13
	v_mov_b32_e32 v147, v14
	v_pk_mul_f32 v[140:141], v[146:147], v[140:141]
	v_pk_mov_b32 v[146:147], v[14:15], v[8:9] op_sel:[1,0]
	v_add_f32_e32 v35, 1.0, v151
	v_fma_mixlo_f16 v32, v12, v32, 0
	v_cvt_pk_f16_f32 v141, v140, v141
	v_pk_mul_f32 v[142:143], v[146:147], v[142:143]
	v_rcp_f32_e32 v35, v35
	v_pack_b32_f16 v140, v32, v141
	v_cvt_pk_f16_f32 v32, v142, v143
	v_mov_b32_e32 v142, v9
	v_mov_b32_e32 v143, v10
	v_pk_mul_f32 v[142:143], v[142:143], v[144:145]
	v_alignbit_b32 v141, v32, v141, 16
	v_cvt_pk_f16_f32 v143, v142, v143
	v_alignbit_b32 v142, v143, v32, 16
	v_lshrrev_b32_e32 v143, 16, v143
	v_fma_mixhi_f16 v143, v11, v35, 0
	v_cvt_f32_f16_e32 v32, v136
	v_cvt_f32_f16_sdwa v35, v136 dst_sel:DWORD dst_unused:UNUSED_PAD src0_sel:WORD_1
	v_cvt_f32_f16_e32 v136, v137
	v_cvt_f32_f16_sdwa v137, v137 dst_sel:DWORD dst_unused:UNUSED_PAD src0_sel:WORD_1
	global_store_dwordx4 v[148:149], v[140:143], off offset:256
	v_max_f32_e32 v35, 0xc1f00000, v35
	v_max_f32_e32 v136, 0xc1f00000, v136
	v_mul_f32_e32 v136, 0xbfb8aa3b, v136
	v_exp_f32_e32 v142, v136
	v_max_f32_e32 v136, 0xc1f00000, v137
	v_mul_f32_e32 v136, 0xbfb8aa3b, v136
	v_cvt_f32_f16_e32 v137, v138
	v_exp_f32_e32 v143, v136
	v_cvt_f32_f16_sdwa v136, v138 dst_sel:DWORD dst_unused:UNUSED_PAD src0_sel:WORD_1
	v_mul_f32_e32 v35, 0xbfb8aa3b, v35
	v_max_f32_e32 v137, 0xc1f00000, v137
	v_mul_f32_e32 v137, 0xbfb8aa3b, v137
	v_max_f32_e32 v136, 0xc1f00000, v136
	v_mul_f32_e32 v136, 0xbfb8aa3b, v136
	v_exp_f32_e32 v144, v137
	v_cvt_f32_f16_e32 v137, v139
	v_exp_f32_e32 v145, v136
	v_cvt_f32_f16_sdwa v136, v139 dst_sel:DWORD dst_unused:UNUSED_PAD src0_sel:WORD_1
	v_exp_f32_e32 v35, v35
	v_max_f32_e32 v32, 0xc1f00000, v32
	v_mul_f32_e32 v32, 0xbfb8aa3b, v32
	v_exp_f32_e32 v32, v32
	v_max_f32_e32 v137, 0xc1f00000, v137
	v_max_f32_e32 v136, 0xc1f00000, v136
	v_mul_f32_e32 v137, 0xbfb8aa3b, v137
	v_mul_f32_e32 v136, 0xbfb8aa3b, v136
	v_add_f32_e32 v35, 1.0, v35
	v_exp_f32_e32 v146, v137
	v_exp_f32_e32 v147, v136
	v_rcp_f32_e32 v136, v35
	v_add_f32_e32 v35, 1.0, v142
	v_rcp_f32_e32 v137, v35
	v_add_f32_e32 v35, 1.0, v143
	v_add_f32_e32 v32, 1.0, v32
	v_rcp_f32_e32 v138, v35
	v_add_f32_e32 v35, 1.0, v144
	v_rcp_f32_e32 v32, v32
	v_rcp_f32_e32 v139, v35
	v_add_f32_e32 v35, 1.0, v145
	v_rcp_f32_e32 v142, v35
	v_add_f32_e32 v35, 1.0, v146
	v_rcp_f32_e32 v143, v35
	v_mov_b32_e32 v144, v41
	v_mov_b32_e32 v145, v42
	v_pk_mul_f32 v[136:137], v[144:145], v[136:137]
	v_pk_mov_b32 v[144:145], v[42:43], v[36:37] op_sel:[1,0]
	v_add_f32_e32 v35, 1.0, v147
	v_fma_mixlo_f16 v32, v40, v32, 0
	v_cvt_pk_f16_f32 v137, v136, v137
	v_pk_mul_f32 v[138:139], v[144:145], v[138:139]
	v_rcp_f32_e32 v35, v35
	v_pack_b32_f16 v136, v32, v137
	v_cvt_pk_f16_f32 v32, v138, v139
	v_mov_b32_e32 v138, v37
	v_mov_b32_e32 v139, v38
	v_pk_mul_f32 v[138:139], v[138:139], v[142:143]
	v_alignbit_b32 v137, v32, v137, 16
	v_cvt_pk_f16_f32 v139, v138, v139
	v_alignbit_b32 v138, v139, v32, 16
	v_lshrrev_b32_e32 v139, 16, v139
	v_fma_mixhi_f16 v139, v39, v35, 0
	v_cvt_f32_f16_e32 v32, v132
	v_cvt_f32_f16_sdwa v35, v132 dst_sel:DWORD dst_unused:UNUSED_PAD src0_sel:WORD_1
	v_cvt_f32_f16_e32 v132, v133
	v_cvt_f32_f16_sdwa v133, v133 dst_sel:DWORD dst_unused:UNUSED_PAD src0_sel:WORD_1
	v_lshlrev_b64 v[140:141], 11, v[170:171]
	v_lshl_add_u64 v[140:141], s[14:15], 0, v[140:141]
	v_max_f32_e32 v132, 0xc1f00000, v132
	v_lshl_add_u64 v[140:141], v[140:141], 0, v[166:167]
	v_mul_f32_e32 v132, 0xbfb8aa3b, v132
	global_store_dwordx4 v[140:141], v[136:139], off
	v_max_f32_e32 v35, 0xc1f00000, v35
	v_mul_f32_e32 v35, 0xbfb8aa3b, v35
	v_exp_f32_e32 v136, v132
	v_max_f32_e32 v132, 0xc1f00000, v133
	v_mul_f32_e32 v132, 0xbfb8aa3b, v132
	v_cvt_f32_f16_e32 v133, v134
	v_exp_f32_e32 v137, v132
	v_cvt_f32_f16_sdwa v132, v134 dst_sel:DWORD dst_unused:UNUSED_PAD src0_sel:WORD_1
	v_exp_f32_e32 v35, v35
	v_max_f32_e32 v133, 0xc1f00000, v133
	v_mul_f32_e32 v133, 0xbfb8aa3b, v133
	v_max_f32_e32 v132, 0xc1f00000, v132
	v_mul_f32_e32 v132, 0xbfb8aa3b, v132
	v_exp_f32_e32 v138, v133
	v_cvt_f32_f16_e32 v133, v135
	v_exp_f32_e32 v139, v132
	v_cvt_f32_f16_sdwa v132, v135 dst_sel:DWORD dst_unused:UNUSED_PAD src0_sel:WORD_1
	v_max_f32_e32 v32, 0xc1f00000, v32
	v_mul_f32_e32 v32, 0xbfb8aa3b, v32
	v_exp_f32_e32 v32, v32
	v_max_f32_e32 v133, 0xc1f00000, v133
	v_max_f32_e32 v132, 0xc1f00000, v132
	v_mul_f32_e32 v133, 0xbfb8aa3b, v133
	v_mul_f32_e32 v132, 0xbfb8aa3b, v132
	v_add_f32_e32 v35, 1.0, v35
	v_exp_f32_e32 v142, v133
	v_exp_f32_e32 v143, v132
	v_rcp_f32_e32 v132, v35
	v_add_f32_e32 v35, 1.0, v136
	v_rcp_f32_e32 v133, v35
	v_add_f32_e32 v35, 1.0, v137
	v_add_f32_e32 v32, 1.0, v32
	v_rcp_f32_e32 v134, v35
	v_add_f32_e32 v35, 1.0, v138
	v_rcp_f32_e32 v32, v32
	v_rcp_f32_e32 v135, v35
	v_add_f32_e32 v35, 1.0, v139
	v_rcp_f32_e32 v136, v35
	v_add_f32_e32 v35, 1.0, v142
	v_rcp_f32_e32 v137, v35
	v_mov_b32_e32 v138, v5
	v_mov_b32_e32 v139, v6
	v_pk_mul_f32 v[132:133], v[138:139], v[132:133]
	v_pk_mov_b32 v[138:139], v[6:7], v[0:1] op_sel:[1,0]
	v_add_f32_e32 v35, 1.0, v143
	v_fma_mixlo_f16 v32, v4, v32, 0
	v_cvt_pk_f16_f32 v133, v132, v133
	v_pk_mul_f32 v[134:135], v[138:139], v[134:135]
	v_rcp_f32_e32 v35, v35
	v_pack_b32_f16 v132, v32, v133
	v_cvt_pk_f16_f32 v32, v134, v135
	v_mov_b32_e32 v134, v1
	v_mov_b32_e32 v135, v2
	v_pk_mul_f32 v[134:135], v[134:135], v[136:137]
	v_alignbit_b32 v133, v32, v133, 16
	v_cvt_pk_f16_f32 v135, v134, v135
	v_alignbit_b32 v134, v135, v32, 16
	v_lshrrev_b32_e32 v135, 16, v135
	v_fma_mixhi_f16 v135, v3, v35, 0
	global_store_dwordx4 v[140:141], v[132:135], off offset:256
	s_cbranch_execnz .LBB0_944

.LBB0_958:
	s_add_u32 s12, s10, 0x100
	s_addc_u32 s13, s11, 0
	s_add_i32 s38, 0, 0x10000
	v_add_u32_e32 v142, s38, v196
	ds_read_b128 v[122:125], v142
	ds_read_b128 v[138:141], v142 offset:2048
	ds_read_b128 v[130:133], v142 offset:1024
	ds_read_b128 v[142:145], v142 offset:3072
	s_cmp_eq_u32 s37, 12
	s_cselect_b32 s17, s7, s13
	s_cselect_b32 s16, s6, s12
	s_cselect_b32 s15, s9, s36
	s_cselect_b32 s14, s8, s35
	v_lshl_add_u64 v[230:231], s[10:11], 0, v[188:189]
	s_add_i32 m0, s21, 0xc000
	ds_read_b128 v[146:149], v198
	ds_read_b128 v[192:195], v198 offset:2048
	ds_read_b128 v[204:207], v198 offset:4096
	ds_read_b128 v[212:215], v198 offset:6144
	ds_read_b128 v[150:153], v198 offset:1024
	ds_read_b128 v[200:203], v198 offset:3072
	ds_read_b128 v[208:211], v198 offset:5120
	ds_read_b128 v[216:219], v198 offset:7168
	global_load_lds_dwordx4 v[230:231], off
	v_lshl_add_u64 v[230:231], s[10:11], 0, v[190:191]
	s_add_i32 m0, s21, 0xe000
	s_nop 0
	global_load_lds_dwordx4 v[230:231], off
	s_waitcnt lgkmcnt(8)
	s_barrier
	s_waitcnt lgkmcnt(7)
	s_setprio 1
	v_mfma_f32_16x16x32_f16 v[134:137], v[122:125], v[146:149], v[134:137]
	v_mfma_f32_16x16x32_f16 v[126:129], v[138:141], v[146:149], v[126:129]
	s_waitcnt lgkmcnt(6)
	v_mfma_f32_16x16x32_f16 v[110:113], v[122:125], v[192:195], v[110:113]
	v_mfma_f32_16x16x32_f16 v[106:109], v[138:141], v[192:195], v[106:109]
	s_waitcnt lgkmcnt(5)
	v_mfma_f32_16x16x32_f16 v[94:97], v[122:125], v[204:207], v[94:97]
	v_mfma_f32_16x16x32_f16 v[90:93], v[138:141], v[204:207], v[90:93]
	s_waitcnt lgkmcnt(4)
	v_mfma_f32_16x16x32_f16 v[78:81], v[122:125], v[212:215], v[78:81]
	v_mfma_f32_16x16x32_f16 v[74:77], v[138:141], v[212:215], v[74:77]
	s_waitcnt lgkmcnt(3)
	v_mfma_f32_16x16x32_f16 v[134:137], v[130:133], v[150:153], v[134:137]
	v_mfma_f32_16x16x32_f16 v[126:129], v[142:145], v[150:153], v[126:129]
	s_waitcnt lgkmcnt(2)
	v_mfma_f32_16x16x32_f16 v[110:113], v[130:133], v[200:203], v[110:113]
	v_mfma_f32_16x16x32_f16 v[106:109], v[142:145], v[200:203], v[106:109]
	s_waitcnt lgkmcnt(1)
	v_mfma_f32_16x16x32_f16 v[94:97], v[130:133], v[208:211], v[94:97]
	v_mfma_f32_16x16x32_f16 v[90:93], v[142:145], v[208:211], v[90:93]
	s_waitcnt lgkmcnt(0)
	v_mfma_f32_16x16x32_f16 v[78:81], v[130:133], v[216:219], v[78:81]
	v_mfma_f32_16x16x32_f16 v[74:77], v[142:145], v[216:219], v[74:77]
	s_setprio 0
	s_barrier
	s_add_i32 s39, 0, 0x14000
	s_add_i32 s10, s38, s20
	v_add_u32_e32 v199, s39, v196
	v_lshl_add_u64 v[246:247], s[14:15], 0, v[32:33]
	s_mov_b32 m0, s10
	ds_read_b128 v[230:233], v199
	ds_read_b128 v[238:241], v199 offset:2048
	ds_read_b128 v[234:237], v199 offset:1024
	ds_read_b128 v[242:245], v199 offset:3072
	global_load_lds_dwordx4 v[246:247], off
	v_lshl_add_u64 v[248:249], s[14:15], 0, v[154:155]
	s_add_i32 m0, s10, 0x2000
	s_nop 0
	global_load_lds_dwordx4 v[248:249], off
	s_barrier
	s_waitcnt lgkmcnt(2)
	s_setprio 1
	v_mfma_f32_16x16x32_f16 v[118:121], v[230:233], v[146:149], v[118:121]
	v_mfma_f32_16x16x32_f16 v[114:117], v[238:241], v[146:149], v[114:117]
	v_mfma_f32_16x16x32_f16 v[102:105], v[230:233], v[192:195], v[102:105]
	v_mfma_f32_16x16x32_f16 v[98:101], v[238:241], v[192:195], v[98:101]
	v_mfma_f32_16x16x32_f16 v[86:89], v[230:233], v[204:207], v[86:89]
	v_mfma_f32_16x16x32_f16 v[82:85], v[238:241], v[204:207], v[82:85]
	v_mfma_f32_16x16x32_f16 v[70:73], v[230:233], v[212:215], v[70:73]
	v_mfma_f32_16x16x32_f16 v[66:69], v[238:241], v[212:215], v[66:69]
	s_waitcnt lgkmcnt(0)
	v_mfma_f32_16x16x32_f16 v[118:121], v[234:237], v[150:153], v[118:121]
	v_mfma_f32_16x16x32_f16 v[114:117], v[242:245], v[150:153], v[114:117]
	v_mfma_f32_16x16x32_f16 v[102:105], v[234:237], v[200:203], v[102:105]
	v_mfma_f32_16x16x32_f16 v[98:101], v[242:245], v[200:203], v[98:101]
	v_mfma_f32_16x16x32_f16 v[86:89], v[234:237], v[208:211], v[86:89]
	v_mfma_f32_16x16x32_f16 v[82:85], v[242:245], v[208:211], v[82:85]
	v_mfma_f32_16x16x32_f16 v[70:73], v[234:237], v[216:219], v[70:73]
	v_mfma_f32_16x16x32_f16 v[66:69], v[242:245], v[216:219], v[66:69]
	s_setprio 0
	s_mov_b32 m0, s21
	v_lshl_add_u64 v[228:229], s[16:17], 0, v[32:33]
	s_barrier
	ds_read_b128 v[146:149], v198 offset:16384
	ds_read_b128 v[192:195], v198 offset:18432
	ds_read_b128 v[204:207], v198 offset:20480
	ds_read_b128 v[212:215], v198 offset:22528
	ds_read_b128 v[150:153], v198 offset:17408
	ds_read_b128 v[200:203], v198 offset:19456
	ds_read_b128 v[208:211], v198 offset:21504
	ds_read_b128 v[216:219], v198 offset:23552
	global_load_lds_dwordx4 v[228:229], off
	v_lshl_add_u64 v[222:223], s[16:17], 0, v[154:155]
	s_mov_b32 m0, s22
	s_nop 0
	global_load_lds_dwordx4 v[222:223], off
	s_waitcnt vmcnt(10)
	s_barrier
	s_waitcnt lgkmcnt(7)
	s_setprio 1
	v_mfma_f32_16x16x32_f16 v[62:65], v[122:125], v[146:149], v[62:65]
	v_mfma_f32_16x16x32_f16 v[58:61], v[138:141], v[146:149], v[58:61]
	s_waitcnt lgkmcnt(6)
	v_mfma_f32_16x16x32_f16 v[46:49], v[122:125], v[192:195], v[46:49]
	v_mfma_f32_16x16x32_f16 v[42:45], v[138:141], v[192:195], v[42:45]
	s_waitcnt lgkmcnt(5)
	v_mfma_f32_16x16x32_f16 v[28:31], v[122:125], v[204:207], v[28:31]
	v_mfma_f32_16x16x32_f16 v[24:27], v[138:141], v[204:207], v[24:27]
	s_waitcnt lgkmcnt(4)
	v_mfma_f32_16x16x32_f16 v[12:15], v[122:125], v[212:215], v[12:15]
	v_mfma_f32_16x16x32_f16 v[8:11], v[138:141], v[212:215], v[8:11]
	s_waitcnt lgkmcnt(3)
	v_mfma_f32_16x16x32_f16 v[62:65], v[130:133], v[150:153], v[62:65]
	v_mfma_f32_16x16x32_f16 v[58:61], v[142:145], v[150:153], v[58:61]
	s_waitcnt lgkmcnt(2)
	v_mfma_f32_16x16x32_f16 v[46:49], v[130:133], v[200:203], v[46:49]
	v_mfma_f32_16x16x32_f16 v[42:45], v[142:145], v[200:203], v[42:45]
	s_waitcnt lgkmcnt(1)
	v_mfma_f32_16x16x32_f16 v[28:31], v[130:133], v[208:211], v[28:31]
	v_mfma_f32_16x16x32_f16 v[24:27], v[142:145], v[208:211], v[24:27]
	s_waitcnt lgkmcnt(0)
	v_mfma_f32_16x16x32_f16 v[12:15], v[130:133], v[216:219], v[12:15]
	v_mfma_f32_16x16x32_f16 v[8:11], v[142:145], v[216:219], v[8:11]
	s_setprio 0
	s_barrier
	s_add_u32 s10, s14, 0x40000
	s_addc_u32 s11, s15, 0
	s_add_i32 s38, s39, s20
	v_lshl_add_u64 v[122:123], s[10:11], 0, v[32:33]
	s_mov_b32 m0, s38
	s_nop 0
	global_load_lds_dwordx4 v[122:123], off
	v_lshl_add_u64 v[122:123], s[10:11], 0, v[154:155]
	s_add_i32 m0, s38, 0x2000
	s_nop 0
	global_load_lds_dwordx4 v[122:123], off
	v_add_u32_e32 v142, 0x18000, v196
	ds_read_b128 v[122:125], v142
	ds_read_b128 v[138:141], v142 offset:2048
	ds_read_b128 v[130:133], v142 offset:1024
	ds_read_b128 v[142:145], v142 offset:3072
	s_waitcnt vmcnt(6)
	s_barrier
	s_setprio 1
	v_mfma_f32_16x16x32_f16 v[54:57], v[230:233], v[146:149], v[54:57]
	v_mfma_f32_16x16x32_f16 v[50:53], v[238:241], v[146:149], v[50:53]
	v_mfma_f32_16x16x32_f16 v[38:41], v[230:233], v[192:195], v[38:41]
	v_mfma_f32_16x16x32_f16 v[34:37], v[238:241], v[192:195], v[34:37]
	v_mfma_f32_16x16x32_f16 v[20:23], v[230:233], v[204:207], v[20:23]
	v_mfma_f32_16x16x32_f16 v[16:19], v[238:241], v[204:207], v[16:19]
	v_mfma_f32_16x16x32_f16 v[4:7], v[230:233], v[212:215], v[4:7]
	v_mfma_f32_16x16x32_f16 v[0:3], v[238:241], v[212:215], v[0:3]
	v_mfma_f32_16x16x32_f16 v[54:57], v[234:237], v[150:153], v[54:57]
	v_mfma_f32_16x16x32_f16 v[50:53], v[242:245], v[150:153], v[50:53]
	v_mfma_f32_16x16x32_f16 v[38:41], v[234:237], v[200:203], v[38:41]
	v_mfma_f32_16x16x32_f16 v[34:37], v[242:245], v[200:203], v[34:37]
	v_mfma_f32_16x16x32_f16 v[20:23], v[234:237], v[208:211], v[20:23]
	v_mfma_f32_16x16x32_f16 v[16:19], v[242:245], v[208:211], v[16:19]
	v_mfma_f32_16x16x32_f16 v[4:7], v[234:237], v[216:219], v[4:7]
	v_mfma_f32_16x16x32_f16 v[0:3], v[242:245], v[216:219], v[0:3]
	s_setprio 0
	s_add_i32 s38, 0, 0x18000
	s_barrier
	s_add_u32 s10, s16, 0x40000
	s_addc_u32 s11, s17, 0
	s_mov_b32 m0, s23
	v_lshl_add_u64 v[230:231], s[10:11], 0, v[32:33]
	ds_read_b128 v[146:149], v198 offset:32768
	ds_read_b128 v[192:195], v198 offset:34816
	ds_read_b128 v[204:207], v198 offset:36864
	ds_read_b128 v[212:215], v198 offset:38912
	ds_read_b128 v[150:153], v198 offset:33792
	ds_read_b128 v[200:203], v198 offset:35840
	ds_read_b128 v[208:211], v198 offset:37888
	ds_read_b128 v[216:219], v198 offset:39936
	global_load_lds_dwordx4 v[230:231], off
	v_lshl_add_u64 v[230:231], s[10:11], 0, v[154:155]
	s_mov_b32 m0, s24
	s_nop 0
	global_load_lds_dwordx4 v[230:231], off
	s_waitcnt lgkmcnt(8)
	s_barrier
	s_waitcnt lgkmcnt(7)
	s_setprio 1
	v_mfma_f32_16x16x32_f16 v[134:137], v[122:125], v[146:149], v[134:137]
	v_mfma_f32_16x16x32_f16 v[126:129], v[138:141], v[146:149], v[126:129]
	s_waitcnt lgkmcnt(6)
	v_mfma_f32_16x16x32_f16 v[110:113], v[122:125], v[192:195], v[110:113]
	v_mfma_f32_16x16x32_f16 v[106:109], v[138:141], v[192:195], v[106:109]
	s_waitcnt lgkmcnt(5)
	v_mfma_f32_16x16x32_f16 v[94:97], v[122:125], v[204:207], v[94:97]
	v_mfma_f32_16x16x32_f16 v[90:93], v[138:141], v[204:207], v[90:93]
	s_waitcnt lgkmcnt(4)
	v_mfma_f32_16x16x32_f16 v[78:81], v[122:125], v[212:215], v[78:81]
	v_mfma_f32_16x16x32_f16 v[74:77], v[138:141], v[212:215], v[74:77]
	s_waitcnt lgkmcnt(3)
	v_mfma_f32_16x16x32_f16 v[134:137], v[130:133], v[150:153], v[134:137]
	v_mfma_f32_16x16x32_f16 v[126:129], v[142:145], v[150:153], v[126:129]
	s_waitcnt lgkmcnt(2)
	v_mfma_f32_16x16x32_f16 v[110:113], v[130:133], v[200:203], v[110:113]
	v_mfma_f32_16x16x32_f16 v[106:109], v[142:145], v[200:203], v[106:109]
	s_waitcnt lgkmcnt(1)
	v_mfma_f32_16x16x32_f16 v[94:97], v[130:133], v[208:211], v[94:97]
	v_mfma_f32_16x16x32_f16 v[90:93], v[142:145], v[208:211], v[90:93]
	s_waitcnt lgkmcnt(0)
	v_mfma_f32_16x16x32_f16 v[78:81], v[130:133], v[216:219], v[78:81]
	v_mfma_f32_16x16x32_f16 v[74:77], v[142:145], v[216:219], v[74:77]
	s_setprio 0
	s_barrier
	s_add_i32 s16, 0, 0x1c000
	s_add_i32 s10, s38, s20
	v_add_u32_e32 v199, s16, v196
	v_lshl_add_u64 v[246:247], v[246:247], 0, s[84:85]
	s_mov_b32 m0, s10
	ds_read_b128 v[230:233], v199
	ds_read_b128 v[238:241], v199 offset:2048
	ds_read_b128 v[234:237], v199 offset:1024
	ds_read_b128 v[242:245], v199 offset:3072
	global_load_lds_dwordx4 v[246:247], off
	v_lshl_add_u64 v[246:247], v[248:249], 0, s[84:85]
	s_add_i32 m0, s10, 0x2000
	s_nop 0
	global_load_lds_dwordx4 v[246:247], off
	s_barrier
	s_waitcnt lgkmcnt(2)
	s_setprio 1
	v_mfma_f32_16x16x32_f16 v[118:121], v[230:233], v[146:149], v[118:121]
	v_mfma_f32_16x16x32_f16 v[114:117], v[238:241], v[146:149], v[114:117]
	v_mfma_f32_16x16x32_f16 v[102:105], v[230:233], v[192:195], v[102:105]
	v_mfma_f32_16x16x32_f16 v[98:101], v[238:241], v[192:195], v[98:101]
	v_mfma_f32_16x16x32_f16 v[86:89], v[230:233], v[204:207], v[86:89]
	v_mfma_f32_16x16x32_f16 v[82:85], v[238:241], v[204:207], v[82:85]
	v_mfma_f32_16x16x32_f16 v[70:73], v[230:233], v[212:215], v[70:73]
	v_mfma_f32_16x16x32_f16 v[66:69], v[238:241], v[212:215], v[66:69]
	s_waitcnt lgkmcnt(0)
	v_mfma_f32_16x16x32_f16 v[118:121], v[234:237], v[150:153], v[118:121]
	v_mfma_f32_16x16x32_f16 v[114:117], v[242:245], v[150:153], v[114:117]
	v_mfma_f32_16x16x32_f16 v[102:105], v[234:237], v[200:203], v[102:105]
	v_mfma_f32_16x16x32_f16 v[98:101], v[242:245], v[200:203], v[98:101]
	v_mfma_f32_16x16x32_f16 v[86:89], v[234:237], v[208:211], v[86:89]
	v_mfma_f32_16x16x32_f16 v[82:85], v[242:245], v[208:211], v[82:85]
	v_mfma_f32_16x16x32_f16 v[70:73], v[234:237], v[216:219], v[70:73]
	v_mfma_f32_16x16x32_f16 v[66:69], v[242:245], v[216:219], v[66:69]
	s_setprio 0
	s_mov_b32 m0, s25
	v_lshl_add_u64 v[228:229], v[228:229], 0, s[84:85]
	s_barrier
	ds_read_b128 v[146:149], v198 offset:49152
	ds_read_b128 v[192:195], v198 offset:51200
	ds_read_b128 v[204:207], v198 offset:53248
	ds_read_b128 v[212:215], v198 offset:55296
	ds_read_b128 v[150:153], v198 offset:50176
	ds_read_b128 v[200:203], v198 offset:52224
	ds_read_b128 v[208:211], v198 offset:54272
	ds_read_b128 v[216:219], v198 offset:56320
	global_load_lds_dwordx4 v[228:229], off
	v_lshl_add_u64 v[222:223], v[222:223], 0, s[84:85]
	s_mov_b32 m0, s27
	s_nop 0
	global_load_lds_dwordx4 v[222:223], off
	s_barrier
	s_waitcnt lgkmcnt(7)
	s_setprio 1
	v_mfma_f32_16x16x32_f16 v[62:65], v[122:125], v[146:149], v[62:65]
	v_mfma_f32_16x16x32_f16 v[58:61], v[138:141], v[146:149], v[58:61]
	s_waitcnt lgkmcnt(6)
	v_mfma_f32_16x16x32_f16 v[46:49], v[122:125], v[192:195], v[46:49]
	v_mfma_f32_16x16x32_f16 v[42:45], v[138:141], v[192:195], v[42:45]
	s_waitcnt lgkmcnt(5)
	v_mfma_f32_16x16x32_f16 v[28:31], v[122:125], v[204:207], v[28:31]
	v_mfma_f32_16x16x32_f16 v[24:27], v[138:141], v[204:207], v[24:27]
	s_waitcnt lgkmcnt(4)
	v_mfma_f32_16x16x32_f16 v[12:15], v[122:125], v[212:215], v[12:15]
	v_mfma_f32_16x16x32_f16 v[8:11], v[138:141], v[212:215], v[8:11]
	s_waitcnt lgkmcnt(3)
	v_mfma_f32_16x16x32_f16 v[62:65], v[130:133], v[150:153], v[62:65]
	v_mfma_f32_16x16x32_f16 v[58:61], v[142:145], v[150:153], v[58:61]
	s_waitcnt lgkmcnt(2)
	v_mfma_f32_16x16x32_f16 v[46:49], v[130:133], v[200:203], v[46:49]
	v_mfma_f32_16x16x32_f16 v[42:45], v[142:145], v[200:203], v[42:45]
	s_waitcnt lgkmcnt(1)
	v_mfma_f32_16x16x32_f16 v[28:31], v[130:133], v[208:211], v[28:31]
	v_mfma_f32_16x16x32_f16 v[24:27], v[142:145], v[208:211], v[24:27]
	s_waitcnt lgkmcnt(0)
	v_mfma_f32_16x16x32_f16 v[12:15], v[130:133], v[216:219], v[12:15]
	v_mfma_f32_16x16x32_f16 v[8:11], v[142:145], v[216:219], v[8:11]
	s_setprio 0
	s_barrier
	s_add_u32 s10, s14, 0x40080
	s_addc_u32 s11, s15, 0
	s_add_i32 s14, s16, s20
	v_lshl_add_u64 v[122:123], s[10:11], 0, v[32:33]
	s_mov_b32 m0, s14
	s_nop 0
	global_load_lds_dwordx4 v[122:123], off
	v_lshl_add_u64 v[122:123], s[10:11], 0, v[154:155]
	s_add_i32 m0, s14, 0x2000
	s_nop 0
	global_load_lds_dwordx4 v[122:123], off
	s_waitcnt vmcnt(6)
	s_barrier
	s_setprio 1
	v_mfma_f32_16x16x32_f16 v[54:57], v[230:233], v[146:149], v[54:57]
	v_mfma_f32_16x16x32_f16 v[50:53], v[238:241], v[146:149], v[50:53]
	v_mfma_f32_16x16x32_f16 v[38:41], v[230:233], v[192:195], v[38:41]
	v_mfma_f32_16x16x32_f16 v[34:37], v[238:241], v[192:195], v[34:37]
	v_mfma_f32_16x16x32_f16 v[20:23], v[230:233], v[204:207], v[20:23]
	v_mfma_f32_16x16x32_f16 v[16:19], v[238:241], v[204:207], v[16:19]
	v_mfma_f32_16x16x32_f16 v[4:7], v[230:233], v[212:215], v[4:7]
	v_mfma_f32_16x16x32_f16 v[0:3], v[238:241], v[212:215], v[0:3]
	v_mfma_f32_16x16x32_f16 v[54:57], v[234:237], v[150:153], v[54:57]
	v_mfma_f32_16x16x32_f16 v[50:53], v[242:245], v[150:153], v[50:53]
	v_mfma_f32_16x16x32_f16 v[38:41], v[234:237], v[200:203], v[38:41]
	v_mfma_f32_16x16x32_f16 v[34:37], v[242:245], v[200:203], v[34:37]
	v_mfma_f32_16x16x32_f16 v[20:23], v[234:237], v[208:211], v[20:23]
	v_mfma_f32_16x16x32_f16 v[16:19], v[242:245], v[208:211], v[16:19]
	v_mfma_f32_16x16x32_f16 v[4:7], v[234:237], v[216:219], v[4:7]
	v_mfma_f32_16x16x32_f16 v[0:3], v[242:245], v[216:219], v[0:3]
	s_setprio 0
	s_add_i32 s37, s37, 2
	s_add_u32 s35, s35, 0x100
	s_addc_u32 s36, s36, 0
	s_cmp_gt_u32 s37, 13
	s_mov_b64 s[10:11], s[12:13]
	s_barrier
	s_cbranch_scc0 .LBB0_958
	s_cmp_eq_u32 s34, 2
	s_movk_i32 s6, 0x2800
	v_lshl_or_b32 v122, s31, 8, v197
	s_cselect_b32 s6, 0x2000, s6
	s_mov_b32 s7, 0x23a3c000
	s_cselect_b32 s8, s7, 0x23abc000
	s_add_u32 s6, s70, s6
	v_ashrrev_i32_e32 v123, 31, v122
	s_addc_u32 s7, s71, 0
	v_lshlrev_b64 v[192:193], 1, v[122:123]
	v_lshl_add_u64 v[194:195], s[6:7], 0, v[192:193]
	v_lshl_add_u64 v[122:123], v[194:195], 0, v[156:157]
	v_lshl_add_u64 v[124:125], v[194:195], 0, v[158:159]
	v_lshl_add_u64 v[130:131], v[194:195], 0, v[160:161]
	v_lshl_add_u64 v[208:209], v[194:195], 0, v[162:163]
	global_load_dwordx4 v[200:203], v[122:123], off
	global_load_dwordx4 v[204:207], v[122:123], off offset:256
	global_load_dwordx4 v[150:153], v[124:125], off
	global_load_dwordx4 v[146:149], v[124:125], off offset:256
	global_load_dwordx4 v[142:145], v[130:131], off
	global_load_dwordx4 v[138:141], v[130:131], off offset:256
	s_nop 0
	global_load_dwordx4 v[130:133], v[208:209], off
	global_load_dwordx4 v[122:125], v[208:209], off offset:256
	v_readlane_b32 s36, v252, 26
	v_readlane_b32 s42, v252, 32
	v_readlane_b32 s43, v252, 33
	s_add_u32 s6, s42, s8
	s_addc_u32 s7, s43, 0
	v_readlane_b32 s37, v252, 27
	v_readlane_b32 s38, v252, 28
	v_readlane_b32 s39, v252, 29
	v_readlane_b32 s40, v252, 30
	v_readlane_b32 s41, v252, 31
	v_lshl_add_u64 v[192:193], s[6:7], 0, v[192:193]
	s_waitcnt vmcnt(0)
	v_cvt_f32_f16_e32 v199, v200
	v_cvt_f32_f16_sdwa v200, v200 dst_sel:DWORD dst_unused:UNUSED_PAD src0_sel:WORD_1
	v_cvt_f32_f16_e32 v210, v201
	v_lshl_add_u64 v[208:209], v[192:193], 0, v[164:165]
	v_max_f32_e32 v199, 0xc1f00000, v199
	v_mul_f32_e32 v199, 0xbfb8aa3b, v199
	v_exp_f32_e32 v199, v199
	v_max_f32_e32 v200, 0xc1f00000, v200
	v_max_f32_e32 v210, 0xc1f00000, v210
	v_mul_f32_e32 v200, 0xbfb8aa3b, v200
	v_add_f32_e32 v199, 1.0, v199
	v_rcp_f32_e32 v199, v199
	v_exp_f32_e32 v200, v200
	v_mul_f32_e32 v210, 0xbfb8aa3b, v210
	v_exp_f32_e32 v211, v210
	v_fma_mixlo_f16 v199, v134, v199, 0
	v_add_f32_e32 v134, 1.0, v200
	v_rcp_f32_e32 v210, v134
	v_add_f32_e32 v134, 1.0, v211
	v_cvt_f32_f16_sdwa v200, v201 dst_sel:DWORD dst_unused:UNUSED_PAD src0_sel:WORD_1
	v_rcp_f32_e32 v211, v134
	v_mov_b32_e32 v134, v135
	v_mov_b32_e32 v135, v136
	v_cvt_f32_f16_e32 v136, v202
	v_max_f32_e32 v200, 0xc1f00000, v200
	v_mul_f32_e32 v200, 0xbfb8aa3b, v200
	v_exp_f32_e32 v200, v200
	v_max_f32_e32 v136, 0xc1f00000, v136
	v_mul_f32_e32 v136, 0xbfb8aa3b, v136
	v_exp_f32_e32 v136, v136
	v_pk_mul_f32 v[134:135], v[134:135], v[210:211]
	s_nop 0
	v_cvt_pk_f16_f32 v135, v134, v135
	v_add_f32_e32 v134, 1.0, v200
	v_rcp_f32_e32 v200, v134
	v_add_f32_e32 v134, 1.0, v136
	v_rcp_f32_e32 v201, v134
	v_pk_mov_b32 v[136:137], v[136:137], v[126:127] op_sel:[1,0]
	v_cvt_f32_f16_sdwa v126, v202 dst_sel:DWORD dst_unused:UNUSED_PAD src0_sel:WORD_1
	v_pack_b32_f16 v134, v199, v135
	v_pk_mul_f32 v[136:137], v[136:137], v[200:201]
	v_cvt_f32_f16_sdwa v200, v203 dst_sel:DWORD dst_unused:UNUSED_PAD src0_sel:WORD_1
	v_cvt_pk_f16_f32 v199, v136, v137
	v_cvt_f32_f16_e32 v136, v203
	v_max_f32_e32 v126, 0xc1f00000, v126
	v_mul_f32_e32 v126, 0xbfb8aa3b, v126
	v_exp_f32_e32 v126, v126
	v_max_f32_e32 v136, 0xc1f00000, v136
	v_mul_f32_e32 v136, 0xbfb8aa3b, v136
	v_exp_f32_e32 v137, v136
	v_add_f32_e32 v126, 1.0, v126
	v_rcp_f32_e32 v136, v126
	v_alignbit_b32 v135, v199, v135, 16
	v_add_f32_e32 v126, 1.0, v137
	v_rcp_f32_e32 v137, v126
	v_mov_b32_e32 v126, v127
	v_mov_b32_e32 v127, v128
	v_cvt_f32_f16_e32 v128, v204
	v_pk_mul_f32 v[126:127], v[126:127], v[136:137]
	s_nop 0
	v_cvt_pk_f16_f32 v126, v126, v127
	v_max_f32_e32 v127, 0xc1f00000, v200
	v_mul_f32_e32 v127, 0xbfb8aa3b, v127
	v_exp_f32_e32 v127, v127
	v_alignbit_b32 v136, v126, v199, 16
	v_lshrrev_b32_e32 v137, 16, v126
	v_add_f32_e32 v126, 1.0, v127
	v_rcp_f32_e32 v126, v126
	v_max_f32_e32 v127, 0xc1f00000, v128
	v_mul_f32_e32 v127, 0xbfb8aa3b, v127
	v_exp_f32_e32 v127, v127
	v_fma_mixhi_f16 v137, v129, v126, 0
	v_cvt_f32_f16_sdwa v126, v204 dst_sel:DWORD dst_unused:UNUSED_PAD src0_sel:WORD_1
	v_cvt_f32_f16_e32 v128, v205
	v_add_f32_e32 v127, 1.0, v127
	v_rcp_f32_e32 v127, v127
	v_max_f32_e32 v126, 0xc1f00000, v126
	v_mul_f32_e32 v126, 0xbfb8aa3b, v126
	v_max_f32_e32 v128, 0xc1f00000, v128
	v_exp_f32_e32 v126, v126
	v_mul_f32_e32 v128, 0xbfb8aa3b, v128
	v_exp_f32_e32 v128, v128
	v_fma_mixlo_f16 v129, v118, v127, 0
	v_add_f32_e32 v118, 1.0, v126
	v_rcp_f32_e32 v126, v118
	v_add_f32_e32 v118, 1.0, v128
	v_rcp_f32_e32 v127, v118
	v_cvt_f32_f16_sdwa v128, v205 dst_sel:DWORD dst_unused:UNUSED_PAD src0_sel:WORD_1
	v_mov_b32_e32 v118, v119
	v_mov_b32_e32 v119, v120
	v_cvt_f32_f16_e32 v120, v206
	v_max_f32_e32 v128, 0xc1f00000, v128
	v_mul_f32_e32 v128, 0xbfb8aa3b, v128
	v_exp_f32_e32 v128, v128
	v_max_f32_e32 v120, 0xc1f00000, v120
	v_mul_f32_e32 v120, 0xbfb8aa3b, v120
	v_exp_f32_e32 v120, v120
	v_pk_mul_f32 v[118:119], v[118:119], v[126:127]
	v_add_f32_e32 v126, 1.0, v128
	v_rcp_f32_e32 v126, v126
	v_add_f32_e32 v120, 1.0, v120
	v_rcp_f32_e32 v127, v120
	v_pk_mov_b32 v[120:121], v[120:121], v[114:115] op_sel:[1,0]
	v_cvt_f32_f16_sdwa v114, v206 dst_sel:DWORD dst_unused:UNUSED_PAD src0_sel:WORD_1
	v_cvt_pk_f16_f32 v119, v118, v119
	v_pk_mul_f32 v[120:121], v[120:121], v[126:127]
	v_cvt_f32_f16_sdwa v127, v207 dst_sel:DWORD dst_unused:UNUSED_PAD src0_sel:WORD_1
	v_cvt_pk_f16_f32 v126, v120, v121
	v_cvt_f32_f16_e32 v120, v207
	v_max_f32_e32 v114, 0xc1f00000, v114
	v_mul_f32_e32 v114, 0xbfb8aa3b, v114
	v_exp_f32_e32 v114, v114
	v_max_f32_e32 v120, 0xc1f00000, v120
	v_mul_f32_e32 v120, 0xbfb8aa3b, v120
	v_exp_f32_e32 v121, v120
	v_add_f32_e32 v114, 1.0, v114
	v_rcp_f32_e32 v120, v114
	v_pack_b32_f16 v118, v129, v119
	v_add_f32_e32 v114, 1.0, v121
	v_rcp_f32_e32 v121, v114
	v_mov_b32_e32 v114, v115
	v_max_f32_e32 v115, 0xc1f00000, v127
	v_mul_f32_e32 v115, 0xbfb8aa3b, v115
	v_exp_f32_e32 v127, v115
	v_mov_b32_e32 v115, v116
	v_pk_mul_f32 v[114:115], v[114:115], v[120:121]
	v_cvt_f32_f16_e32 v116, v150
	v_cvt_pk_f16_f32 v114, v114, v115
	v_add_f32_e32 v115, 1.0, v127
	v_rcp_f32_e32 v115, v115
	v_alignbit_b32 v120, v114, v126, 16
	v_lshrrev_b32_e32 v121, 16, v114
	v_max_f32_e32 v114, 0xc1f00000, v116
	v_alignbit_b32 v119, v126, v119, 16
	v_fma_mixhi_f16 v121, v117, v115, 0
	v_mul_f32_e32 v114, 0xbfb8aa3b, v114
	v_cvt_f32_f16_sdwa v117, v150 dst_sel:DWORD dst_unused:UNUSED_PAD src0_sel:WORD_1
	v_exp_f32_e32 v116, v114
	global_store_dwordx4 v[208:209], v[118:121], off offset:256
	v_lshl_add_u64 v[114:115], v[192:193], 0, v[166:167]
	v_max_f32_e32 v117, 0xc1f00000, v117
	v_cvt_f32_f16_e32 v118, v151
	v_add_f32_e32 v116, 1.0, v116
	v_mul_f32_e32 v117, 0xbfb8aa3b, v117
	v_rcp_f32_e32 v116, v116
	v_max_f32_e32 v118, 0xc1f00000, v118
	v_exp_f32_e32 v117, v117
	v_mul_f32_e32 v118, 0xbfb8aa3b, v118
	v_exp_f32_e32 v118, v118
	v_fma_mixlo_f16 v119, v110, v116, 0
	v_add_f32_e32 v110, 1.0, v117
	v_rcp_f32_e32 v116, v110
	v_add_f32_e32 v110, 1.0, v118
	v_rcp_f32_e32 v117, v110
	v_cvt_f32_f16_sdwa v118, v151 dst_sel:DWORD dst_unused:UNUSED_PAD src0_sel:WORD_1
	v_mov_b32_e32 v110, v111
	v_mov_b32_e32 v111, v112
	v_cvt_f32_f16_e32 v112, v152
	v_pk_mul_f32 v[110:111], v[110:111], v[116:117]
	v_max_f32_e32 v116, 0xc1f00000, v118
	v_mul_f32_e32 v116, 0xbfb8aa3b, v116
	v_max_f32_e32 v112, 0xc1f00000, v112
	v_exp_f32_e32 v116, v116
	v_mul_f32_e32 v112, 0xbfb8aa3b, v112
	v_exp_f32_e32 v112, v112
	v_cvt_pk_f16_f32 v111, v110, v111
	v_add_f32_e32 v110, 1.0, v116
	v_rcp_f32_e32 v116, v110
	v_add_f32_e32 v110, 1.0, v112
	v_rcp_f32_e32 v117, v110
	v_pk_mov_b32 v[112:113], v[112:113], v[106:107] op_sel:[1,0]
	v_cvt_f32_f16_sdwa v106, v152 dst_sel:DWORD dst_unused:UNUSED_PAD src0_sel:WORD_1
	v_pack_b32_f16 v110, v119, v111
	v_pk_mul_f32 v[112:113], v[112:113], v[116:117]
	v_cvt_f32_f16_sdwa v117, v153 dst_sel:DWORD dst_unused:UNUSED_PAD src0_sel:WORD_1
	v_cvt_pk_f16_f32 v116, v112, v113
	v_cvt_f32_f16_e32 v112, v153
	v_max_f32_e32 v106, 0xc1f00000, v106
	v_mul_f32_e32 v106, 0xbfb8aa3b, v106
	v_exp_f32_e32 v106, v106
	v_max_f32_e32 v112, 0xc1f00000, v112
	v_mul_f32_e32 v112, 0xbfb8aa3b, v112
	v_exp_f32_e32 v113, v112
	v_add_f32_e32 v106, 1.0, v106
	v_rcp_f32_e32 v112, v106
	v_alignbit_b32 v111, v116, v111, 16
	v_add_f32_e32 v106, 1.0, v113
	v_rcp_f32_e32 v113, v106
	v_mov_b32_e32 v106, v107
	v_mov_b32_e32 v107, v108
	v_cvt_f32_f16_e32 v108, v146
	v_pk_mul_f32 v[106:107], v[106:107], v[112:113]
	global_store_dwordx4 v[208:209], v[134:137], off
	v_cvt_pk_f16_f32 v106, v106, v107
	v_max_f32_e32 v107, 0xc1f00000, v117
	v_mul_f32_e32 v107, 0xbfb8aa3b, v107
	v_exp_f32_e32 v107, v107
	v_alignbit_b32 v112, v106, v116, 16
	v_lshrrev_b32_e32 v113, 16, v106
	v_add_f32_e32 v106, 1.0, v107
	v_rcp_f32_e32 v106, v106
	v_max_f32_e32 v107, 0xc1f00000, v108
	v_mul_f32_e32 v107, 0xbfb8aa3b, v107
	v_exp_f32_e32 v107, v107
	v_fma_mixhi_f16 v113, v109, v106, 0
	v_cvt_f32_f16_sdwa v106, v146 dst_sel:DWORD dst_unused:UNUSED_PAD src0_sel:WORD_1
	v_cvt_f32_f16_e32 v108, v147
	v_add_f32_e32 v107, 1.0, v107
	v_rcp_f32_e32 v107, v107
	v_max_f32_e32 v106, 0xc1f00000, v106
	v_mul_f32_e32 v106, 0xbfb8aa3b, v106
	v_max_f32_e32 v108, 0xc1f00000, v108
	v_exp_f32_e32 v106, v106
	v_mul_f32_e32 v108, 0xbfb8aa3b, v108
	v_exp_f32_e32 v108, v108
	v_fma_mixlo_f16 v109, v102, v107, 0
	v_add_f32_e32 v102, 1.0, v106
	v_rcp_f32_e32 v106, v102
	v_add_f32_e32 v102, 1.0, v108
	v_rcp_f32_e32 v107, v102
	v_cvt_f32_f16_sdwa v108, v147 dst_sel:DWORD dst_unused:UNUSED_PAD src0_sel:WORD_1
	v_mov_b32_e32 v102, v103
	v_mov_b32_e32 v103, v104
	v_cvt_f32_f16_e32 v104, v148
	v_max_f32_e32 v108, 0xc1f00000, v108
	v_mul_f32_e32 v108, 0xbfb8aa3b, v108
	v_exp_f32_e32 v108, v108
	v_max_f32_e32 v104, 0xc1f00000, v104
	v_mul_f32_e32 v104, 0xbfb8aa3b, v104
	v_exp_f32_e32 v104, v104
	v_pk_mul_f32 v[102:103], v[102:103], v[106:107]
	v_add_f32_e32 v106, 1.0, v108
	v_rcp_f32_e32 v106, v106
	v_add_f32_e32 v104, 1.0, v104
	v_rcp_f32_e32 v107, v104
	v_pk_mov_b32 v[104:105], v[104:105], v[98:99] op_sel:[1,0]
	v_cvt_f32_f16_sdwa v98, v148 dst_sel:DWORD dst_unused:UNUSED_PAD src0_sel:WORD_1
	v_cvt_pk_f16_f32 v103, v102, v103
	v_pk_mul_f32 v[104:105], v[104:105], v[106:107]
	v_cvt_f32_f16_sdwa v107, v149 dst_sel:DWORD dst_unused:UNUSED_PAD src0_sel:WORD_1
	v_cvt_pk_f16_f32 v106, v104, v105
	v_cvt_f32_f16_e32 v104, v149
	v_max_f32_e32 v98, 0xc1f00000, v98
	v_mul_f32_e32 v98, 0xbfb8aa3b, v98
	v_exp_f32_e32 v98, v98
	v_max_f32_e32 v104, 0xc1f00000, v104
	v_mul_f32_e32 v104, 0xbfb8aa3b, v104
	v_exp_f32_e32 v105, v104
	v_add_f32_e32 v98, 1.0, v98
	v_rcp_f32_e32 v104, v98
	v_pack_b32_f16 v102, v109, v103
	v_add_f32_e32 v98, 1.0, v105
	v_rcp_f32_e32 v105, v98
	v_mov_b32_e32 v98, v99
	v_max_f32_e32 v99, 0xc1f00000, v107
	v_mul_f32_e32 v99, 0xbfb8aa3b, v99
	v_exp_f32_e32 v107, v99
	v_mov_b32_e32 v99, v100
	v_pk_mul_f32 v[98:99], v[98:99], v[104:105]
	v_cvt_f32_f16_e32 v100, v142
	v_cvt_pk_f16_f32 v98, v98, v99
	v_add_f32_e32 v99, 1.0, v107
	v_rcp_f32_e32 v99, v99
	v_alignbit_b32 v104, v98, v106, 16
	v_lshrrev_b32_e32 v105, 16, v98
	v_max_f32_e32 v98, 0xc1f00000, v100
	v_alignbit_b32 v103, v106, v103, 16
	v_fma_mixhi_f16 v105, v101, v99, 0
	v_mul_f32_e32 v98, 0xbfb8aa3b, v98
	v_cvt_f32_f16_sdwa v101, v142 dst_sel:DWORD dst_unused:UNUSED_PAD src0_sel:WORD_1
	v_exp_f32_e32 v100, v98
	global_store_dwordx4 v[114:115], v[102:105], off offset:256
	v_lshl_add_u64 v[98:99], v[192:193], 0, v[168:169]
	v_max_f32_e32 v101, 0xc1f00000, v101
	v_cvt_f32_f16_e32 v102, v143
	v_add_f32_e32 v100, 1.0, v100
	v_mul_f32_e32 v101, 0xbfb8aa3b, v101
	v_rcp_f32_e32 v100, v100
	v_max_f32_e32 v102, 0xc1f00000, v102
	v_exp_f32_e32 v101, v101
	v_mul_f32_e32 v102, 0xbfb8aa3b, v102
	v_exp_f32_e32 v102, v102
	v_fma_mixlo_f16 v103, v94, v100, 0
	v_add_f32_e32 v94, 1.0, v101
	v_rcp_f32_e32 v100, v94
	v_add_f32_e32 v94, 1.0, v102
	v_rcp_f32_e32 v101, v94
	v_cvt_f32_f16_sdwa v102, v143 dst_sel:DWORD dst_unused:UNUSED_PAD src0_sel:WORD_1
	v_mov_b32_e32 v94, v95
	v_mov_b32_e32 v95, v96
	v_cvt_f32_f16_e32 v96, v144
	v_pk_mul_f32 v[94:95], v[94:95], v[100:101]
	v_max_f32_e32 v100, 0xc1f00000, v102
	v_mul_f32_e32 v100, 0xbfb8aa3b, v100
	v_max_f32_e32 v96, 0xc1f00000, v96
	v_exp_f32_e32 v100, v100
	v_mul_f32_e32 v96, 0xbfb8aa3b, v96
	v_exp_f32_e32 v96, v96
	v_cvt_pk_f16_f32 v95, v94, v95
	v_add_f32_e32 v94, 1.0, v100
	v_rcp_f32_e32 v100, v94
	v_add_f32_e32 v94, 1.0, v96
	v_rcp_f32_e32 v101, v94
	v_pk_mov_b32 v[96:97], v[96:97], v[90:91] op_sel:[1,0]
	v_cvt_f32_f16_sdwa v90, v144 dst_sel:DWORD dst_unused:UNUSED_PAD src0_sel:WORD_1
	v_pack_b32_f16 v94, v103, v95
	v_pk_mul_f32 v[96:97], v[96:97], v[100:101]
	v_cvt_f32_f16_sdwa v101, v145 dst_sel:DWORD dst_unused:UNUSED_PAD src0_sel:WORD_1
	v_cvt_pk_f16_f32 v100, v96, v97
	v_cvt_f32_f16_e32 v96, v145
	v_max_f32_e32 v90, 0xc1f00000, v90
	v_mul_f32_e32 v90, 0xbfb8aa3b, v90
	v_exp_f32_e32 v90, v90
	v_max_f32_e32 v96, 0xc1f00000, v96
	v_mul_f32_e32 v96, 0xbfb8aa3b, v96
	v_exp_f32_e32 v97, v96
	v_add_f32_e32 v90, 1.0, v90
	v_rcp_f32_e32 v96, v90
	v_alignbit_b32 v95, v100, v95, 16
	v_add_f32_e32 v90, 1.0, v97
	v_rcp_f32_e32 v97, v90
	v_mov_b32_e32 v90, v91
	v_mov_b32_e32 v91, v92
	v_cvt_f32_f16_e32 v92, v138
	v_pk_mul_f32 v[90:91], v[90:91], v[96:97]
	global_store_dwordx4 v[114:115], v[110:113], off
	v_cvt_pk_f16_f32 v90, v90, v91
	v_max_f32_e32 v91, 0xc1f00000, v101
	v_mul_f32_e32 v91, 0xbfb8aa3b, v91
	v_exp_f32_e32 v91, v91
	v_alignbit_b32 v96, v90, v100, 16
	v_lshrrev_b32_e32 v97, 16, v90
	v_add_f32_e32 v90, 1.0, v91
	v_rcp_f32_e32 v90, v90
	v_max_f32_e32 v91, 0xc1f00000, v92
	v_mul_f32_e32 v91, 0xbfb8aa3b, v91
	v_exp_f32_e32 v91, v91
	v_fma_mixhi_f16 v97, v93, v90, 0
	v_cvt_f32_f16_sdwa v90, v138 dst_sel:DWORD dst_unused:UNUSED_PAD src0_sel:WORD_1
	v_cvt_f32_f16_e32 v92, v139
	v_add_f32_e32 v91, 1.0, v91
	v_rcp_f32_e32 v91, v91
	v_max_f32_e32 v90, 0xc1f00000, v90
	v_mul_f32_e32 v90, 0xbfb8aa3b, v90
	v_max_f32_e32 v92, 0xc1f00000, v92
	v_exp_f32_e32 v90, v90
	v_mul_f32_e32 v92, 0xbfb8aa3b, v92
	v_exp_f32_e32 v92, v92
	v_fma_mixlo_f16 v93, v86, v91, 0
	v_add_f32_e32 v86, 1.0, v90
	v_rcp_f32_e32 v90, v86
	v_add_f32_e32 v86, 1.0, v92
	v_rcp_f32_e32 v91, v86
	v_cvt_f32_f16_sdwa v92, v139 dst_sel:DWORD dst_unused:UNUSED_PAD src0_sel:WORD_1
	v_mov_b32_e32 v86, v87
	v_mov_b32_e32 v87, v88
	v_cvt_f32_f16_e32 v88, v140
	v_max_f32_e32 v92, 0xc1f00000, v92
	v_mul_f32_e32 v92, 0xbfb8aa3b, v92
	v_exp_f32_e32 v92, v92
	v_max_f32_e32 v88, 0xc1f00000, v88
	v_mul_f32_e32 v88, 0xbfb8aa3b, v88
	v_exp_f32_e32 v88, v88
	v_pk_mul_f32 v[86:87], v[86:87], v[90:91]
	v_add_f32_e32 v90, 1.0, v92
	v_rcp_f32_e32 v90, v90
	v_add_f32_e32 v88, 1.0, v88
	v_rcp_f32_e32 v91, v88
	v_pk_mov_b32 v[88:89], v[88:89], v[82:83] op_sel:[1,0]
	v_cvt_f32_f16_sdwa v82, v140 dst_sel:DWORD dst_unused:UNUSED_PAD src0_sel:WORD_1
	v_cvt_pk_f16_f32 v87, v86, v87
	v_pk_mul_f32 v[88:89], v[88:89], v[90:91]
	v_cvt_f32_f16_sdwa v91, v141 dst_sel:DWORD dst_unused:UNUSED_PAD src0_sel:WORD_1
	v_cvt_pk_f16_f32 v90, v88, v89
	v_cvt_f32_f16_e32 v88, v141
	v_max_f32_e32 v82, 0xc1f00000, v82
	v_mul_f32_e32 v82, 0xbfb8aa3b, v82
	v_exp_f32_e32 v82, v82
	v_max_f32_e32 v88, 0xc1f00000, v88
	v_mul_f32_e32 v88, 0xbfb8aa3b, v88
	v_exp_f32_e32 v89, v88
	v_add_f32_e32 v82, 1.0, v82
	v_rcp_f32_e32 v88, v82
	v_pack_b32_f16 v86, v93, v87
	v_add_f32_e32 v82, 1.0, v89
	v_rcp_f32_e32 v89, v82
	v_mov_b32_e32 v82, v83
	v_max_f32_e32 v83, 0xc1f00000, v91
	v_mul_f32_e32 v83, 0xbfb8aa3b, v83
	v_exp_f32_e32 v91, v83
	v_mov_b32_e32 v83, v84
	v_pk_mul_f32 v[82:83], v[82:83], v[88:89]
	v_cvt_f32_f16_e32 v84, v130
	v_cvt_pk_f16_f32 v82, v82, v83
	v_add_f32_e32 v83, 1.0, v91
	v_rcp_f32_e32 v83, v83
	v_alignbit_b32 v88, v82, v90, 16
	v_lshrrev_b32_e32 v89, 16, v82
	v_max_f32_e32 v82, 0xc1f00000, v84
	v_alignbit_b32 v87, v90, v87, 16
	v_fma_mixhi_f16 v89, v85, v83, 0
	v_mul_f32_e32 v82, 0xbfb8aa3b, v82
	v_cvt_f32_f16_sdwa v85, v130 dst_sel:DWORD dst_unused:UNUSED_PAD src0_sel:WORD_1
	v_exp_f32_e32 v84, v82
	global_store_dwordx4 v[98:99], v[86:89], off offset:256
	v_lshl_add_u64 v[82:83], v[192:193], 0, v[170:171]
	v_max_f32_e32 v85, 0xc1f00000, v85
	v_cvt_f32_f16_e32 v86, v131
	v_add_f32_e32 v84, 1.0, v84
	v_mul_f32_e32 v85, 0xbfb8aa3b, v85
	v_rcp_f32_e32 v84, v84
	v_max_f32_e32 v86, 0xc1f00000, v86
	v_exp_f32_e32 v85, v85
	v_mul_f32_e32 v86, 0xbfb8aa3b, v86
	v_exp_f32_e32 v86, v86
	v_fma_mixlo_f16 v87, v78, v84, 0
	v_add_f32_e32 v78, 1.0, v85
	v_rcp_f32_e32 v84, v78
	v_add_f32_e32 v78, 1.0, v86
	v_rcp_f32_e32 v85, v78
	v_cvt_f32_f16_sdwa v86, v131 dst_sel:DWORD dst_unused:UNUSED_PAD src0_sel:WORD_1
	v_mov_b32_e32 v78, v79
	v_mov_b32_e32 v79, v80
	v_cvt_f32_f16_e32 v80, v132
	v_pk_mul_f32 v[78:79], v[78:79], v[84:85]
	v_max_f32_e32 v84, 0xc1f00000, v86
	v_mul_f32_e32 v84, 0xbfb8aa3b, v84
	v_max_f32_e32 v80, 0xc1f00000, v80
	v_exp_f32_e32 v84, v84
	v_mul_f32_e32 v80, 0xbfb8aa3b, v80
	v_exp_f32_e32 v80, v80
	v_cvt_pk_f16_f32 v79, v78, v79
	v_add_f32_e32 v78, 1.0, v84
	v_rcp_f32_e32 v84, v78
	v_add_f32_e32 v78, 1.0, v80
	v_rcp_f32_e32 v85, v78
	v_pk_mov_b32 v[80:81], v[80:81], v[74:75] op_sel:[1,0]
	v_cvt_f32_f16_sdwa v74, v132 dst_sel:DWORD dst_unused:UNUSED_PAD src0_sel:WORD_1
	v_pack_b32_f16 v78, v87, v79
	v_pk_mul_f32 v[80:81], v[80:81], v[84:85]
	v_cvt_f32_f16_sdwa v85, v133 dst_sel:DWORD dst_unused:UNUSED_PAD src0_sel:WORD_1
	v_cvt_pk_f16_f32 v84, v80, v81
	v_cvt_f32_f16_e32 v80, v133
	v_max_f32_e32 v74, 0xc1f00000, v74
	v_mul_f32_e32 v74, 0xbfb8aa3b, v74
	v_exp_f32_e32 v74, v74
	v_max_f32_e32 v80, 0xc1f00000, v80
	v_mul_f32_e32 v80, 0xbfb8aa3b, v80
	v_exp_f32_e32 v81, v80
	v_add_f32_e32 v74, 1.0, v74
	v_rcp_f32_e32 v80, v74
	v_alignbit_b32 v79, v84, v79, 16
	v_add_f32_e32 v74, 1.0, v81
	v_rcp_f32_e32 v81, v74
	v_mov_b32_e32 v74, v75
	v_mov_b32_e32 v75, v76
	v_cvt_f32_f16_e32 v76, v122
	v_pk_mul_f32 v[74:75], v[74:75], v[80:81]
	global_store_dwordx4 v[98:99], v[94:97], off
	v_cvt_pk_f16_f32 v74, v74, v75
	v_max_f32_e32 v75, 0xc1f00000, v85
	v_mul_f32_e32 v75, 0xbfb8aa3b, v75
	v_exp_f32_e32 v75, v75
	v_alignbit_b32 v80, v74, v84, 16
	v_lshrrev_b32_e32 v81, 16, v74
	v_add_f32_e32 v74, 1.0, v75
	v_rcp_f32_e32 v74, v74
	v_max_f32_e32 v75, 0xc1f00000, v76
	v_mul_f32_e32 v75, 0xbfb8aa3b, v75
	v_exp_f32_e32 v75, v75
	v_fma_mixhi_f16 v81, v77, v74, 0
	v_cvt_f32_f16_sdwa v74, v122 dst_sel:DWORD dst_unused:UNUSED_PAD src0_sel:WORD_1
	v_cvt_f32_f16_e32 v76, v123
	v_add_f32_e32 v75, 1.0, v75
	v_rcp_f32_e32 v75, v75
	v_max_f32_e32 v74, 0xc1f00000, v74
	v_mul_f32_e32 v74, 0xbfb8aa3b, v74
	v_max_f32_e32 v76, 0xc1f00000, v76
	v_exp_f32_e32 v74, v74
	v_mul_f32_e32 v76, 0xbfb8aa3b, v76
	v_exp_f32_e32 v76, v76
	v_fma_mixlo_f16 v77, v70, v75, 0
	v_add_f32_e32 v70, 1.0, v74
	v_rcp_f32_e32 v74, v70
	v_add_f32_e32 v70, 1.0, v76
	v_rcp_f32_e32 v75, v70
	v_cvt_f32_f16_sdwa v76, v123 dst_sel:DWORD dst_unused:UNUSED_PAD src0_sel:WORD_1
	v_mov_b32_e32 v70, v71
	v_mov_b32_e32 v71, v72
	v_cvt_f32_f16_e32 v72, v124
	v_max_f32_e32 v76, 0xc1f00000, v76
	v_mul_f32_e32 v76, 0xbfb8aa3b, v76
	v_exp_f32_e32 v76, v76
	v_max_f32_e32 v72, 0xc1f00000, v72
	v_mul_f32_e32 v72, 0xbfb8aa3b, v72
	v_exp_f32_e32 v72, v72
	v_pk_mul_f32 v[70:71], v[70:71], v[74:75]
	v_add_f32_e32 v74, 1.0, v76
	v_rcp_f32_e32 v74, v74
	v_add_f32_e32 v72, 1.0, v72
	v_rcp_f32_e32 v75, v72
	v_pk_mov_b32 v[72:73], v[72:73], v[66:67] op_sel:[1,0]
	v_cvt_f32_f16_sdwa v66, v124 dst_sel:DWORD dst_unused:UNUSED_PAD src0_sel:WORD_1
	v_cvt_pk_f16_f32 v71, v70, v71
	v_pk_mul_f32 v[72:73], v[72:73], v[74:75]
	v_cvt_f32_f16_sdwa v75, v125 dst_sel:DWORD dst_unused:UNUSED_PAD src0_sel:WORD_1
	v_cvt_pk_f16_f32 v74, v72, v73
	v_cvt_f32_f16_e32 v72, v125
	v_max_f32_e32 v66, 0xc1f00000, v66
	v_mul_f32_e32 v66, 0xbfb8aa3b, v66
	v_exp_f32_e32 v66, v66
	v_max_f32_e32 v72, 0xc1f00000, v72
	v_mul_f32_e32 v72, 0xbfb8aa3b, v72
	v_exp_f32_e32 v73, v72
	v_add_f32_e32 v66, 1.0, v66
	v_rcp_f32_e32 v72, v66
	v_pack_b32_f16 v70, v77, v71
	v_add_f32_e32 v66, 1.0, v73
	v_rcp_f32_e32 v73, v66
	v_max_f32_e32 v66, 0xc1f00000, v75
	v_mul_f32_e32 v66, 0xbfb8aa3b, v66
	v_exp_f32_e32 v75, v66
	v_mov_b32_e32 v66, v67
	v_mov_b32_e32 v67, v68
	v_pk_mul_f32 v[66:67], v[66:67], v[72:73]
	v_add_f32_e32 v68, 1.0, v75
	v_rcp_f32_e32 v68, v68
	v_cvt_pk_f16_f32 v66, v66, v67
	v_lshrrev_b32_e32 v73, 16, v66
	v_alignbit_b32 v71, v74, v71, 16
	v_alignbit_b32 v72, v66, v74, 16
	v_fma_mixhi_f16 v73, v69, v68, 0
	global_store_dwordx4 v[82:83], v[78:81], off
	global_store_dwordx4 v[82:83], v[70:73], off offset:256
	v_lshl_add_u64 v[66:67], v[194:195], 0, v[172:173]
	v_lshl_add_u64 v[68:69], v[194:195], 0, v[174:175]
	v_lshl_add_u64 v[70:71], v[194:195], 0, v[176:177]
	v_lshl_add_u64 v[98:99], v[194:195], 0, v[178:179]
	global_load_dwordx4 v[90:93], v[66:67], off
	global_load_dwordx4 v[94:97], v[66:67], off offset:256
	global_load_dwordx4 v[86:89], v[68:69], off
	global_load_dwordx4 v[82:85], v[68:69], off offset:256
	global_load_dwordx4 v[78:81], v[70:71], off
	global_load_dwordx4 v[74:77], v[70:71], off offset:256
	s_nop 0
	global_load_dwordx4 v[70:73], v[98:99], off
	global_load_dwordx4 v[66:69], v[98:99], off offset:256
	s_waitcnt vmcnt(0)
	v_cvt_f32_f16_e32 v100, v90
	v_cvt_f32_f16_sdwa v90, v90 dst_sel:DWORD dst_unused:UNUSED_PAD src0_sel:WORD_1
	v_cvt_f32_f16_e32 v101, v91
	v_lshl_add_u64 v[98:99], v[192:193], 0, v[180:181]
	v_max_f32_e32 v100, 0xc1f00000, v100
	v_mul_f32_e32 v100, 0xbfb8aa3b, v100
	v_exp_f32_e32 v100, v100
	v_max_f32_e32 v90, 0xc1f00000, v90
	v_max_f32_e32 v101, 0xc1f00000, v101
	v_mul_f32_e32 v90, 0xbfb8aa3b, v90
	v_add_f32_e32 v100, 1.0, v100
	v_rcp_f32_e32 v100, v100
	v_exp_f32_e32 v90, v90
	v_mul_f32_e32 v101, 0xbfb8aa3b, v101
	v_exp_f32_e32 v101, v101
	v_fma_mixlo_f16 v102, v62, v100, 0
	v_add_f32_e32 v62, 1.0, v90
	v_rcp_f32_e32 v100, v62
	v_add_f32_e32 v62, 1.0, v101
	v_cvt_f32_f16_sdwa v90, v91 dst_sel:DWORD dst_unused:UNUSED_PAD src0_sel:WORD_1
	v_rcp_f32_e32 v101, v62
	v_mov_b32_e32 v62, v63
	v_mov_b32_e32 v63, v64
	v_cvt_f32_f16_e32 v64, v92
	v_max_f32_e32 v90, 0xc1f00000, v90
	v_mul_f32_e32 v90, 0xbfb8aa3b, v90
	v_exp_f32_e32 v90, v90
	v_max_f32_e32 v64, 0xc1f00000, v64
	v_mul_f32_e32 v64, 0xbfb8aa3b, v64
	v_exp_f32_e32 v64, v64
	v_pk_mul_f32 v[62:63], v[62:63], v[100:101]
	s_nop 0
	v_cvt_pk_f16_f32 v63, v62, v63
	v_add_f32_e32 v62, 1.0, v90
	v_rcp_f32_e32 v90, v62
	v_add_f32_e32 v62, 1.0, v64
	v_rcp_f32_e32 v91, v62
	v_pk_mov_b32 v[64:65], v[64:65], v[58:59] op_sel:[1,0]
	v_cvt_f32_f16_sdwa v58, v92 dst_sel:DWORD dst_unused:UNUSED_PAD src0_sel:WORD_1
	v_pack_b32_f16 v62, v102, v63
	v_pk_mul_f32 v[64:65], v[64:65], v[90:91]
	v_cvt_f32_f16_sdwa v91, v93 dst_sel:DWORD dst_unused:UNUSED_PAD src0_sel:WORD_1
	v_cvt_pk_f16_f32 v90, v64, v65
	v_cvt_f32_f16_e32 v64, v93
	v_max_f32_e32 v58, 0xc1f00000, v58
	v_mul_f32_e32 v58, 0xbfb8aa3b, v58
	v_exp_f32_e32 v58, v58
	v_max_f32_e32 v64, 0xc1f00000, v64
	v_mul_f32_e32 v64, 0xbfb8aa3b, v64
	v_exp_f32_e32 v65, v64
	v_add_f32_e32 v58, 1.0, v58
	v_rcp_f32_e32 v64, v58
	v_alignbit_b32 v63, v90, v63, 16
	v_add_f32_e32 v58, 1.0, v65
	v_rcp_f32_e32 v65, v58
	v_mov_b32_e32 v58, v59
	v_mov_b32_e32 v59, v60
	v_cvt_f32_f16_e32 v60, v94
	v_pk_mul_f32 v[58:59], v[58:59], v[64:65]
	s_nop 0
	v_cvt_pk_f16_f32 v58, v58, v59
	v_max_f32_e32 v59, 0xc1f00000, v91
	v_mul_f32_e32 v59, 0xbfb8aa3b, v59
	v_exp_f32_e32 v59, v59
	v_alignbit_b32 v64, v58, v90, 16
	v_lshrrev_b32_e32 v65, 16, v58
	v_add_f32_e32 v58, 1.0, v59
	v_rcp_f32_e32 v58, v58
	v_max_f32_e32 v59, 0xc1f00000, v60
	v_mul_f32_e32 v59, 0xbfb8aa3b, v59
	v_exp_f32_e32 v59, v59
	v_fma_mixhi_f16 v65, v61, v58, 0
	v_cvt_f32_f16_sdwa v58, v94 dst_sel:DWORD dst_unused:UNUSED_PAD src0_sel:WORD_1
	v_cvt_f32_f16_e32 v60, v95
	v_add_f32_e32 v59, 1.0, v59
	v_rcp_f32_e32 v59, v59
	v_max_f32_e32 v58, 0xc1f00000, v58
	v_mul_f32_e32 v58, 0xbfb8aa3b, v58
	v_max_f32_e32 v60, 0xc1f00000, v60
	v_exp_f32_e32 v58, v58
	v_mul_f32_e32 v60, 0xbfb8aa3b, v60
	v_exp_f32_e32 v60, v60
	v_fma_mixlo_f16 v61, v54, v59, 0
	v_add_f32_e32 v54, 1.0, v58
	v_rcp_f32_e32 v58, v54
	v_add_f32_e32 v54, 1.0, v60
	v_rcp_f32_e32 v59, v54
	v_cvt_f32_f16_sdwa v60, v95 dst_sel:DWORD dst_unused:UNUSED_PAD src0_sel:WORD_1
	v_mov_b32_e32 v54, v55
	v_mov_b32_e32 v55, v56
	v_cvt_f32_f16_e32 v56, v96
	v_max_f32_e32 v60, 0xc1f00000, v60
	v_mul_f32_e32 v60, 0xbfb8aa3b, v60
	v_exp_f32_e32 v60, v60
	v_max_f32_e32 v56, 0xc1f00000, v56
	v_mul_f32_e32 v56, 0xbfb8aa3b, v56
	v_exp_f32_e32 v56, v56
	v_pk_mul_f32 v[54:55], v[54:55], v[58:59]
	v_add_f32_e32 v58, 1.0, v60
	v_rcp_f32_e32 v58, v58
	v_add_f32_e32 v56, 1.0, v56
	v_rcp_f32_e32 v59, v56
	v_pk_mov_b32 v[56:57], v[56:57], v[50:51] op_sel:[1,0]
	v_cvt_f32_f16_sdwa v50, v96 dst_sel:DWORD dst_unused:UNUSED_PAD src0_sel:WORD_1
	v_cvt_pk_f16_f32 v55, v54, v55
	v_pk_mul_f32 v[56:57], v[56:57], v[58:59]
	v_cvt_f32_f16_sdwa v59, v97 dst_sel:DWORD dst_unused:UNUSED_PAD src0_sel:WORD_1
	v_cvt_pk_f16_f32 v58, v56, v57
	v_cvt_f32_f16_e32 v56, v97
	v_max_f32_e32 v50, 0xc1f00000, v50
	v_mul_f32_e32 v50, 0xbfb8aa3b, v50
	v_exp_f32_e32 v50, v50
	v_max_f32_e32 v56, 0xc1f00000, v56
	v_mul_f32_e32 v56, 0xbfb8aa3b, v56
	v_exp_f32_e32 v57, v56
	v_add_f32_e32 v50, 1.0, v50
	v_rcp_f32_e32 v56, v50
	v_pack_b32_f16 v54, v61, v55
	v_add_f32_e32 v50, 1.0, v57
	v_rcp_f32_e32 v57, v50
	v_mov_b32_e32 v50, v51
	v_max_f32_e32 v51, 0xc1f00000, v59
	v_mul_f32_e32 v51, 0xbfb8aa3b, v51
	v_exp_f32_e32 v59, v51
	v_mov_b32_e32 v51, v52
	v_pk_mul_f32 v[50:51], v[50:51], v[56:57]
	v_cvt_f32_f16_e32 v52, v86
	v_cvt_pk_f16_f32 v50, v50, v51
	v_add_f32_e32 v51, 1.0, v59
	v_rcp_f32_e32 v51, v51
	v_alignbit_b32 v56, v50, v58, 16
	v_lshrrev_b32_e32 v57, 16, v50
	v_max_f32_e32 v50, 0xc1f00000, v52
	v_alignbit_b32 v55, v58, v55, 16
	v_fma_mixhi_f16 v57, v53, v51, 0
	v_mul_f32_e32 v50, 0xbfb8aa3b, v50
	v_cvt_f32_f16_sdwa v53, v86 dst_sel:DWORD dst_unused:UNUSED_PAD src0_sel:WORD_1
	v_exp_f32_e32 v52, v50
	global_store_dwordx4 v[98:99], v[54:57], off offset:256
	v_lshl_add_u64 v[50:51], v[192:193], 0, v[182:183]
	v_max_f32_e32 v53, 0xc1f00000, v53
	v_cvt_f32_f16_e32 v54, v87
	v_add_f32_e32 v52, 1.0, v52
	v_mul_f32_e32 v53, 0xbfb8aa3b, v53
	v_rcp_f32_e32 v52, v52
	v_max_f32_e32 v54, 0xc1f00000, v54
	v_exp_f32_e32 v53, v53
	v_mul_f32_e32 v54, 0xbfb8aa3b, v54
	v_exp_f32_e32 v54, v54
	v_fma_mixlo_f16 v55, v46, v52, 0
	v_add_f32_e32 v46, 1.0, v53
	v_rcp_f32_e32 v52, v46
	v_add_f32_e32 v46, 1.0, v54
	v_rcp_f32_e32 v53, v46
	v_cvt_f32_f16_sdwa v54, v87 dst_sel:DWORD dst_unused:UNUSED_PAD src0_sel:WORD_1
	v_mov_b32_e32 v46, v47
	v_mov_b32_e32 v47, v48
	v_cvt_f32_f16_e32 v48, v88
	v_pk_mul_f32 v[46:47], v[46:47], v[52:53]
	v_max_f32_e32 v52, 0xc1f00000, v54
	v_mul_f32_e32 v52, 0xbfb8aa3b, v52
	v_max_f32_e32 v48, 0xc1f00000, v48
	v_exp_f32_e32 v52, v52
	v_mul_f32_e32 v48, 0xbfb8aa3b, v48
	v_exp_f32_e32 v48, v48
	v_cvt_pk_f16_f32 v47, v46, v47
	v_add_f32_e32 v46, 1.0, v52
	v_rcp_f32_e32 v52, v46
	v_add_f32_e32 v46, 1.0, v48
	v_rcp_f32_e32 v53, v46
	v_pk_mov_b32 v[48:49], v[48:49], v[42:43] op_sel:[1,0]
	v_cvt_f32_f16_sdwa v42, v88 dst_sel:DWORD dst_unused:UNUSED_PAD src0_sel:WORD_1
	v_pack_b32_f16 v46, v55, v47
	v_pk_mul_f32 v[48:49], v[48:49], v[52:53]
	v_cvt_f32_f16_sdwa v53, v89 dst_sel:DWORD dst_unused:UNUSED_PAD src0_sel:WORD_1
	v_cvt_pk_f16_f32 v52, v48, v49
	v_cvt_f32_f16_e32 v48, v89
	v_max_f32_e32 v42, 0xc1f00000, v42
	v_mul_f32_e32 v42, 0xbfb8aa3b, v42
	v_exp_f32_e32 v42, v42
	v_max_f32_e32 v48, 0xc1f00000, v48
	v_mul_f32_e32 v48, 0xbfb8aa3b, v48
	v_exp_f32_e32 v49, v48
	v_add_f32_e32 v42, 1.0, v42
	v_rcp_f32_e32 v48, v42
	v_alignbit_b32 v47, v52, v47, 16
	v_add_f32_e32 v42, 1.0, v49
	v_rcp_f32_e32 v49, v42
	v_mov_b32_e32 v42, v43
	v_mov_b32_e32 v43, v44
	v_cvt_f32_f16_e32 v44, v82
	v_pk_mul_f32 v[42:43], v[42:43], v[48:49]
	global_store_dwordx4 v[98:99], v[62:65], off
	v_cvt_pk_f16_f32 v42, v42, v43
	v_max_f32_e32 v43, 0xc1f00000, v53
	v_mul_f32_e32 v43, 0xbfb8aa3b, v43
	v_exp_f32_e32 v43, v43
	v_alignbit_b32 v48, v42, v52, 16
	v_lshrrev_b32_e32 v49, 16, v42
	v_add_f32_e32 v42, 1.0, v43
	v_rcp_f32_e32 v42, v42
	v_max_f32_e32 v43, 0xc1f00000, v44
	v_mul_f32_e32 v43, 0xbfb8aa3b, v43
	v_exp_f32_e32 v43, v43
	v_fma_mixhi_f16 v49, v45, v42, 0
	v_cvt_f32_f16_sdwa v42, v82 dst_sel:DWORD dst_unused:UNUSED_PAD src0_sel:WORD_1
	v_cvt_f32_f16_e32 v44, v83
	v_add_f32_e32 v43, 1.0, v43
	v_rcp_f32_e32 v43, v43
	v_max_f32_e32 v42, 0xc1f00000, v42
	v_mul_f32_e32 v42, 0xbfb8aa3b, v42
	v_max_f32_e32 v44, 0xc1f00000, v44
	v_exp_f32_e32 v42, v42
	v_mul_f32_e32 v44, 0xbfb8aa3b, v44
	v_exp_f32_e32 v44, v44
	v_fma_mixlo_f16 v45, v38, v43, 0
	v_add_f32_e32 v38, 1.0, v42
	v_rcp_f32_e32 v42, v38
	v_add_f32_e32 v38, 1.0, v44
	v_rcp_f32_e32 v43, v38
	v_cvt_f32_f16_sdwa v44, v83 dst_sel:DWORD dst_unused:UNUSED_PAD src0_sel:WORD_1
	v_mov_b32_e32 v38, v39
	v_mov_b32_e32 v39, v40
	v_cvt_f32_f16_e32 v40, v84
	v_max_f32_e32 v44, 0xc1f00000, v44
	v_mul_f32_e32 v44, 0xbfb8aa3b, v44
	v_exp_f32_e32 v44, v44
	v_max_f32_e32 v40, 0xc1f00000, v40
	v_mul_f32_e32 v40, 0xbfb8aa3b, v40
	v_exp_f32_e32 v40, v40
	v_pk_mul_f32 v[38:39], v[38:39], v[42:43]
	v_add_f32_e32 v42, 1.0, v44
	v_rcp_f32_e32 v42, v42
	v_add_f32_e32 v40, 1.0, v40
	v_rcp_f32_e32 v43, v40
	v_pk_mov_b32 v[40:41], v[40:41], v[34:35] op_sel:[1,0]
	v_cvt_f32_f16_sdwa v34, v84 dst_sel:DWORD dst_unused:UNUSED_PAD src0_sel:WORD_1
	v_cvt_pk_f16_f32 v39, v38, v39
	v_pk_mul_f32 v[40:41], v[40:41], v[42:43]
	v_cvt_f32_f16_sdwa v43, v85 dst_sel:DWORD dst_unused:UNUSED_PAD src0_sel:WORD_1
	v_cvt_pk_f16_f32 v42, v40, v41
	v_cvt_f32_f16_e32 v40, v85
	v_max_f32_e32 v34, 0xc1f00000, v34
	v_mul_f32_e32 v34, 0xbfb8aa3b, v34
	v_exp_f32_e32 v34, v34
	v_max_f32_e32 v40, 0xc1f00000, v40
	v_mul_f32_e32 v40, 0xbfb8aa3b, v40
	v_exp_f32_e32 v41, v40
	v_add_f32_e32 v34, 1.0, v34
	v_rcp_f32_e32 v40, v34
	v_pack_b32_f16 v38, v45, v39
	v_add_f32_e32 v34, 1.0, v41
	v_rcp_f32_e32 v41, v34
	v_mov_b32_e32 v34, v35
	v_max_f32_e32 v35, 0xc1f00000, v43
	v_mul_f32_e32 v35, 0xbfb8aa3b, v35
	v_exp_f32_e32 v43, v35
	v_mov_b32_e32 v35, v36
	v_pk_mul_f32 v[34:35], v[34:35], v[40:41]
	v_cvt_f32_f16_e32 v36, v78
	v_cvt_pk_f16_f32 v34, v34, v35
	v_add_f32_e32 v35, 1.0, v43
	v_rcp_f32_e32 v35, v35
	v_alignbit_b32 v40, v34, v42, 16
	v_lshrrev_b32_e32 v41, 16, v34
	v_max_f32_e32 v34, 0xc1f00000, v36
	v_alignbit_b32 v39, v42, v39, 16
	v_fma_mixhi_f16 v41, v37, v35, 0
	v_mul_f32_e32 v34, 0xbfb8aa3b, v34
	v_cvt_f32_f16_sdwa v37, v78 dst_sel:DWORD dst_unused:UNUSED_PAD src0_sel:WORD_1
	v_exp_f32_e32 v36, v34
	global_store_dwordx4 v[50:51], v[38:41], off offset:256
	v_lshl_add_u64 v[34:35], v[192:193], 0, v[184:185]
	v_max_f32_e32 v37, 0xc1f00000, v37
	v_cvt_f32_f16_e32 v38, v79
	v_add_f32_e32 v36, 1.0, v36
	v_mul_f32_e32 v37, 0xbfb8aa3b, v37
	v_rcp_f32_e32 v36, v36
	v_max_f32_e32 v38, 0xc1f00000, v38
	v_exp_f32_e32 v37, v37
	v_mul_f32_e32 v38, 0xbfb8aa3b, v38
	v_exp_f32_e32 v38, v38
	v_fma_mixlo_f16 v39, v28, v36, 0
	v_add_f32_e32 v28, 1.0, v37
	v_rcp_f32_e32 v36, v28
	v_add_f32_e32 v28, 1.0, v38
	v_rcp_f32_e32 v37, v28
	v_cvt_f32_f16_sdwa v38, v79 dst_sel:DWORD dst_unused:UNUSED_PAD src0_sel:WORD_1
	v_mov_b32_e32 v28, v29
	v_mov_b32_e32 v29, v30
	v_cvt_f32_f16_e32 v30, v80
	v_pk_mul_f32 v[28:29], v[28:29], v[36:37]
	v_max_f32_e32 v36, 0xc1f00000, v38
	v_mul_f32_e32 v36, 0xbfb8aa3b, v36
	v_max_f32_e32 v30, 0xc1f00000, v30
	v_exp_f32_e32 v36, v36
	v_mul_f32_e32 v30, 0xbfb8aa3b, v30
	v_exp_f32_e32 v30, v30
	v_cvt_pk_f16_f32 v29, v28, v29
	v_add_f32_e32 v28, 1.0, v36
	v_rcp_f32_e32 v36, v28
	v_add_f32_e32 v28, 1.0, v30
	v_rcp_f32_e32 v37, v28
	v_pk_mov_b32 v[30:31], v[30:31], v[24:25] op_sel:[1,0]
	v_cvt_f32_f16_sdwa v24, v80 dst_sel:DWORD dst_unused:UNUSED_PAD src0_sel:WORD_1
	v_pack_b32_f16 v28, v39, v29
	v_pk_mul_f32 v[30:31], v[30:31], v[36:37]
	v_cvt_f32_f16_sdwa v37, v81 dst_sel:DWORD dst_unused:UNUSED_PAD src0_sel:WORD_1
	v_cvt_pk_f16_f32 v36, v30, v31
	v_cvt_f32_f16_e32 v30, v81
	v_max_f32_e32 v24, 0xc1f00000, v24
	v_mul_f32_e32 v24, 0xbfb8aa3b, v24
	v_exp_f32_e32 v24, v24
	v_max_f32_e32 v30, 0xc1f00000, v30
	v_mul_f32_e32 v30, 0xbfb8aa3b, v30
	v_exp_f32_e32 v31, v30
	v_add_f32_e32 v24, 1.0, v24
	v_rcp_f32_e32 v30, v24
	v_alignbit_b32 v29, v36, v29, 16
	v_add_f32_e32 v24, 1.0, v31
	v_rcp_f32_e32 v31, v24
	v_mov_b32_e32 v24, v25
	v_mov_b32_e32 v25, v26
	v_cvt_f32_f16_e32 v26, v74
	v_pk_mul_f32 v[24:25], v[24:25], v[30:31]
	global_store_dwordx4 v[50:51], v[46:49], off
	v_cvt_pk_f16_f32 v24, v24, v25
	v_max_f32_e32 v25, 0xc1f00000, v37
	v_mul_f32_e32 v25, 0xbfb8aa3b, v25
	v_exp_f32_e32 v25, v25
	v_alignbit_b32 v30, v24, v36, 16
	v_lshrrev_b32_e32 v31, 16, v24
	v_add_f32_e32 v24, 1.0, v25
	v_rcp_f32_e32 v24, v24
	v_max_f32_e32 v25, 0xc1f00000, v26
	v_mul_f32_e32 v25, 0xbfb8aa3b, v25
	v_exp_f32_e32 v25, v25
	v_fma_mixhi_f16 v31, v27, v24, 0
	v_cvt_f32_f16_sdwa v24, v74 dst_sel:DWORD dst_unused:UNUSED_PAD src0_sel:WORD_1
	v_cvt_f32_f16_e32 v26, v75
	v_add_f32_e32 v25, 1.0, v25
	v_rcp_f32_e32 v25, v25
	v_max_f32_e32 v24, 0xc1f00000, v24
	v_mul_f32_e32 v24, 0xbfb8aa3b, v24
	v_max_f32_e32 v26, 0xc1f00000, v26
	v_exp_f32_e32 v24, v24
	v_mul_f32_e32 v26, 0xbfb8aa3b, v26
	v_exp_f32_e32 v26, v26
	v_fma_mixlo_f16 v27, v20, v25, 0
	v_add_f32_e32 v20, 1.0, v24
	v_rcp_f32_e32 v24, v20
	v_add_f32_e32 v20, 1.0, v26
	v_rcp_f32_e32 v25, v20
	v_cvt_f32_f16_sdwa v26, v75 dst_sel:DWORD dst_unused:UNUSED_PAD src0_sel:WORD_1
	v_mov_b32_e32 v20, v21
	v_mov_b32_e32 v21, v22
	v_cvt_f32_f16_e32 v22, v76
	v_max_f32_e32 v26, 0xc1f00000, v26
	v_mul_f32_e32 v26, 0xbfb8aa3b, v26
	v_exp_f32_e32 v26, v26
	v_max_f32_e32 v22, 0xc1f00000, v22
	v_mul_f32_e32 v22, 0xbfb8aa3b, v22
	v_exp_f32_e32 v22, v22
	v_pk_mul_f32 v[20:21], v[20:21], v[24:25]
	v_add_f32_e32 v24, 1.0, v26
	v_rcp_f32_e32 v24, v24
	v_add_f32_e32 v22, 1.0, v22
	v_rcp_f32_e32 v25, v22
	v_pk_mov_b32 v[22:23], v[22:23], v[16:17] op_sel:[1,0]
	v_cvt_f32_f16_sdwa v16, v76 dst_sel:DWORD dst_unused:UNUSED_PAD src0_sel:WORD_1
	v_cvt_pk_f16_f32 v21, v20, v21
	v_pk_mul_f32 v[22:23], v[22:23], v[24:25]
	v_cvt_f32_f16_sdwa v25, v77 dst_sel:DWORD dst_unused:UNUSED_PAD src0_sel:WORD_1
	v_cvt_pk_f16_f32 v24, v22, v23
	v_cvt_f32_f16_e32 v22, v77
	v_max_f32_e32 v16, 0xc1f00000, v16
	v_mul_f32_e32 v16, 0xbfb8aa3b, v16
	v_exp_f32_e32 v16, v16
	v_max_f32_e32 v22, 0xc1f00000, v22
	v_mul_f32_e32 v22, 0xbfb8aa3b, v22
	v_exp_f32_e32 v23, v22
	v_add_f32_e32 v16, 1.0, v16
	v_rcp_f32_e32 v22, v16
	v_pack_b32_f16 v20, v27, v21
	v_add_f32_e32 v16, 1.0, v23
	v_rcp_f32_e32 v23, v16
	v_mov_b32_e32 v16, v17
	v_max_f32_e32 v17, 0xc1f00000, v25
	v_mul_f32_e32 v17, 0xbfb8aa3b, v17
	v_exp_f32_e32 v25, v17
	v_mov_b32_e32 v17, v18
	v_pk_mul_f32 v[16:17], v[16:17], v[22:23]
	v_cvt_f32_f16_e32 v18, v70
	v_cvt_pk_f16_f32 v16, v16, v17
	v_add_f32_e32 v17, 1.0, v25
	v_rcp_f32_e32 v17, v17
	v_alignbit_b32 v22, v16, v24, 16
	v_lshrrev_b32_e32 v23, 16, v16
	v_max_f32_e32 v16, 0xc1f00000, v18
	v_alignbit_b32 v21, v24, v21, 16
	v_fma_mixhi_f16 v23, v19, v17, 0
	v_mul_f32_e32 v16, 0xbfb8aa3b, v16
	v_cvt_f32_f16_sdwa v19, v70 dst_sel:DWORD dst_unused:UNUSED_PAD src0_sel:WORD_1
	v_exp_f32_e32 v18, v16
	global_store_dwordx4 v[34:35], v[20:23], off offset:256
	v_lshl_add_u64 v[16:17], v[192:193], 0, v[186:187]
	v_max_f32_e32 v19, 0xc1f00000, v19
	v_cvt_f32_f16_e32 v20, v71
	v_add_f32_e32 v18, 1.0, v18
	v_mul_f32_e32 v19, 0xbfb8aa3b, v19
	v_rcp_f32_e32 v18, v18
	v_max_f32_e32 v20, 0xc1f00000, v20
	v_exp_f32_e32 v19, v19
	v_mul_f32_e32 v20, 0xbfb8aa3b, v20
	v_exp_f32_e32 v20, v20
	v_fma_mixlo_f16 v21, v12, v18, 0
	v_add_f32_e32 v12, 1.0, v19
	v_rcp_f32_e32 v18, v12
	v_add_f32_e32 v12, 1.0, v20
	v_rcp_f32_e32 v19, v12
	v_cvt_f32_f16_sdwa v20, v71 dst_sel:DWORD dst_unused:UNUSED_PAD src0_sel:WORD_1
	v_mov_b32_e32 v12, v13
	v_mov_b32_e32 v13, v14
	v_cvt_f32_f16_e32 v14, v72
	v_pk_mul_f32 v[12:13], v[12:13], v[18:19]
	v_max_f32_e32 v18, 0xc1f00000, v20
	v_mul_f32_e32 v18, 0xbfb8aa3b, v18
	v_max_f32_e32 v14, 0xc1f00000, v14
	v_exp_f32_e32 v18, v18
	v_mul_f32_e32 v14, 0xbfb8aa3b, v14
	v_exp_f32_e32 v14, v14
	v_cvt_pk_f16_f32 v13, v12, v13
	v_add_f32_e32 v12, 1.0, v18
	v_rcp_f32_e32 v18, v12
	v_add_f32_e32 v12, 1.0, v14
	v_rcp_f32_e32 v19, v12
	v_pk_mov_b32 v[14:15], v[14:15], v[8:9] op_sel:[1,0]
	v_cvt_f32_f16_sdwa v8, v72 dst_sel:DWORD dst_unused:UNUSED_PAD src0_sel:WORD_1
	v_pack_b32_f16 v12, v21, v13
	v_pk_mul_f32 v[14:15], v[14:15], v[18:19]
	v_cvt_f32_f16_sdwa v19, v73 dst_sel:DWORD dst_unused:UNUSED_PAD src0_sel:WORD_1
	v_cvt_pk_f16_f32 v18, v14, v15
	v_cvt_f32_f16_e32 v14, v73
	v_max_f32_e32 v8, 0xc1f00000, v8
	v_mul_f32_e32 v8, 0xbfb8aa3b, v8
	v_exp_f32_e32 v8, v8
	v_max_f32_e32 v14, 0xc1f00000, v14
	v_mul_f32_e32 v14, 0xbfb8aa3b, v14
	v_exp_f32_e32 v15, v14
	v_add_f32_e32 v8, 1.0, v8
	v_rcp_f32_e32 v14, v8
	v_alignbit_b32 v13, v18, v13, 16
	v_add_f32_e32 v8, 1.0, v15
	v_rcp_f32_e32 v15, v8
	v_mov_b32_e32 v8, v9
	v_mov_b32_e32 v9, v10
	v_cvt_f32_f16_e32 v10, v66
	v_pk_mul_f32 v[8:9], v[8:9], v[14:15]
	global_store_dwordx4 v[34:35], v[28:31], off
	v_cvt_pk_f16_f32 v8, v8, v9
	v_max_f32_e32 v9, 0xc1f00000, v19
	v_mul_f32_e32 v9, 0xbfb8aa3b, v9
	v_exp_f32_e32 v9, v9
	v_alignbit_b32 v14, v8, v18, 16
	v_lshrrev_b32_e32 v15, 16, v8
	v_add_f32_e32 v8, 1.0, v9
	v_rcp_f32_e32 v8, v8
	v_max_f32_e32 v9, 0xc1f00000, v10
	v_mul_f32_e32 v9, 0xbfb8aa3b, v9
	v_exp_f32_e32 v9, v9
	v_fma_mixhi_f16 v15, v11, v8, 0
	v_cvt_f32_f16_sdwa v8, v66 dst_sel:DWORD dst_unused:UNUSED_PAD src0_sel:WORD_1
	v_cvt_f32_f16_e32 v10, v67
	v_add_f32_e32 v9, 1.0, v9
	v_rcp_f32_e32 v9, v9
	v_max_f32_e32 v8, 0xc1f00000, v8
	v_mul_f32_e32 v8, 0xbfb8aa3b, v8
	v_max_f32_e32 v10, 0xc1f00000, v10
	v_exp_f32_e32 v8, v8
	v_mul_f32_e32 v10, 0xbfb8aa3b, v10
	v_exp_f32_e32 v10, v10
	v_fma_mixlo_f16 v11, v4, v9, 0
	v_add_f32_e32 v4, 1.0, v8
	v_rcp_f32_e32 v8, v4
	v_add_f32_e32 v4, 1.0, v10
	v_rcp_f32_e32 v9, v4
	v_cvt_f32_f16_sdwa v10, v67 dst_sel:DWORD dst_unused:UNUSED_PAD src0_sel:WORD_1
	v_mov_b32_e32 v4, v5
	v_mov_b32_e32 v5, v6
	v_cvt_f32_f16_e32 v6, v68
	v_max_f32_e32 v10, 0xc1f00000, v10
	v_mul_f32_e32 v10, 0xbfb8aa3b, v10
	v_exp_f32_e32 v10, v10
	v_max_f32_e32 v6, 0xc1f00000, v6
	v_mul_f32_e32 v6, 0xbfb8aa3b, v6
	v_exp_f32_e32 v6, v6
	v_pk_mul_f32 v[4:5], v[4:5], v[8:9]
	v_add_f32_e32 v8, 1.0, v10
	v_rcp_f32_e32 v8, v8
	v_add_f32_e32 v6, 1.0, v6
	v_rcp_f32_e32 v9, v6
	v_pk_mov_b32 v[6:7], v[6:7], v[0:1] op_sel:[1,0]
	v_cvt_f32_f16_sdwa v0, v68 dst_sel:DWORD dst_unused:UNUSED_PAD src0_sel:WORD_1
	v_cvt_pk_f16_f32 v5, v4, v5
	v_pk_mul_f32 v[6:7], v[6:7], v[8:9]
	v_cvt_f32_f16_sdwa v9, v69 dst_sel:DWORD dst_unused:UNUSED_PAD src0_sel:WORD_1
	v_cvt_pk_f16_f32 v8, v6, v7
	v_cvt_f32_f16_e32 v6, v69
	v_max_f32_e32 v0, 0xc1f00000, v0
	v_mul_f32_e32 v0, 0xbfb8aa3b, v0
	v_exp_f32_e32 v0, v0
	v_max_f32_e32 v6, 0xc1f00000, v6
	v_mul_f32_e32 v6, 0xbfb8aa3b, v6
	v_exp_f32_e32 v7, v6
	v_add_f32_e32 v0, 1.0, v0
	v_rcp_f32_e32 v6, v0
	v_pack_b32_f16 v4, v11, v5
	v_add_f32_e32 v0, 1.0, v7
	v_rcp_f32_e32 v7, v0
	v_max_f32_e32 v0, 0xc1f00000, v9
	v_mul_f32_e32 v0, 0xbfb8aa3b, v0
	v_exp_f32_e32 v9, v0
	v_mov_b32_e32 v0, v1
	v_mov_b32_e32 v1, v2
	v_pk_mul_f32 v[0:1], v[0:1], v[6:7]
	v_add_f32_e32 v2, 1.0, v9
	v_rcp_f32_e32 v2, v2
	v_cvt_pk_f16_f32 v0, v0, v1
	v_lshrrev_b32_e32 v7, 16, v0
	v_alignbit_b32 v5, v8, v5, 16
	v_alignbit_b32 v6, v0, v8, 16
	v_fma_mixhi_f16 v7, v3, v2, 0
	global_store_dwordx4 v[16:17], v[12:15], off
	global_store_dwordx4 v[16:17], v[4:7], off offset:256
	s_and_b64 vcc, exec, s[4:5]
	s_mov_b32 s31, s30
	s_mov_b32 s34, s29
	s_mov_b64 s[12:13], s[0:1]
	s_mov_b64 s[10:11], s[2:3]
	s_cbranch_vccz .LBB0_955
	s_waitcnt vmcnt(0)
	s_cmpk_gt_u32 s19, 0xff
	s_cbranch_scc1 .LBB0_962
	s_barrier

.LBB0_1117:
	s_add_i32 s41, s22, 2
	s_add_u32 s20, s14, 0x100
	s_addc_u32 s21, s15, 0
	s_add_i32 s42, 0, 0x10000
	s_waitcnt vmcnt(0)
	v_add_u32_e32 v102, s42, v230
	ds_read_b128 v[78:81], v102
	ds_read_b128 v[94:97], v102 offset:2048
	ds_read_b128 v[86:89], v102 offset:1024
	ds_read_b128 v[102:105], v102 offset:3072
	s_cmp_eq_u32 s38, s22
	s_cselect_b32 s22, s18, s39
	s_cselect_b32 s25, s17, s21
	s_cselect_b32 s24, s16, s20
	s_cselect_b32 s23, s19, s40
	v_lshl_add_u64 v[178:179], s[14:15], 0, v[200:201]
	s_add_i32 m0, s28, 0xc000
	ds_read_b128 v[122:125], v232
	ds_read_b128 v[130:133], v232 offset:2048
	ds_read_b128 v[154:157], v232 offset:4096
	ds_read_b128 v[170:173], v232 offset:6144
	ds_read_b128 v[126:129], v232 offset:1024
	ds_read_b128 v[134:137], v232 offset:3072
	ds_read_b128 v[158:161], v232 offset:5120
	ds_read_b128 v[174:177], v232 offset:7168
	global_load_lds_dwordx4 v[178:179], off
	v_lshl_add_u64 v[178:179], s[14:15], 0, v[202:203]
	s_add_i32 m0, s28, 0xe000
	s_nop 0
	global_load_lds_dwordx4 v[178:179], off
	s_waitcnt lgkmcnt(8)
	s_barrier
	s_waitcnt lgkmcnt(7)
	s_setprio 1
	v_mfma_f32_16x16x32_f16 v[166:169], v[78:81], v[122:125], v[166:169]
	v_mfma_f32_16x16x32_f16 v[162:165], v[94:97], v[122:125], v[162:165]
	s_waitcnt lgkmcnt(6)
	v_mfma_f32_16x16x32_f16 v[150:153], v[78:81], v[130:133], v[150:153]
	v_mfma_f32_16x16x32_f16 v[142:145], v[94:97], v[130:133], v[142:145]
	s_waitcnt lgkmcnt(5)
	v_mfma_f32_16x16x32_f16 v[110:113], v[78:81], v[154:157], v[110:113]
	v_mfma_f32_16x16x32_f16 v[106:109], v[94:97], v[154:157], v[106:109]
	s_waitcnt lgkmcnt(4)
	v_mfma_f32_16x16x32_f16 v[82:85], v[78:81], v[170:173], v[82:85]
	v_mfma_f32_16x16x32_f16 v[74:77], v[94:97], v[170:173], v[74:77]
	s_waitcnt lgkmcnt(3)
	v_mfma_f32_16x16x32_f16 v[166:169], v[86:89], v[126:129], v[166:169]
	v_mfma_f32_16x16x32_f16 v[162:165], v[102:105], v[126:129], v[162:165]
	s_waitcnt lgkmcnt(2)
	v_mfma_f32_16x16x32_f16 v[150:153], v[86:89], v[134:137], v[150:153]
	v_mfma_f32_16x16x32_f16 v[142:145], v[102:105], v[134:137], v[142:145]
	s_waitcnt lgkmcnt(1)
	v_mfma_f32_16x16x32_f16 v[110:113], v[86:89], v[158:161], v[110:113]
	v_mfma_f32_16x16x32_f16 v[106:109], v[102:105], v[158:161], v[106:109]
	s_waitcnt lgkmcnt(0)
	v_mfma_f32_16x16x32_f16 v[82:85], v[86:89], v[174:177], v[82:85]
	v_mfma_f32_16x16x32_f16 v[74:77], v[102:105], v[174:177], v[74:77]
	s_setprio 0
	s_barrier
	s_add_i32 s43, 0, 0x14000
	s_add_i32 s14, s42, s13
	v_add_u32_e32 v190, s43, v230
	v_lshl_add_u64 v[204:205], s[22:23], 0, v[32:33]
	s_mov_b32 m0, s14
	ds_read_b128 v[178:181], v190
	ds_read_b128 v[186:189], v190 offset:2048
	ds_read_b128 v[182:185], v190 offset:1024
	ds_read_b128 v[190:193], v190 offset:3072
	global_load_lds_dwordx4 v[204:205], off
	v_lshl_add_u64 v[206:207], s[22:23], 0, v[198:199]
	s_add_i32 m0, s14, 0x2000
	s_nop 0
	global_load_lds_dwordx4 v[206:207], off
	s_barrier
	s_waitcnt lgkmcnt(3)
	s_setprio 1
	v_mfma_f32_16x16x32_f16 v[146:149], v[178:181], v[122:125], v[146:149]
	v_mfma_f32_16x16x32_f16 v[118:121], v[178:181], v[130:133], v[118:121]
	s_waitcnt lgkmcnt(2)
	v_mfma_f32_16x16x32_f16 v[114:117], v[186:189], v[130:133], v[114:117]
	v_mfma_f32_16x16x32_f16 v[98:101], v[178:181], v[154:157], v[98:101]
	v_mfma_f32_16x16x32_f16 v[90:93], v[186:189], v[154:157], v[90:93]
	v_mfma_f32_16x16x32_f16 v[70:73], v[178:181], v[170:173], v[70:73]
	s_waitcnt lgkmcnt(1)
	v_mfma_f32_16x16x32_f16 v[66:69], v[186:189], v[170:173], v[66:69]
	v_mfma_f32_16x16x32_f16 v[146:149], v[182:185], v[126:129], v[146:149]
	v_mfma_f32_16x16x32_f16 v[122:125], v[186:189], v[122:125], v[138:141]
	v_mfma_f32_16x16x32_f16 v[118:121], v[182:185], v[134:137], v[118:121]
	s_waitcnt lgkmcnt(0)
	v_mfma_f32_16x16x32_f16 v[114:117], v[190:193], v[134:137], v[114:117]
	v_mfma_f32_16x16x32_f16 v[98:101], v[182:185], v[158:161], v[98:101]
	v_mfma_f32_16x16x32_f16 v[90:93], v[190:193], v[158:161], v[90:93]
	v_mfma_f32_16x16x32_f16 v[70:73], v[182:185], v[174:177], v[70:73]
	v_mfma_f32_16x16x32_f16 v[66:69], v[190:193], v[174:177], v[66:69]
	v_mfma_f32_16x16x32_f16 v[122:125], v[190:193], v[126:129], v[122:125]
	s_setprio 0
	s_mov_b32 m0, s28
	v_lshl_add_u64 v[208:209], s[24:25], 0, v[32:33]
	s_barrier
	ds_read_b128 v[126:129], v232 offset:16384
	ds_read_b128 v[134:137], v232 offset:18432
	ds_read_b128 v[154:157], v232 offset:20480
	ds_read_b128 v[170:173], v232 offset:22528
	ds_read_b128 v[130:133], v232 offset:17408
	ds_read_b128 v[138:141], v232 offset:19456
	ds_read_b128 v[158:161], v232 offset:21504
	ds_read_b128 v[174:177], v232 offset:23552
	global_load_lds_dwordx4 v[208:209], off
	v_lshl_add_u64 v[210:211], s[24:25], 0, v[198:199]
	s_mov_b32 m0, s29
	s_nop 0
	global_load_lds_dwordx4 v[210:211], off
	s_waitcnt vmcnt(10)
	s_barrier
	s_waitcnt lgkmcnt(7)
	s_setprio 1
	v_mfma_f32_16x16x32_f16 v[62:65], v[78:81], v[126:129], v[62:65]
	v_mfma_f32_16x16x32_f16 v[58:61], v[94:97], v[126:129], v[58:61]
	s_waitcnt lgkmcnt(6)
	v_mfma_f32_16x16x32_f16 v[46:49], v[78:81], v[134:137], v[46:49]
	v_mfma_f32_16x16x32_f16 v[42:45], v[94:97], v[134:137], v[42:45]
	s_waitcnt lgkmcnt(5)
	v_mfma_f32_16x16x32_f16 v[28:31], v[78:81], v[154:157], v[28:31]
	v_mfma_f32_16x16x32_f16 v[24:27], v[94:97], v[154:157], v[24:27]
	s_waitcnt lgkmcnt(4)
	v_mfma_f32_16x16x32_f16 v[12:15], v[78:81], v[170:173], v[12:15]
	v_mfma_f32_16x16x32_f16 v[8:11], v[94:97], v[170:173], v[8:11]
	s_waitcnt lgkmcnt(3)
	v_mfma_f32_16x16x32_f16 v[62:65], v[86:89], v[130:133], v[62:65]
	v_mfma_f32_16x16x32_f16 v[58:61], v[102:105], v[130:133], v[58:61]
	s_waitcnt lgkmcnt(2)
	v_mfma_f32_16x16x32_f16 v[46:49], v[86:89], v[138:141], v[46:49]
	v_mfma_f32_16x16x32_f16 v[42:45], v[102:105], v[138:141], v[42:45]
	s_waitcnt lgkmcnt(1)
	v_mfma_f32_16x16x32_f16 v[28:31], v[86:89], v[158:161], v[28:31]
	v_mfma_f32_16x16x32_f16 v[24:27], v[102:105], v[158:161], v[24:27]
	s_waitcnt lgkmcnt(0)
	v_mfma_f32_16x16x32_f16 v[12:15], v[86:89], v[174:177], v[12:15]
	v_mfma_f32_16x16x32_f16 v[8:11], v[102:105], v[174:177], v[8:11]
	s_setprio 0
	s_barrier
	s_add_u32 s14, s22, 0x40000
	s_addc_u32 s15, s23, 0
	s_add_i32 s42, s43, s13
	v_lshl_add_u64 v[78:79], s[14:15], 0, v[32:33]
	s_mov_b32 m0, s42
	s_nop 0
	global_load_lds_dwordx4 v[78:79], off
	v_lshl_add_u64 v[78:79], s[14:15], 0, v[198:199]
	s_add_i32 m0, s42, 0x2000
	s_nop 0
	global_load_lds_dwordx4 v[78:79], off
	v_add_u32_e32 v102, 0x18000, v230
	ds_read_b128 v[78:81], v102
	ds_read_b128 v[86:89], v102 offset:1024
	ds_read_b128 v[94:97], v102 offset:2048
	ds_read_b128 v[102:105], v102 offset:3072
	s_waitcnt vmcnt(6)
	s_barrier
	s_setprio 1
	v_mfma_f32_16x16x32_f16 v[54:57], v[178:181], v[126:129], v[54:57]
	v_mfma_f32_16x16x32_f16 v[50:53], v[186:189], v[126:129], v[50:53]
	v_mfma_f32_16x16x32_f16 v[38:41], v[178:181], v[134:137], v[38:41]
	v_mfma_f32_16x16x32_f16 v[34:37], v[186:189], v[134:137], v[34:37]
	v_mfma_f32_16x16x32_f16 v[20:23], v[178:181], v[154:157], v[20:23]
	v_mfma_f32_16x16x32_f16 v[16:19], v[186:189], v[154:157], v[16:19]
	v_mfma_f32_16x16x32_f16 v[4:7], v[178:181], v[170:173], v[4:7]
	v_mfma_f32_16x16x32_f16 v[0:3], v[186:189], v[170:173], v[0:3]
	v_mfma_f32_16x16x32_f16 v[54:57], v[182:185], v[130:133], v[54:57]
	v_mfma_f32_16x16x32_f16 v[50:53], v[190:193], v[130:133], v[50:53]
	v_mfma_f32_16x16x32_f16 v[38:41], v[182:185], v[138:141], v[38:41]
	v_mfma_f32_16x16x32_f16 v[34:37], v[190:193], v[138:141], v[34:37]
	v_mfma_f32_16x16x32_f16 v[20:23], v[182:185], v[158:161], v[20:23]
	v_mfma_f32_16x16x32_f16 v[16:19], v[190:193], v[158:161], v[16:19]
	v_mfma_f32_16x16x32_f16 v[4:7], v[182:185], v[174:177], v[4:7]
	v_mfma_f32_16x16x32_f16 v[0:3], v[190:193], v[174:177], v[0:3]
	s_setprio 0
	s_add_i32 s42, 0, 0x18000
	s_barrier
	s_add_u32 s14, s24, 0x40000
	s_addc_u32 s15, s25, 0
	s_mov_b32 m0, s30
	v_lshl_add_u64 v[138:139], s[14:15], 0, v[32:33]
	ds_read_b128 v[126:129], v232 offset:32768
	ds_read_b128 v[130:133], v232 offset:33792
	ds_read_b128 v[134:137], v232 offset:34816
	ds_read_b128 v[154:157], v232 offset:35840
	ds_read_b128 v[158:161], v232 offset:36864
	ds_read_b128 v[174:177], v232 offset:38912
	ds_read_b128 v[170:173], v232 offset:37888
	ds_read_b128 v[178:181], v232 offset:39936
	global_load_lds_dwordx4 v[138:139], off
	v_lshl_add_u64 v[138:139], s[14:15], 0, v[198:199]
	s_mov_b32 m0, s31
	s_nop 0
	global_load_lds_dwordx4 v[138:139], off
	s_waitcnt lgkmcnt(8)
	s_barrier
	s_waitcnt lgkmcnt(6)
	s_setprio 1
	v_mfma_f32_16x16x32_f16 v[138:141], v[78:81], v[126:129], v[166:169]
	v_mfma_f32_16x16x32_f16 v[166:169], v[86:89], v[130:133], v[138:141]
	v_mfma_f32_16x16x32_f16 v[138:141], v[94:97], v[126:129], v[162:165]
	v_mfma_f32_16x16x32_f16 v[162:165], v[102:105], v[130:133], v[138:141]
	s_waitcnt lgkmcnt(4)
	v_mfma_f32_16x16x32_f16 v[138:141], v[78:81], v[134:137], v[150:153]
	v_mfma_f32_16x16x32_f16 v[150:153], v[86:89], v[154:157], v[138:141]
	s_waitcnt lgkmcnt(3)
	v_mfma_f32_16x16x32_f16 v[138:141], v[94:97], v[134:137], v[142:145]
	v_mfma_f32_16x16x32_f16 v[110:113], v[78:81], v[158:161], v[110:113]
	s_waitcnt lgkmcnt(2)
	v_mfma_f32_16x16x32_f16 v[106:109], v[94:97], v[158:161], v[106:109]
	v_mfma_f32_16x16x32_f16 v[82:85], v[78:81], v[174:177], v[82:85]
	v_mfma_f32_16x16x32_f16 v[74:77], v[94:97], v[174:177], v[74:77]
	v_mfma_f32_16x16x32_f16 v[142:145], v[102:105], v[154:157], v[138:141]
	s_waitcnt lgkmcnt(1)
	v_mfma_f32_16x16x32_f16 v[110:113], v[86:89], v[170:173], v[110:113]
	v_mfma_f32_16x16x32_f16 v[106:109], v[102:105], v[170:173], v[106:109]
	s_waitcnt lgkmcnt(0)
	v_mfma_f32_16x16x32_f16 v[82:85], v[86:89], v[178:181], v[82:85]
	v_mfma_f32_16x16x32_f16 v[74:77], v[102:105], v[178:181], v[74:77]
	s_setprio 0
	s_barrier
	s_add_i32 s24, 0, 0x1c000
	v_add_u32_e32 v138, s24, v230
	s_add_i32 s14, s42, s13
	ds_read_b128 v[182:185], v138
	ds_read_b128 v[190:193], v138 offset:2048
	ds_read_b128 v[186:189], v138 offset:1024
	ds_read_b128 v[194:197], v138 offset:3072
	v_lshl_add_u64 v[138:139], v[204:205], 0, s[84:85]
	s_mov_b32 m0, s14
	s_nop 0
	global_load_lds_dwordx4 v[138:139], off
	v_lshl_add_u64 v[138:139], v[206:207], 0, s[84:85]
	s_add_i32 m0, s14, 0x2000
	s_nop 0
	global_load_lds_dwordx4 v[138:139], off
	s_barrier
	s_waitcnt lgkmcnt(2)
	s_setprio 1
	v_mfma_f32_16x16x32_f16 v[138:141], v[182:185], v[126:129], v[146:149]
	v_mfma_f32_16x16x32_f16 v[122:125], v[190:193], v[126:129], v[122:125]
	v_mfma_f32_16x16x32_f16 v[118:121], v[182:185], v[134:137], v[118:121]
	v_mfma_f32_16x16x32_f16 v[114:117], v[190:193], v[134:137], v[114:117]
	v_mfma_f32_16x16x32_f16 v[98:101], v[182:185], v[158:161], v[98:101]
	v_mfma_f32_16x16x32_f16 v[90:93], v[190:193], v[158:161], v[90:93]
	v_mfma_f32_16x16x32_f16 v[70:73], v[182:185], v[174:177], v[70:73]
	v_mfma_f32_16x16x32_f16 v[66:69], v[190:193], v[174:177], v[66:69]
	s_waitcnt lgkmcnt(0)
	v_mfma_f32_16x16x32_f16 v[146:149], v[186:189], v[130:133], v[138:141]
	v_mfma_f32_16x16x32_f16 v[138:141], v[194:197], v[130:133], v[122:125]
	v_mfma_f32_16x16x32_f16 v[118:121], v[186:189], v[154:157], v[118:121]
	v_mfma_f32_16x16x32_f16 v[114:117], v[194:197], v[154:157], v[114:117]
	v_mfma_f32_16x16x32_f16 v[98:101], v[186:189], v[170:173], v[98:101]
	v_mfma_f32_16x16x32_f16 v[90:93], v[194:197], v[170:173], v[90:93]
	v_mfma_f32_16x16x32_f16 v[70:73], v[186:189], v[178:181], v[70:73]
	v_mfma_f32_16x16x32_f16 v[66:69], v[194:197], v[178:181], v[66:69]
	s_setprio 0
	s_mov_b32 m0, s34
	v_lshl_add_u64 v[178:179], v[208:209], 0, s[84:85]
	s_barrier
	ds_read_b128 v[122:125], v232 offset:49152
	ds_read_b128 v[130:133], v232 offset:51200
	ds_read_b128 v[154:157], v232 offset:53248
	ds_read_b128 v[170:173], v232 offset:55296
	ds_read_b128 v[126:129], v232 offset:50176
	ds_read_b128 v[134:137], v232 offset:52224
	ds_read_b128 v[158:161], v232 offset:54272
	ds_read_b128 v[174:177], v232 offset:56320
	global_load_lds_dwordx4 v[178:179], off
	v_lshl_add_u64 v[178:179], v[210:211], 0, s[84:85]
	s_mov_b32 m0, s35
	s_nop 0
	global_load_lds_dwordx4 v[178:179], off
	s_barrier
	s_waitcnt lgkmcnt(7)
	s_setprio 1
	v_mfma_f32_16x16x32_f16 v[62:65], v[78:81], v[122:125], v[62:65]
	v_mfma_f32_16x16x32_f16 v[58:61], v[94:97], v[122:125], v[58:61]
	s_waitcnt lgkmcnt(6)
	v_mfma_f32_16x16x32_f16 v[46:49], v[78:81], v[130:133], v[46:49]
	v_mfma_f32_16x16x32_f16 v[42:45], v[94:97], v[130:133], v[42:45]
	s_waitcnt lgkmcnt(5)
	v_mfma_f32_16x16x32_f16 v[28:31], v[78:81], v[154:157], v[28:31]
	v_mfma_f32_16x16x32_f16 v[24:27], v[94:97], v[154:157], v[24:27]
	s_waitcnt lgkmcnt(4)
	v_mfma_f32_16x16x32_f16 v[12:15], v[78:81], v[170:173], v[12:15]
	v_mfma_f32_16x16x32_f16 v[8:11], v[94:97], v[170:173], v[8:11]
	s_waitcnt lgkmcnt(3)
	v_mfma_f32_16x16x32_f16 v[62:65], v[86:89], v[126:129], v[62:65]
	v_mfma_f32_16x16x32_f16 v[58:61], v[102:105], v[126:129], v[58:61]
	s_waitcnt lgkmcnt(2)
	v_mfma_f32_16x16x32_f16 v[46:49], v[86:89], v[134:137], v[46:49]
	v_mfma_f32_16x16x32_f16 v[42:45], v[102:105], v[134:137], v[42:45]
	s_waitcnt lgkmcnt(1)
	v_mfma_f32_16x16x32_f16 v[28:31], v[86:89], v[158:161], v[28:31]
	v_mfma_f32_16x16x32_f16 v[24:27], v[102:105], v[158:161], v[24:27]
	s_waitcnt lgkmcnt(0)
	v_mfma_f32_16x16x32_f16 v[12:15], v[86:89], v[174:177], v[12:15]
	v_mfma_f32_16x16x32_f16 v[8:11], v[102:105], v[174:177], v[8:11]
	s_setprio 0
	s_barrier
	s_add_u32 s14, s22, 0x40080
	s_addc_u32 s15, s23, 0
	s_add_i32 s22, s24, s13
	v_lshl_add_u64 v[78:79], s[14:15], 0, v[32:33]
	s_mov_b32 m0, s22
	s_nop 0
	global_load_lds_dwordx4 v[78:79], off
	v_lshl_add_u64 v[78:79], s[14:15], 0, v[198:199]
	s_add_i32 m0, s22, 0x2000
	s_nop 0
	global_load_lds_dwordx4 v[78:79], off
	s_waitcnt vmcnt(6)
	s_barrier
	s_setprio 1
	v_mfma_f32_16x16x32_f16 v[54:57], v[182:185], v[122:125], v[54:57]
	v_mfma_f32_16x16x32_f16 v[50:53], v[190:193], v[122:125], v[50:53]
	v_mfma_f32_16x16x32_f16 v[38:41], v[182:185], v[130:133], v[38:41]
	v_mfma_f32_16x16x32_f16 v[34:37], v[190:193], v[130:133], v[34:37]
	v_mfma_f32_16x16x32_f16 v[20:23], v[182:185], v[154:157], v[20:23]
	v_mfma_f32_16x16x32_f16 v[16:19], v[190:193], v[154:157], v[16:19]
	v_mfma_f32_16x16x32_f16 v[4:7], v[182:185], v[170:173], v[4:7]
	v_mfma_f32_16x16x32_f16 v[0:3], v[190:193], v[170:173], v[0:3]
	v_mfma_f32_16x16x32_f16 v[54:57], v[186:189], v[126:129], v[54:57]
	v_mfma_f32_16x16x32_f16 v[50:53], v[194:197], v[126:129], v[50:53]
	v_mfma_f32_16x16x32_f16 v[38:41], v[186:189], v[134:137], v[38:41]
	v_mfma_f32_16x16x32_f16 v[34:37], v[194:197], v[134:137], v[34:37]
	v_mfma_f32_16x16x32_f16 v[20:23], v[186:189], v[158:161], v[20:23]
	v_mfma_f32_16x16x32_f16 v[16:19], v[194:197], v[158:161], v[16:19]
	v_mfma_f32_16x16x32_f16 v[4:7], v[186:189], v[174:177], v[4:7]
	v_mfma_f32_16x16x32_f16 v[0:3], v[194:197], v[174:177], v[0:3]
	s_setprio 0
	s_add_u32 s39, s39, 0x100
	s_addc_u32 s40, s40, 0
	s_cmp_ge_u32 s41, s37
	s_mov_b64 s[14:15], s[20:21]
	s_mov_b32 s22, s41
	s_barrier
	s_cbranch_scc0 .LBB0_1117
	v_lshl_or_b32 v124, s12, 8, v231
	s_cmp_eq_u32 s10, 0
	s_movk_i32 s12, 0x5000
	s_cselect_b32 s12, 0xe000, s12
	v_readlane_b32 s14, v252, 51
	s_add_u32 s14, s14, s12
	v_readlane_b32 s12, v252, 52
	s_addc_u32 s15, s12, 0
	v_ashrrev_i32_e32 v125, 31, v124
	v_lshl_add_u64 v[86:87], v[124:125], 2, s[14:15]
	global_load_dwordx4 v[94:97], v[86:87], off offset:16
	global_load_dwordx4 v[102:105], v[86:87], off
	global_load_dwordx4 v[78:81], v[86:87], off offset:528
	s_nop 0
	global_load_dwordx4 v[86:89], v[86:87], off offset:512
	v_lshl_add_u32 v130, s10, 8, v229
	v_or_b32_e32 v128, 16, v130
	v_or_b32_e32 v126, 32, v130
	v_or_b32_e32 v122, 48, v130
	s_cmp_eq_u32 s11, 0
	v_ashrrev_i32_e32 v131, 31, v130
	v_ashrrev_i32_e32 v129, 31, v128
	v_ashrrev_i32_e32 v127, 31, v126
	v_ashrrev_i32_e32 v123, 31, v122
	s_cbranch_scc1 .LBB0_1120
	s_add_i32 s96, s11, -1
	s_lshl_b64 s[10:11], s[96:97], 20
	v_readlane_b32 s14, v252, 11
	v_readlane_b32 s15, v252, 12
	s_add_u32 s10, s14, s10
	s_addc_u32 s11, s15, s11
	v_lshlrev_b64 v[132:133], 2, v[124:125]
	v_lshrrev_b32_e32 v134, 5, v220
	v_mul_u32_u24_e32 v134, 48, v134
	s_nop 0
	v_sub_co_u32_e32 v132, vcc, v132, v134
	s_nop 1
	v_subbrev_co_u32_e32 v133, vcc, 0, v133, vcc
	v_lshl_add_u64 v[132:133], s[10:11], 0, v[132:133]
	s_mov_b64 s[10:11], 0x80000
	v_lshlrev_b64 v[204:205], 12, v[130:131]
	v_lshl_add_u64 v[204:205], v[204:205], 0, v[132:133]
	v_lshl_add_u64 v[212:213], v[204:205], 0, s[10:11]
	v_lshlrev_b64 v[206:207], 12, v[128:129]
	v_lshl_add_u64 v[206:207], v[206:207], 0, v[132:133]
	v_lshl_add_u64 v[214:215], v[206:207], 0, s[10:11]
	v_lshlrev_b64 v[208:209], 12, v[126:127]
	v_lshl_add_u64 v[208:209], v[208:209], 0, v[132:133]
	v_lshl_add_u64 v[216:217], v[208:209], 0, s[10:11]
	v_lshlrev_b64 v[210:211], 12, v[122:123]
	v_lshl_add_u64 v[210:211], v[210:211], 0, v[132:133]
	v_lshl_add_u64 v[218:219], v[210:211], 0, s[10:11]
	s_waitcnt vmcnt(0)
	v_pk_mul_f32 v[172:173], v[166:167], v[102:103]
	v_pk_mul_f32 v[174:175], v[168:169], v[104:105]
	v_pk_mul_f32 v[176:177], v[162:163], v[94:95]
	v_pk_mul_f32 v[178:179], v[164:165], v[96:97]
	s_nop 1
	v_permlane32_swap_b32_e32 v172, v176
	v_permlane32_swap_b32_e32 v173, v177
	v_permlane32_swap_b32_e32 v174, v178
	v_permlane32_swap_b32_e32 v175, v179
	s_nop 0
	global_store_dwordx4 v[204:205], v[172:175], off
	global_store_dwordx4 v[204:205], v[176:179], off offset:64
	v_pk_mul_f32 v[180:181], v[146:147], v[86:87]
	v_pk_mul_f32 v[182:183], v[148:149], v[88:89]
	v_pk_mul_f32 v[184:185], v[138:139], v[78:79]
	v_pk_mul_f32 v[186:187], v[140:141], v[80:81]
	s_nop 1
	v_permlane32_swap_b32_e32 v180, v184
	v_permlane32_swap_b32_e32 v181, v185
	v_permlane32_swap_b32_e32 v182, v186
	v_permlane32_swap_b32_e32 v183, v187
	s_nop 0
	global_store_dwordx4 v[204:205], v[180:183], off offset:512
	global_store_dwordx4 v[204:205], v[184:187], off offset:576
	v_pk_mul_f32 v[188:189], v[150:151], v[102:103]
	v_pk_mul_f32 v[190:191], v[152:153], v[104:105]
	v_pk_mul_f32 v[192:193], v[142:143], v[94:95]
	v_pk_mul_f32 v[194:195], v[144:145], v[96:97]
	s_nop 1
	v_permlane32_swap_b32_e32 v188, v192
	v_permlane32_swap_b32_e32 v189, v193
	v_permlane32_swap_b32_e32 v190, v194
	v_permlane32_swap_b32_e32 v191, v195
	s_nop 0
	global_store_dwordx4 v[206:207], v[188:191], off
	global_store_dwordx4 v[206:207], v[192:195], off offset:64
	v_pk_mul_f32 v[154:155], v[118:119], v[86:87]
	v_pk_mul_f32 v[156:157], v[120:121], v[88:89]
	v_pk_mul_f32 v[158:159], v[114:115], v[78:79]
	v_pk_mul_f32 v[160:161], v[116:117], v[80:81]
	s_nop 1
	v_permlane32_swap_b32_e32 v154, v158
	v_permlane32_swap_b32_e32 v155, v159
	v_permlane32_swap_b32_e32 v156, v160
	v_permlane32_swap_b32_e32 v157, v161
	s_nop 0
	global_store_dwordx4 v[206:207], v[154:157], off offset:512
	global_store_dwordx4 v[206:207], v[158:161], off offset:576
	v_pk_mul_f32 v[172:173], v[110:111], v[102:103]
	v_pk_mul_f32 v[174:175], v[112:113], v[104:105]
	v_pk_mul_f32 v[176:177], v[106:107], v[94:95]
	v_pk_mul_f32 v[178:179], v[108:109], v[96:97]
	s_nop 1
	v_permlane32_swap_b32_e32 v172, v176
	v_permlane32_swap_b32_e32 v173, v177
	v_permlane32_swap_b32_e32 v174, v178
	v_permlane32_swap_b32_e32 v175, v179
	s_nop 0
	global_store_dwordx4 v[208:209], v[172:175], off
	global_store_dwordx4 v[208:209], v[176:179], off offset:64
	v_pk_mul_f32 v[180:181], v[98:99], v[86:87]
	v_pk_mul_f32 v[182:183], v[100:101], v[88:89]
	v_pk_mul_f32 v[184:185], v[90:91], v[78:79]
	v_pk_mul_f32 v[186:187], v[92:93], v[80:81]
	s_nop 1
	v_permlane32_swap_b32_e32 v180, v184
	v_permlane32_swap_b32_e32 v181, v185
	v_permlane32_swap_b32_e32 v182, v186
	v_permlane32_swap_b32_e32 v183, v187
	s_nop 0
	global_store_dwordx4 v[208:209], v[180:183], off offset:512
	global_store_dwordx4 v[208:209], v[184:187], off offset:576
	v_pk_mul_f32 v[188:189], v[82:83], v[102:103]
	v_pk_mul_f32 v[190:191], v[84:85], v[104:105]
	v_pk_mul_f32 v[192:193], v[74:75], v[94:95]
	v_pk_mul_f32 v[194:195], v[76:77], v[96:97]
	s_nop 1
	v_permlane32_swap_b32_e32 v188, v192
	v_permlane32_swap_b32_e32 v189, v193
	v_permlane32_swap_b32_e32 v190, v194
	v_permlane32_swap_b32_e32 v191, v195
	s_nop 0
	global_store_dwordx4 v[210:211], v[188:191], off
	global_store_dwordx4 v[210:211], v[192:195], off offset:64
	v_pk_mul_f32 v[154:155], v[70:71], v[86:87]
	v_pk_mul_f32 v[156:157], v[72:73], v[88:89]
	v_pk_mul_f32 v[158:159], v[66:67], v[78:79]
	v_pk_mul_f32 v[160:161], v[68:69], v[80:81]
	s_nop 1
	v_permlane32_swap_b32_e32 v154, v158
	v_permlane32_swap_b32_e32 v155, v159
	v_permlane32_swap_b32_e32 v156, v160
	v_permlane32_swap_b32_e32 v157, v161
	s_nop 0
	global_store_dwordx4 v[210:211], v[154:157], off offset:512
	global_store_dwordx4 v[210:211], v[158:161], off offset:576
	v_pk_mul_f32 v[172:173], v[62:63], v[102:103]
	v_pk_mul_f32 v[174:175], v[64:65], v[104:105]
	v_pk_mul_f32 v[176:177], v[58:59], v[94:95]
	v_pk_mul_f32 v[178:179], v[60:61], v[96:97]
	s_nop 1
	v_permlane32_swap_b32_e32 v172, v176
	v_permlane32_swap_b32_e32 v173, v177
	v_permlane32_swap_b32_e32 v174, v178
	v_permlane32_swap_b32_e32 v175, v179
	s_nop 0
	global_store_dwordx4 v[212:213], v[172:175], off
	global_store_dwordx4 v[212:213], v[176:179], off offset:64
	v_pk_mul_f32 v[180:181], v[54:55], v[86:87]
	v_pk_mul_f32 v[182:183], v[56:57], v[88:89]
	v_pk_mul_f32 v[184:185], v[50:51], v[78:79]
	v_pk_mul_f32 v[186:187], v[52:53], v[80:81]
	s_nop 1
	v_permlane32_swap_b32_e32 v180, v184
	v_permlane32_swap_b32_e32 v181, v185
	v_permlane32_swap_b32_e32 v182, v186
	v_permlane32_swap_b32_e32 v183, v187
	s_nop 0
	global_store_dwordx4 v[212:213], v[180:183], off offset:512
	global_store_dwordx4 v[212:213], v[184:187], off offset:576
	v_pk_mul_f32 v[188:189], v[46:47], v[102:103]
	v_pk_mul_f32 v[190:191], v[48:49], v[104:105]
	v_pk_mul_f32 v[192:193], v[42:43], v[94:95]
	v_pk_mul_f32 v[194:195], v[44:45], v[96:97]
	s_nop 1
	v_permlane32_swap_b32_e32 v188, v192
	v_permlane32_swap_b32_e32 v189, v193
	v_permlane32_swap_b32_e32 v190, v194
	v_permlane32_swap_b32_e32 v191, v195
	s_nop 0
	global_store_dwordx4 v[214:215], v[188:191], off
	global_store_dwordx4 v[214:215], v[192:195], off offset:64
	v_pk_mul_f32 v[154:155], v[38:39], v[86:87]
	v_pk_mul_f32 v[156:157], v[40:41], v[88:89]
	v_pk_mul_f32 v[158:159], v[34:35], v[78:79]
	v_pk_mul_f32 v[160:161], v[36:37], v[80:81]
	s_nop 1
	v_permlane32_swap_b32_e32 v154, v158
	v_permlane32_swap_b32_e32 v155, v159
	v_permlane32_swap_b32_e32 v156, v160
	v_permlane32_swap_b32_e32 v157, v161
	s_nop 0
	global_store_dwordx4 v[214:215], v[154:157], off offset:512
	global_store_dwordx4 v[214:215], v[158:161], off offset:576
	v_pk_mul_f32 v[172:173], v[28:29], v[102:103]
	v_pk_mul_f32 v[174:175], v[30:31], v[104:105]
	v_pk_mul_f32 v[176:177], v[24:25], v[94:95]
	v_pk_mul_f32 v[178:179], v[26:27], v[96:97]
	s_nop 1
	v_permlane32_swap_b32_e32 v172, v176
	v_permlane32_swap_b32_e32 v173, v177
	v_permlane32_swap_b32_e32 v174, v178
	v_permlane32_swap_b32_e32 v175, v179
	s_nop 0
	global_store_dwordx4 v[216:217], v[172:175], off
	global_store_dwordx4 v[216:217], v[176:179], off offset:64
	v_pk_mul_f32 v[180:181], v[20:21], v[86:87]
	v_pk_mul_f32 v[182:183], v[22:23], v[88:89]
	v_pk_mul_f32 v[184:185], v[16:17], v[78:79]
	v_pk_mul_f32 v[186:187], v[18:19], v[80:81]
	s_nop 1
	v_permlane32_swap_b32_e32 v180, v184
	v_permlane32_swap_b32_e32 v181, v185
	v_permlane32_swap_b32_e32 v182, v186
	v_permlane32_swap_b32_e32 v183, v187
	s_nop 0
	global_store_dwordx4 v[216:217], v[180:183], off offset:512
	global_store_dwordx4 v[216:217], v[184:187], off offset:576
	v_pk_mul_f32 v[188:189], v[12:13], v[102:103]
	v_pk_mul_f32 v[190:191], v[14:15], v[104:105]
	v_pk_mul_f32 v[192:193], v[8:9], v[94:95]
	v_pk_mul_f32 v[194:195], v[10:11], v[96:97]
	s_nop 1
	v_permlane32_swap_b32_e32 v188, v192
	v_permlane32_swap_b32_e32 v189, v193
	v_permlane32_swap_b32_e32 v190, v194
	v_permlane32_swap_b32_e32 v191, v195
	s_nop 0
	global_store_dwordx4 v[218:219], v[188:191], off
	global_store_dwordx4 v[218:219], v[192:195], off offset:64
	v_pk_mul_f32 v[154:155], v[4:5], v[86:87]
	v_pk_mul_f32 v[156:157], v[6:7], v[88:89]
	v_pk_mul_f32 v[158:159], v[0:1], v[78:79]
	v_pk_mul_f32 v[160:161], v[2:3], v[80:81]
	s_nop 1
	v_permlane32_swap_b32_e32 v154, v158
	v_permlane32_swap_b32_e32 v155, v159
	v_permlane32_swap_b32_e32 v156, v160
	v_permlane32_swap_b32_e32 v157, v161
	s_nop 0
	global_store_dwordx4 v[218:219], v[154:157], off offset:512
	global_store_dwordx4 v[218:219], v[158:161], off offset:576
	s_cbranch_execnz .LBB0_1104
	s_branch .LBB0_1103

.LBB0_1276:
	s_add_u32 s16, s14, 0x100
	s_addc_u32 s17, s15, 0
	s_add_i32 s39, 0, 0x10000
	v_add_u32_e32 v152, s39, v137
	ds_read_b128 v[140:143], v152
	ds_read_b128 v[148:151], v152 offset:2048
	ds_read_b128 v[144:147], v152 offset:1024
	ds_read_b128 v[152:155], v152 offset:3072
	s_cmp_eq_u32 s38, 12
	s_cselect_b32 s21, s11, s17
	s_cselect_b32 s20, s10, s16
	s_cselect_b32 s19, s13, s37
	s_cselect_b32 s18, s12, s3
	v_lshl_add_u64 v[188:189], s[14:15], 0, v[132:133]
	s_add_i32 m0, s9, 0xc000
	ds_read_b128 v[156:159], v139
	ds_read_b128 v[164:167], v139 offset:2048
	ds_read_b128 v[172:175], v139 offset:4096
	ds_read_b128 v[180:183], v139 offset:6144
	ds_read_b128 v[160:163], v139 offset:1024
	ds_read_b128 v[168:171], v139 offset:3072
	ds_read_b128 v[176:179], v139 offset:5120
	ds_read_b128 v[184:187], v139 offset:7168
	global_load_lds_dwordx4 v[188:189], off
	v_lshl_add_u64 v[188:189], s[14:15], 0, v[134:135]
	s_add_i32 m0, s9, 0xe000
	s_nop 0
	global_load_lds_dwordx4 v[188:189], off
	s_waitcnt lgkmcnt(8)
	s_barrier
	s_waitcnt lgkmcnt(7)
	s_setprio 1
	v_mfma_f32_16x16x32_f16 v[126:129], v[140:143], v[156:159], v[126:129]
	v_mfma_f32_16x16x32_f16 v[122:125], v[148:151], v[156:159], v[122:125]
	s_waitcnt lgkmcnt(6)
	v_mfma_f32_16x16x32_f16 v[110:113], v[140:143], v[164:167], v[110:113]
	v_mfma_f32_16x16x32_f16 v[106:109], v[148:151], v[164:167], v[106:109]
	s_waitcnt lgkmcnt(5)
	v_mfma_f32_16x16x32_f16 v[94:97], v[140:143], v[172:175], v[94:97]
	v_mfma_f32_16x16x32_f16 v[90:93], v[148:151], v[172:175], v[90:93]
	s_waitcnt lgkmcnt(4)
	v_mfma_f32_16x16x32_f16 v[78:81], v[140:143], v[180:183], v[78:81]
	v_mfma_f32_16x16x32_f16 v[74:77], v[148:151], v[180:183], v[74:77]
	s_waitcnt lgkmcnt(3)
	v_mfma_f32_16x16x32_f16 v[126:129], v[144:147], v[160:163], v[126:129]
	v_mfma_f32_16x16x32_f16 v[122:125], v[152:155], v[160:163], v[122:125]
	s_waitcnt lgkmcnt(2)
	v_mfma_f32_16x16x32_f16 v[110:113], v[144:147], v[168:171], v[110:113]
	v_mfma_f32_16x16x32_f16 v[106:109], v[152:155], v[168:171], v[106:109]
	s_waitcnt lgkmcnt(1)
	v_mfma_f32_16x16x32_f16 v[94:97], v[144:147], v[176:179], v[94:97]
	v_mfma_f32_16x16x32_f16 v[90:93], v[152:155], v[176:179], v[90:93]
	s_waitcnt lgkmcnt(0)
	v_mfma_f32_16x16x32_f16 v[78:81], v[144:147], v[184:187], v[78:81]
	v_mfma_f32_16x16x32_f16 v[74:77], v[152:155], v[184:187], v[74:77]
	s_setprio 0
	s_barrier
	s_add_i32 s40, 0, 0x14000
	s_add_i32 s14, s39, s26
	v_add_u32_e32 v200, s40, v137
	v_lshl_add_u64 v[204:205], s[18:19], 0, v[32:33]
	s_mov_b32 m0, s14
	ds_read_b128 v[188:191], v200
	ds_read_b128 v[196:199], v200 offset:2048
	ds_read_b128 v[192:195], v200 offset:1024
	ds_read_b128 v[200:203], v200 offset:3072
	global_load_lds_dwordx4 v[204:205], off
	v_lshl_add_u64 v[206:207], s[18:19], 0, v[130:131]
	s_add_i32 m0, s14, 0x2000
	s_nop 0
	global_load_lds_dwordx4 v[206:207], off
	s_barrier
	s_waitcnt lgkmcnt(2)
	s_setprio 1
	v_mfma_f32_16x16x32_f16 v[118:121], v[188:191], v[156:159], v[118:121]
	v_mfma_f32_16x16x32_f16 v[114:117], v[196:199], v[156:159], v[114:117]
	v_mfma_f32_16x16x32_f16 v[102:105], v[188:191], v[164:167], v[102:105]
	v_mfma_f32_16x16x32_f16 v[98:101], v[196:199], v[164:167], v[98:101]
	v_mfma_f32_16x16x32_f16 v[86:89], v[188:191], v[172:175], v[86:89]
	v_mfma_f32_16x16x32_f16 v[82:85], v[196:199], v[172:175], v[82:85]
	v_mfma_f32_16x16x32_f16 v[70:73], v[188:191], v[180:183], v[70:73]
	v_mfma_f32_16x16x32_f16 v[66:69], v[196:199], v[180:183], v[66:69]
	s_waitcnt lgkmcnt(0)
	v_mfma_f32_16x16x32_f16 v[118:121], v[192:195], v[160:163], v[118:121]
	v_mfma_f32_16x16x32_f16 v[114:117], v[200:203], v[160:163], v[114:117]
	v_mfma_f32_16x16x32_f16 v[102:105], v[192:195], v[168:171], v[102:105]
	v_mfma_f32_16x16x32_f16 v[98:101], v[200:203], v[168:171], v[98:101]
	v_mfma_f32_16x16x32_f16 v[86:89], v[192:195], v[176:179], v[86:89]
	v_mfma_f32_16x16x32_f16 v[82:85], v[200:203], v[176:179], v[82:85]
	v_mfma_f32_16x16x32_f16 v[70:73], v[192:195], v[184:187], v[70:73]
	v_mfma_f32_16x16x32_f16 v[66:69], v[200:203], v[184:187], v[66:69]
	s_setprio 0
	s_mov_b32 m0, s9
	v_lshl_add_u64 v[208:209], s[20:21], 0, v[32:33]
	s_barrier
	ds_read_b128 v[156:159], v139 offset:16384
	ds_read_b128 v[164:167], v139 offset:18432
	ds_read_b128 v[172:175], v139 offset:20480
	ds_read_b128 v[180:183], v139 offset:22528
	ds_read_b128 v[160:163], v139 offset:17408
	ds_read_b128 v[168:171], v139 offset:19456
	ds_read_b128 v[176:179], v139 offset:21504
	ds_read_b128 v[184:187], v139 offset:23552
	global_load_lds_dwordx4 v[208:209], off
	v_lshl_add_u64 v[210:211], s[20:21], 0, v[130:131]
	s_mov_b32 m0, s27
	s_nop 0
	global_load_lds_dwordx4 v[210:211], off
	s_waitcnt vmcnt(10)
	s_barrier
	s_waitcnt lgkmcnt(7)
	s_setprio 1
	v_mfma_f32_16x16x32_f16 v[62:65], v[140:143], v[156:159], v[62:65]
	v_mfma_f32_16x16x32_f16 v[58:61], v[148:151], v[156:159], v[58:61]
	s_waitcnt lgkmcnt(6)
	v_mfma_f32_16x16x32_f16 v[46:49], v[140:143], v[164:167], v[46:49]
	v_mfma_f32_16x16x32_f16 v[42:45], v[148:151], v[164:167], v[42:45]
	s_waitcnt lgkmcnt(5)
	v_mfma_f32_16x16x32_f16 v[28:31], v[140:143], v[172:175], v[28:31]
	v_mfma_f32_16x16x32_f16 v[24:27], v[148:151], v[172:175], v[24:27]
	s_waitcnt lgkmcnt(4)
	v_mfma_f32_16x16x32_f16 v[12:15], v[140:143], v[180:183], v[12:15]
	v_mfma_f32_16x16x32_f16 v[8:11], v[148:151], v[180:183], v[8:11]
	s_waitcnt lgkmcnt(3)
	v_mfma_f32_16x16x32_f16 v[62:65], v[144:147], v[160:163], v[62:65]
	v_mfma_f32_16x16x32_f16 v[58:61], v[152:155], v[160:163], v[58:61]
	s_waitcnt lgkmcnt(2)
	v_mfma_f32_16x16x32_f16 v[46:49], v[144:147], v[168:171], v[46:49]
	v_mfma_f32_16x16x32_f16 v[42:45], v[152:155], v[168:171], v[42:45]
	s_waitcnt lgkmcnt(1)
	v_mfma_f32_16x16x32_f16 v[28:31], v[144:147], v[176:179], v[28:31]
	v_mfma_f32_16x16x32_f16 v[24:27], v[152:155], v[176:179], v[24:27]
	s_waitcnt lgkmcnt(0)
	v_mfma_f32_16x16x32_f16 v[12:15], v[144:147], v[184:187], v[12:15]
	v_mfma_f32_16x16x32_f16 v[8:11], v[152:155], v[184:187], v[8:11]
	s_setprio 0
	s_barrier
	s_add_u32 s14, s18, 0x40000
	s_addc_u32 s15, s19, 0
	s_add_i32 s39, s40, s26
	v_lshl_add_u64 v[140:141], s[14:15], 0, v[32:33]
	s_mov_b32 m0, s39
	s_nop 0
	global_load_lds_dwordx4 v[140:141], off
	v_lshl_add_u64 v[140:141], s[14:15], 0, v[130:131]
	s_add_i32 m0, s39, 0x2000
	s_nop 0
	global_load_lds_dwordx4 v[140:141], off
	v_add_u32_e32 v152, 0x18000, v137
	ds_read_b128 v[140:143], v152
	ds_read_b128 v[148:151], v152 offset:2048
	ds_read_b128 v[144:147], v152 offset:1024
	ds_read_b128 v[152:155], v152 offset:3072
	s_waitcnt vmcnt(6)
	s_barrier
	s_setprio 1
	v_mfma_f32_16x16x32_f16 v[54:57], v[188:191], v[156:159], v[54:57]
	v_mfma_f32_16x16x32_f16 v[50:53], v[196:199], v[156:159], v[50:53]
	v_mfma_f32_16x16x32_f16 v[38:41], v[188:191], v[164:167], v[38:41]
	v_mfma_f32_16x16x32_f16 v[34:37], v[196:199], v[164:167], v[34:37]
	v_mfma_f32_16x16x32_f16 v[20:23], v[188:191], v[172:175], v[20:23]
	v_mfma_f32_16x16x32_f16 v[16:19], v[196:199], v[172:175], v[16:19]
	v_mfma_f32_16x16x32_f16 v[4:7], v[188:191], v[180:183], v[4:7]
	v_mfma_f32_16x16x32_f16 v[0:3], v[196:199], v[180:183], v[0:3]
	v_mfma_f32_16x16x32_f16 v[54:57], v[192:195], v[160:163], v[54:57]
	v_mfma_f32_16x16x32_f16 v[50:53], v[200:203], v[160:163], v[50:53]
	v_mfma_f32_16x16x32_f16 v[38:41], v[192:195], v[168:171], v[38:41]
	v_mfma_f32_16x16x32_f16 v[34:37], v[200:203], v[168:171], v[34:37]
	v_mfma_f32_16x16x32_f16 v[20:23], v[192:195], v[176:179], v[20:23]
	v_mfma_f32_16x16x32_f16 v[16:19], v[200:203], v[176:179], v[16:19]
	v_mfma_f32_16x16x32_f16 v[4:7], v[192:195], v[184:187], v[4:7]
	v_mfma_f32_16x16x32_f16 v[0:3], v[200:203], v[184:187], v[0:3]
	s_setprio 0
	s_add_i32 s39, 0, 0x18000
	s_barrier
	s_add_u32 s14, s20, 0x40000
	s_addc_u32 s15, s21, 0
	s_mov_b32 m0, s28
	v_lshl_add_u64 v[188:189], s[14:15], 0, v[32:33]
	ds_read_b128 v[156:159], v139 offset:32768
	ds_read_b128 v[164:167], v139 offset:34816
	ds_read_b128 v[172:175], v139 offset:36864
	ds_read_b128 v[180:183], v139 offset:38912
	ds_read_b128 v[160:163], v139 offset:33792
	ds_read_b128 v[168:171], v139 offset:35840
	ds_read_b128 v[176:179], v139 offset:37888
	ds_read_b128 v[184:187], v139 offset:39936
	global_load_lds_dwordx4 v[188:189], off
	v_lshl_add_u64 v[188:189], s[14:15], 0, v[130:131]
	s_mov_b32 m0, s29
	s_nop 0
	global_load_lds_dwordx4 v[188:189], off
	s_waitcnt lgkmcnt(8)
	s_barrier
	s_waitcnt lgkmcnt(7)
	s_setprio 1
	v_mfma_f32_16x16x32_f16 v[126:129], v[140:143], v[156:159], v[126:129]
	v_mfma_f32_16x16x32_f16 v[122:125], v[148:151], v[156:159], v[122:125]
	s_waitcnt lgkmcnt(6)
	v_mfma_f32_16x16x32_f16 v[110:113], v[140:143], v[164:167], v[110:113]
	v_mfma_f32_16x16x32_f16 v[106:109], v[148:151], v[164:167], v[106:109]
	s_waitcnt lgkmcnt(5)
	v_mfma_f32_16x16x32_f16 v[94:97], v[140:143], v[172:175], v[94:97]
	v_mfma_f32_16x16x32_f16 v[90:93], v[148:151], v[172:175], v[90:93]
	s_waitcnt lgkmcnt(4)
	v_mfma_f32_16x16x32_f16 v[78:81], v[140:143], v[180:183], v[78:81]
	v_mfma_f32_16x16x32_f16 v[74:77], v[148:151], v[180:183], v[74:77]
	s_waitcnt lgkmcnt(3)
	v_mfma_f32_16x16x32_f16 v[126:129], v[144:147], v[160:163], v[126:129]
	v_mfma_f32_16x16x32_f16 v[122:125], v[152:155], v[160:163], v[122:125]
	s_waitcnt lgkmcnt(2)
	v_mfma_f32_16x16x32_f16 v[110:113], v[144:147], v[168:171], v[110:113]
	v_mfma_f32_16x16x32_f16 v[106:109], v[152:155], v[168:171], v[106:109]
	s_waitcnt lgkmcnt(1)
	v_mfma_f32_16x16x32_f16 v[94:97], v[144:147], v[176:179], v[94:97]
	v_mfma_f32_16x16x32_f16 v[90:93], v[152:155], v[176:179], v[90:93]
	s_waitcnt lgkmcnt(0)
	v_mfma_f32_16x16x32_f16 v[78:81], v[144:147], v[184:187], v[78:81]
	v_mfma_f32_16x16x32_f16 v[74:77], v[152:155], v[184:187], v[74:77]
	s_setprio 0
	s_barrier
	s_add_i32 s20, 0, 0x1c000
	s_add_i32 s14, s39, s26
	v_add_u32_e32 v200, s20, v137
	v_lshl_add_u64 v[204:205], v[204:205], 0, s[84:85]
	s_mov_b32 m0, s14
	ds_read_b128 v[188:191], v200
	ds_read_b128 v[196:199], v200 offset:2048
	ds_read_b128 v[192:195], v200 offset:1024
	ds_read_b128 v[200:203], v200 offset:3072
	global_load_lds_dwordx4 v[204:205], off
	v_lshl_add_u64 v[204:205], v[206:207], 0, s[84:85]
	s_add_i32 m0, s14, 0x2000
	s_nop 0
	global_load_lds_dwordx4 v[204:205], off
	s_barrier
	s_waitcnt lgkmcnt(2)
	s_setprio 1
	v_mfma_f32_16x16x32_f16 v[118:121], v[188:191], v[156:159], v[118:121]
	v_mfma_f32_16x16x32_f16 v[114:117], v[196:199], v[156:159], v[114:117]
	v_mfma_f32_16x16x32_f16 v[102:105], v[188:191], v[164:167], v[102:105]
	v_mfma_f32_16x16x32_f16 v[98:101], v[196:199], v[164:167], v[98:101]
	v_mfma_f32_16x16x32_f16 v[86:89], v[188:191], v[172:175], v[86:89]
	v_mfma_f32_16x16x32_f16 v[82:85], v[196:199], v[172:175], v[82:85]
	v_mfma_f32_16x16x32_f16 v[70:73], v[188:191], v[180:183], v[70:73]
	v_mfma_f32_16x16x32_f16 v[66:69], v[196:199], v[180:183], v[66:69]
	s_waitcnt lgkmcnt(0)
	v_mfma_f32_16x16x32_f16 v[118:121], v[192:195], v[160:163], v[118:121]
	v_mfma_f32_16x16x32_f16 v[114:117], v[200:203], v[160:163], v[114:117]
	v_mfma_f32_16x16x32_f16 v[102:105], v[192:195], v[168:171], v[102:105]
	v_mfma_f32_16x16x32_f16 v[98:101], v[200:203], v[168:171], v[98:101]
	v_mfma_f32_16x16x32_f16 v[86:89], v[192:195], v[176:179], v[86:89]
	v_mfma_f32_16x16x32_f16 v[82:85], v[200:203], v[176:179], v[82:85]
	v_mfma_f32_16x16x32_f16 v[70:73], v[192:195], v[184:187], v[70:73]
	v_mfma_f32_16x16x32_f16 v[66:69], v[200:203], v[184:187], v[66:69]
	s_setprio 0
	s_mov_b32 m0, s30
	v_lshl_add_u64 v[204:205], v[208:209], 0, s[84:85]
	s_barrier
	ds_read_b128 v[156:159], v139 offset:49152
	ds_read_b128 v[164:167], v139 offset:51200
	ds_read_b128 v[172:175], v139 offset:53248
	ds_read_b128 v[180:183], v139 offset:55296
	ds_read_b128 v[160:163], v139 offset:50176
	ds_read_b128 v[168:171], v139 offset:52224
	ds_read_b128 v[176:179], v139 offset:54272
	ds_read_b128 v[184:187], v139 offset:56320
	global_load_lds_dwordx4 v[204:205], off
	v_lshl_add_u64 v[204:205], v[210:211], 0, s[84:85]
	s_mov_b32 m0, s31
	s_nop 0
	global_load_lds_dwordx4 v[204:205], off
	s_barrier
	s_waitcnt lgkmcnt(7)
	s_setprio 1
	v_mfma_f32_16x16x32_f16 v[62:65], v[140:143], v[156:159], v[62:65]
	v_mfma_f32_16x16x32_f16 v[58:61], v[148:151], v[156:159], v[58:61]
	s_waitcnt lgkmcnt(6)
	v_mfma_f32_16x16x32_f16 v[46:49], v[140:143], v[164:167], v[46:49]
	v_mfma_f32_16x16x32_f16 v[42:45], v[148:151], v[164:167], v[42:45]
	s_waitcnt lgkmcnt(5)
	v_mfma_f32_16x16x32_f16 v[28:31], v[140:143], v[172:175], v[28:31]
	v_mfma_f32_16x16x32_f16 v[24:27], v[148:151], v[172:175], v[24:27]
	s_waitcnt lgkmcnt(4)
	v_mfma_f32_16x16x32_f16 v[12:15], v[140:143], v[180:183], v[12:15]
	v_mfma_f32_16x16x32_f16 v[8:11], v[148:151], v[180:183], v[8:11]
	s_waitcnt lgkmcnt(3)
	v_mfma_f32_16x16x32_f16 v[62:65], v[144:147], v[160:163], v[62:65]
	v_mfma_f32_16x16x32_f16 v[58:61], v[152:155], v[160:163], v[58:61]
	s_waitcnt lgkmcnt(2)
	v_mfma_f32_16x16x32_f16 v[46:49], v[144:147], v[168:171], v[46:49]
	v_mfma_f32_16x16x32_f16 v[42:45], v[152:155], v[168:171], v[42:45]
	s_waitcnt lgkmcnt(1)
	v_mfma_f32_16x16x32_f16 v[28:31], v[144:147], v[176:179], v[28:31]
	v_mfma_f32_16x16x32_f16 v[24:27], v[152:155], v[176:179], v[24:27]
	s_waitcnt lgkmcnt(0)
	v_mfma_f32_16x16x32_f16 v[12:15], v[144:147], v[184:187], v[12:15]
	v_mfma_f32_16x16x32_f16 v[8:11], v[152:155], v[184:187], v[8:11]
	s_setprio 0
	s_barrier
	s_add_u32 s14, s18, 0x40080
	s_addc_u32 s15, s19, 0
	s_add_i32 s18, s20, s26
	v_lshl_add_u64 v[140:141], s[14:15], 0, v[32:33]
	s_mov_b32 m0, s18
	s_nop 0
	global_load_lds_dwordx4 v[140:141], off
	v_lshl_add_u64 v[140:141], s[14:15], 0, v[130:131]
	s_add_i32 m0, s18, 0x2000
	s_nop 0
	global_load_lds_dwordx4 v[140:141], off
	s_waitcnt vmcnt(6)
	s_barrier
	s_setprio 1
	v_mfma_f32_16x16x32_f16 v[54:57], v[188:191], v[156:159], v[54:57]
	v_mfma_f32_16x16x32_f16 v[50:53], v[196:199], v[156:159], v[50:53]
	v_mfma_f32_16x16x32_f16 v[38:41], v[188:191], v[164:167], v[38:41]
	v_mfma_f32_16x16x32_f16 v[34:37], v[196:199], v[164:167], v[34:37]
	v_mfma_f32_16x16x32_f16 v[20:23], v[188:191], v[172:175], v[20:23]
	v_mfma_f32_16x16x32_f16 v[16:19], v[196:199], v[172:175], v[16:19]
	v_mfma_f32_16x16x32_f16 v[4:7], v[188:191], v[180:183], v[4:7]
	v_mfma_f32_16x16x32_f16 v[0:3], v[196:199], v[180:183], v[0:3]
	v_mfma_f32_16x16x32_f16 v[54:57], v[192:195], v[160:163], v[54:57]
	v_mfma_f32_16x16x32_f16 v[50:53], v[200:203], v[160:163], v[50:53]
	v_mfma_f32_16x16x32_f16 v[38:41], v[192:195], v[168:171], v[38:41]
	v_mfma_f32_16x16x32_f16 v[34:37], v[200:203], v[168:171], v[34:37]
	v_mfma_f32_16x16x32_f16 v[20:23], v[192:195], v[176:179], v[20:23]
	v_mfma_f32_16x16x32_f16 v[16:19], v[200:203], v[176:179], v[16:19]
	v_mfma_f32_16x16x32_f16 v[4:7], v[192:195], v[184:187], v[4:7]
	v_mfma_f32_16x16x32_f16 v[0:3], v[200:203], v[184:187], v[0:3]
	s_setprio 0
	s_add_i32 s38, s38, 2
	s_add_u32 s3, s3, 0x100
	s_addc_u32 s37, s37, 0
	s_cmp_gt_u32 s38, 13
	s_mov_b64 s[14:15], s[16:17]
	s_barrier
	s_cbranch_scc0 .LBB0_1276
	v_mul_f32_e32 v144, 0xbfb8aa3b, v127
	v_mul_f32_e32 v141, 0xbfb8aa3b, v126
	v_exp_f32_e32 v145, v144
	v_mul_f32_e32 v144, 0xbfb8aa3b, v128
	v_exp_f32_e32 v141, v141
	v_exp_f32_e32 v146, v144
	v_mul_f32_e32 v144, 0xbfb8aa3b, v129
	v_exp_f32_e32 v147, v144
	v_mul_f32_e32 v144, 0xbfb8aa3b, v122
	v_exp_f32_e32 v148, v144
	v_mul_f32_e32 v144, 0xbfb8aa3b, v123
	v_exp_f32_e32 v149, v144
	v_mul_f32_e32 v144, 0xbfb8aa3b, v124
	v_exp_f32_e32 v150, v144
	v_mul_f32_e32 v144, 0xbfb8aa3b, v125
	v_add_f32_e32 v141, 1.0, v141
	v_exp_f32_e32 v151, v144
	v_rcp_f32_e32 v144, v141
	v_add_f32_e32 v141, 1.0, v145
	v_rcp_f32_e32 v145, v141
	v_add_f32_e32 v141, 1.0, v146
	v_rcp_f32_e32 v146, v141
	v_add_f32_e32 v141, 1.0, v147
	v_rcp_f32_e32 v147, v141
	v_add_f32_e32 v141, 1.0, v148
	v_rcp_f32_e32 v148, v141
	v_add_f32_e32 v141, 1.0, v149
	v_rcp_f32_e32 v149, v141
	v_add_f32_e32 v141, 1.0, v150
	v_rcp_f32_e32 v150, v141
	v_add_f32_e32 v141, 1.0, v151
	v_pk_mul_f32 v[126:127], v[126:127], v[144:145]
	v_rcp_f32_e32 v151, v141
	v_pk_mul_f32 v[118:119], v[126:127], v[118:119]
	v_pk_mul_f32 v[126:127], v[128:129], v[146:147]
	v_cvt_pk_f16_f32 v118, v118, v119
	v_pk_mul_f32 v[120:121], v[126:127], v[120:121]
	v_lshl_or_b32 v142, s36, 7, v138
	v_cvt_pk_f16_f32 v119, v120, v121
	v_pk_mul_f32 v[120:121], v[122:123], v[148:149]
	v_lshl_add_u32 v140, s8, 8, v136
	v_pk_mul_f32 v[114:115], v[120:121], v[114:115]
	v_ashrrev_i32_e32 v143, 31, v142
	v_cvt_pk_f16_f32 v120, v114, v115
	v_pk_mul_f32 v[114:115], v[124:125], v[150:151]
	s_movk_i32 s3, 0x1600
	v_pk_mul_f32 v[114:115], v[114:115], v[116:117]
	v_lshlrev_b64 v[116:117], 1, v[142:143]
	v_cvt_pk_f16_f32 v121, v114, v115
	v_mov_b64_e32 v[114:115], s[92:93]
	v_mad_i64_i32 v[122:123], s[10:11], v140, s3, v[114:115]
	v_lshl_add_u64 v[122:123], v[122:123], 0, v[116:117]
	global_store_dwordx4 v[122:123], v[118:121], off
	v_mul_f32_e32 v122, 0xbfb8aa3b, v106
	v_mul_f32_e32 v123, 0xbfb8aa3b, v107
	v_mul_f32_e32 v118, 0xbfb8aa3b, v110
	v_mul_f32_e32 v119, 0xbfb8aa3b, v111
	v_exp_f32_e32 v118, v118
	v_exp_f32_e32 v119, v119
	v_mul_f32_e32 v120, 0xbfb8aa3b, v112
	v_mul_f32_e32 v121, 0xbfb8aa3b, v113
	v_exp_f32_e32 v120, v120
	v_exp_f32_e32 v121, v121
	v_exp_f32_e32 v122, v122
	v_exp_f32_e32 v123, v123
	v_mul_f32_e32 v124, 0xbfb8aa3b, v108
	v_mul_f32_e32 v125, 0xbfb8aa3b, v109
	v_add_f32_e32 v118, 1.0, v118
	v_add_f32_e32 v119, 1.0, v119
	v_exp_f32_e32 v124, v124
	v_exp_f32_e32 v125, v125
	v_rcp_f32_e32 v118, v118
	v_rcp_f32_e32 v119, v119
	v_add_f32_e32 v120, 1.0, v120
	v_add_f32_e32 v121, 1.0, v121
	v_rcp_f32_e32 v120, v120
	v_rcp_f32_e32 v121, v121
	v_add_f32_e32 v122, 1.0, v122
	v_add_f32_e32 v123, 1.0, v123
	v_rcp_f32_e32 v122, v122
	v_rcp_f32_e32 v123, v123
	v_add_f32_e32 v124, 1.0, v124
	v_add_f32_e32 v125, 1.0, v125
	v_pk_mul_f32 v[110:111], v[110:111], v[118:119]
	v_rcp_f32_e32 v124, v124
	v_rcp_f32_e32 v125, v125
	v_pk_mul_f32 v[102:103], v[110:111], v[102:103]
	v_pk_mul_f32 v[110:111], v[112:113], v[120:121]
	v_cvt_pk_f16_f32 v102, v102, v103
	v_pk_mul_f32 v[104:105], v[110:111], v[104:105]
	s_and_b64 vcc, exec, s[0:1]
	v_cvt_pk_f16_f32 v103, v104, v105
	v_pk_mul_f32 v[104:105], v[106:107], v[122:123]
	s_mov_b32 s36, s35
	v_pk_mul_f32 v[98:99], v[104:105], v[98:99]
	s_mov_b32 s8, s2
	v_cvt_pk_f16_f32 v104, v98, v99
	v_pk_mul_f32 v[98:99], v[108:109], v[124:125]
	s_mov_b64 s[16:17], s[6:7]
	v_pk_mul_f32 v[98:99], v[98:99], v[100:101]
	v_mul_f32_e32 v100, 0xbfb8aa3b, v96
	v_cvt_pk_f16_f32 v105, v98, v99
	v_or_b32_e32 v98, 16, v140
	v_mad_i64_i32 v[98:99], s[10:11], v98, s3, v[114:115]
	v_lshl_add_u64 v[98:99], v[98:99], 0, v[116:117]
	global_store_dwordx4 v[98:99], v[102:105], off
	v_mul_f32_e32 v98, 0xbfb8aa3b, v94
	v_mul_f32_e32 v99, 0xbfb8aa3b, v95
	v_exp_f32_e32 v98, v98
	v_exp_f32_e32 v99, v99
	v_mul_f32_e32 v101, 0xbfb8aa3b, v97
	v_exp_f32_e32 v100, v100
	v_exp_f32_e32 v101, v101
	v_mul_f32_e32 v102, 0xbfb8aa3b, v90
	v_mul_f32_e32 v103, 0xbfb8aa3b, v91
	v_exp_f32_e32 v102, v102
	v_exp_f32_e32 v103, v103
	v_mul_f32_e32 v104, 0xbfb8aa3b, v92
	v_mul_f32_e32 v105, 0xbfb8aa3b, v93
	v_add_f32_e32 v98, 1.0, v98
	v_add_f32_e32 v99, 1.0, v99
	v_exp_f32_e32 v104, v104
	v_exp_f32_e32 v105, v105
	v_rcp_f32_e32 v98, v98
	v_rcp_f32_e32 v99, v99
	v_add_f32_e32 v100, 1.0, v100
	v_add_f32_e32 v101, 1.0, v101
	v_rcp_f32_e32 v100, v100
	v_rcp_f32_e32 v101, v101
	v_add_f32_e32 v102, 1.0, v102
	v_add_f32_e32 v103, 1.0, v103
	v_rcp_f32_e32 v102, v102
	v_rcp_f32_e32 v103, v103
	v_add_f32_e32 v104, 1.0, v104
	v_add_f32_e32 v105, 1.0, v105
	v_pk_mul_f32 v[94:95], v[94:95], v[98:99]
	v_rcp_f32_e32 v104, v104
	v_rcp_f32_e32 v105, v105
	v_pk_mul_f32 v[86:87], v[94:95], v[86:87]
	v_pk_mul_f32 v[94:95], v[96:97], v[100:101]
	v_cvt_pk_f16_f32 v86, v86, v87
	v_pk_mul_f32 v[88:89], v[94:95], v[88:89]
	s_mov_b64 s[14:15], s[4:5]
	v_cvt_pk_f16_f32 v87, v88, v89
	v_pk_mul_f32 v[88:89], v[90:91], v[102:103]
	s_nop 0
	v_pk_mul_f32 v[82:83], v[88:89], v[82:83]
	s_nop 0
	v_cvt_pk_f16_f32 v88, v82, v83
	v_pk_mul_f32 v[82:83], v[92:93], v[104:105]
	s_nop 0
	v_pk_mul_f32 v[82:83], v[82:83], v[84:85]
	v_mul_f32_e32 v84, 0xbfb8aa3b, v80
	v_cvt_pk_f16_f32 v89, v82, v83
	v_or_b32_e32 v82, 32, v140
	v_mad_i64_i32 v[82:83], s[10:11], v82, s3, v[114:115]
	v_lshl_add_u64 v[82:83], v[82:83], 0, v[116:117]
	global_store_dwordx4 v[82:83], v[86:89], off
	v_mul_f32_e32 v82, 0xbfb8aa3b, v78
	v_mul_f32_e32 v83, 0xbfb8aa3b, v79
	v_exp_f32_e32 v82, v82
	v_exp_f32_e32 v83, v83
	v_mul_f32_e32 v85, 0xbfb8aa3b, v81
	v_exp_f32_e32 v84, v84
	v_exp_f32_e32 v85, v85
	v_mul_f32_e32 v86, 0xbfb8aa3b, v74
	v_mul_f32_e32 v87, 0xbfb8aa3b, v75
	v_exp_f32_e32 v86, v86
	v_exp_f32_e32 v87, v87
	v_mul_f32_e32 v88, 0xbfb8aa3b, v76
	v_mul_f32_e32 v89, 0xbfb8aa3b, v77
	v_add_f32_e32 v82, 1.0, v82
	v_add_f32_e32 v83, 1.0, v83
	v_exp_f32_e32 v88, v88
	v_exp_f32_e32 v89, v89
	v_rcp_f32_e32 v82, v82
	v_rcp_f32_e32 v83, v83
	v_add_f32_e32 v84, 1.0, v84
	v_add_f32_e32 v85, 1.0, v85
	v_rcp_f32_e32 v84, v84
	v_rcp_f32_e32 v85, v85
	v_add_f32_e32 v86, 1.0, v86
	v_add_f32_e32 v87, 1.0, v87
	v_rcp_f32_e32 v86, v86
	v_rcp_f32_e32 v87, v87
	v_add_f32_e32 v88, 1.0, v88
	v_add_f32_e32 v89, 1.0, v89
	v_pk_mul_f32 v[78:79], v[78:79], v[82:83]
	v_rcp_f32_e32 v88, v88
	v_rcp_f32_e32 v89, v89
	v_pk_mul_f32 v[70:71], v[78:79], v[70:71]
	v_pk_mul_f32 v[78:79], v[80:81], v[84:85]
	v_cvt_pk_f16_f32 v70, v70, v71
	v_pk_mul_f32 v[72:73], v[78:79], v[72:73]
	s_nop 0
	v_cvt_pk_f16_f32 v71, v72, v73
	v_pk_mul_f32 v[72:73], v[74:75], v[86:87]
	v_add_u32_e32 v74, 0x80, v140
	v_pk_mul_f32 v[66:67], v[72:73], v[66:67]
	s_nop 0
	v_cvt_pk_f16_f32 v72, v66, v67
	v_pk_mul_f32 v[66:67], v[76:77], v[88:89]
	s_nop 0
	v_pk_mul_f32 v[66:67], v[66:67], v[68:69]
	v_mul_f32_e32 v68, 0xbfb8aa3b, v64
	v_cvt_pk_f16_f32 v73, v66, v67
	v_or_b32_e32 v66, 48, v140
	v_mad_i64_i32 v[66:67], s[10:11], v66, s3, v[114:115]
	v_lshl_add_u64 v[66:67], v[66:67], 0, v[116:117]
	global_store_dwordx4 v[66:67], v[70:73], off
	v_mul_f32_e32 v66, 0xbfb8aa3b, v62
	v_mul_f32_e32 v67, 0xbfb8aa3b, v63
	v_exp_f32_e32 v66, v66
	v_exp_f32_e32 v67, v67
	v_mul_f32_e32 v69, 0xbfb8aa3b, v65
	v_exp_f32_e32 v68, v68
	v_exp_f32_e32 v69, v69
	v_mul_f32_e32 v70, 0xbfb8aa3b, v58
	v_mul_f32_e32 v71, 0xbfb8aa3b, v59
	v_exp_f32_e32 v70, v70
	v_exp_f32_e32 v71, v71
	v_mul_f32_e32 v72, 0xbfb8aa3b, v60
	v_mul_f32_e32 v73, 0xbfb8aa3b, v61
	v_add_f32_e32 v66, 1.0, v66
	v_add_f32_e32 v67, 1.0, v67
	v_exp_f32_e32 v72, v72
	v_exp_f32_e32 v73, v73
	v_rcp_f32_e32 v66, v66
	v_rcp_f32_e32 v67, v67
	v_add_f32_e32 v68, 1.0, v68
	v_add_f32_e32 v69, 1.0, v69
	v_rcp_f32_e32 v68, v68
	v_rcp_f32_e32 v69, v69
	v_add_f32_e32 v70, 1.0, v70
	v_add_f32_e32 v71, 1.0, v71
	v_rcp_f32_e32 v70, v70
	v_rcp_f32_e32 v71, v71
	v_add_f32_e32 v72, 1.0, v72
	v_add_f32_e32 v73, 1.0, v73
	v_pk_mul_f32 v[62:63], v[62:63], v[66:67]
	v_rcp_f32_e32 v72, v72
	v_rcp_f32_e32 v73, v73
	v_pk_mul_f32 v[54:55], v[62:63], v[54:55]
	v_pk_mul_f32 v[62:63], v[64:65], v[68:69]
	v_cvt_pk_f16_f32 v54, v54, v55
	v_pk_mul_f32 v[56:57], v[62:63], v[56:57]
	s_nop 0
	v_cvt_pk_f16_f32 v55, v56, v57
	v_pk_mul_f32 v[56:57], v[58:59], v[70:71]
	s_nop 0
	v_pk_mul_f32 v[50:51], v[56:57], v[50:51]
	s_nop 0
	v_cvt_pk_f16_f32 v56, v50, v51
	v_pk_mul_f32 v[50:51], v[60:61], v[72:73]
	s_nop 0
	v_pk_mul_f32 v[50:51], v[50:51], v[52:53]
	v_mul_f32_e32 v52, 0xbfb8aa3b, v48
	v_cvt_pk_f16_f32 v57, v50, v51
	v_mad_i64_i32 v[50:51], s[10:11], v74, s3, v[114:115]
	v_lshl_add_u64 v[50:51], v[50:51], 0, v[116:117]
	global_store_dwordx4 v[50:51], v[54:57], off
	v_mul_f32_e32 v50, 0xbfb8aa3b, v46
	v_mul_f32_e32 v51, 0xbfb8aa3b, v47
	v_exp_f32_e32 v50, v50
	v_exp_f32_e32 v51, v51
	v_mul_f32_e32 v53, 0xbfb8aa3b, v49
	v_exp_f32_e32 v52, v52
	v_exp_f32_e32 v53, v53
	v_mul_f32_e32 v54, 0xbfb8aa3b, v42
	v_mul_f32_e32 v55, 0xbfb8aa3b, v43
	v_exp_f32_e32 v54, v54
	v_exp_f32_e32 v55, v55
	v_mul_f32_e32 v56, 0xbfb8aa3b, v44
	v_mul_f32_e32 v57, 0xbfb8aa3b, v45
	v_add_f32_e32 v50, 1.0, v50
	v_add_f32_e32 v51, 1.0, v51
	v_exp_f32_e32 v56, v56
	v_exp_f32_e32 v57, v57
	v_rcp_f32_e32 v50, v50
	v_rcp_f32_e32 v51, v51
	v_add_f32_e32 v52, 1.0, v52
	v_add_f32_e32 v53, 1.0, v53
	v_rcp_f32_e32 v52, v52
	v_rcp_f32_e32 v53, v53
	v_add_f32_e32 v54, 1.0, v54
	v_add_f32_e32 v55, 1.0, v55
	v_rcp_f32_e32 v54, v54
	v_rcp_f32_e32 v55, v55
	v_add_f32_e32 v56, 1.0, v56
	v_add_f32_e32 v57, 1.0, v57
	v_pk_mul_f32 v[46:47], v[46:47], v[50:51]
	v_rcp_f32_e32 v56, v56
	v_rcp_f32_e32 v57, v57
	v_pk_mul_f32 v[38:39], v[46:47], v[38:39]
	v_pk_mul_f32 v[46:47], v[48:49], v[52:53]
	v_cvt_pk_f16_f32 v38, v38, v39
	v_pk_mul_f32 v[40:41], v[46:47], v[40:41]
	s_nop 0
	v_cvt_pk_f16_f32 v39, v40, v41
	v_pk_mul_f32 v[40:41], v[42:43], v[54:55]
	s_nop 0
	v_pk_mul_f32 v[34:35], v[40:41], v[34:35]
	s_nop 0
	v_cvt_pk_f16_f32 v40, v34, v35
	v_pk_mul_f32 v[34:35], v[44:45], v[56:57]
	s_nop 0
	v_pk_mul_f32 v[34:35], v[34:35], v[36:37]
	v_mul_f32_e32 v36, 0xbfb8aa3b, v30
	v_cvt_pk_f16_f32 v41, v34, v35
	v_add_u32_e32 v34, 0x90, v140
	v_mad_i64_i32 v[34:35], s[10:11], v34, s3, v[114:115]
	v_lshl_add_u64 v[34:35], v[34:35], 0, v[116:117]
	global_store_dwordx4 v[34:35], v[38:41], off
	v_mul_f32_e32 v34, 0xbfb8aa3b, v28
	v_mul_f32_e32 v35, 0xbfb8aa3b, v29
	v_exp_f32_e32 v34, v34
	v_exp_f32_e32 v35, v35
	v_mul_f32_e32 v37, 0xbfb8aa3b, v31
	v_exp_f32_e32 v36, v36
	v_exp_f32_e32 v37, v37
	v_mul_f32_e32 v38, 0xbfb8aa3b, v24
	v_mul_f32_e32 v39, 0xbfb8aa3b, v25
	v_exp_f32_e32 v38, v38
	v_exp_f32_e32 v39, v39
	v_mul_f32_e32 v40, 0xbfb8aa3b, v26
	v_mul_f32_e32 v41, 0xbfb8aa3b, v27
	v_add_f32_e32 v34, 1.0, v34
	v_add_f32_e32 v35, 1.0, v35
	v_exp_f32_e32 v40, v40
	v_exp_f32_e32 v41, v41
	v_rcp_f32_e32 v34, v34
	v_rcp_f32_e32 v35, v35
	v_add_f32_e32 v36, 1.0, v36
	v_add_f32_e32 v37, 1.0, v37
	v_rcp_f32_e32 v36, v36
	v_rcp_f32_e32 v37, v37
	v_add_f32_e32 v38, 1.0, v38
	v_add_f32_e32 v39, 1.0, v39
	v_rcp_f32_e32 v38, v38
	v_rcp_f32_e32 v39, v39
	v_add_f32_e32 v40, 1.0, v40
	v_add_f32_e32 v41, 1.0, v41
	v_pk_mul_f32 v[28:29], v[28:29], v[34:35]
	v_rcp_f32_e32 v40, v40
	v_rcp_f32_e32 v41, v41
	v_pk_mul_f32 v[20:21], v[28:29], v[20:21]
	v_pk_mul_f32 v[28:29], v[30:31], v[36:37]
	v_cvt_pk_f16_f32 v20, v20, v21
	v_pk_mul_f32 v[22:23], v[28:29], v[22:23]
	s_nop 0
	v_cvt_pk_f16_f32 v21, v22, v23
	v_pk_mul_f32 v[22:23], v[24:25], v[38:39]
	s_nop 0
	v_pk_mul_f32 v[16:17], v[22:23], v[16:17]
	s_nop 0
	v_cvt_pk_f16_f32 v22, v16, v17
	v_pk_mul_f32 v[16:17], v[26:27], v[40:41]
	s_nop 0
	v_pk_mul_f32 v[16:17], v[16:17], v[18:19]
	v_mul_f32_e32 v18, 0xbfb8aa3b, v14
	v_cvt_pk_f16_f32 v23, v16, v17
	v_add_u32_e32 v16, 0xa0, v140
	v_mad_i64_i32 v[16:17], s[10:11], v16, s3, v[114:115]
	v_lshl_add_u64 v[16:17], v[16:17], 0, v[116:117]
	global_store_dwordx4 v[16:17], v[20:23], off
	v_mul_f32_e32 v16, 0xbfb8aa3b, v12
	v_mul_f32_e32 v17, 0xbfb8aa3b, v13
	v_exp_f32_e32 v16, v16
	v_exp_f32_e32 v17, v17
	v_mul_f32_e32 v19, 0xbfb8aa3b, v15
	v_exp_f32_e32 v18, v18
	v_exp_f32_e32 v19, v19
	v_mul_f32_e32 v20, 0xbfb8aa3b, v8
	v_mul_f32_e32 v21, 0xbfb8aa3b, v9
	v_exp_f32_e32 v20, v20
	v_exp_f32_e32 v21, v21
	v_mul_f32_e32 v22, 0xbfb8aa3b, v10
	v_mul_f32_e32 v23, 0xbfb8aa3b, v11
	v_add_f32_e32 v16, 1.0, v16
	v_add_f32_e32 v17, 1.0, v17
	v_exp_f32_e32 v22, v22
	v_exp_f32_e32 v23, v23
	v_rcp_f32_e32 v16, v16
	v_rcp_f32_e32 v17, v17
	v_add_f32_e32 v18, 1.0, v18
	v_add_f32_e32 v19, 1.0, v19
	v_rcp_f32_e32 v18, v18
	v_rcp_f32_e32 v19, v19
	v_add_f32_e32 v20, 1.0, v20
	v_add_f32_e32 v21, 1.0, v21
	v_rcp_f32_e32 v20, v20
	v_rcp_f32_e32 v21, v21
	v_add_f32_e32 v22, 1.0, v22
	v_add_f32_e32 v23, 1.0, v23
	v_pk_mul_f32 v[12:13], v[12:13], v[16:17]
	v_rcp_f32_e32 v22, v22
	v_rcp_f32_e32 v23, v23
	v_pk_mul_f32 v[4:5], v[12:13], v[4:5]
	v_pk_mul_f32 v[12:13], v[14:15], v[18:19]
	v_cvt_pk_f16_f32 v4, v4, v5
	v_pk_mul_f32 v[6:7], v[12:13], v[6:7]
	s_nop 0
	v_cvt_pk_f16_f32 v5, v6, v7
	v_pk_mul_f32 v[6:7], v[8:9], v[20:21]
	s_nop 0
	v_pk_mul_f32 v[0:1], v[6:7], v[0:1]
	s_nop 0
	v_cvt_pk_f16_f32 v6, v0, v1
	v_pk_mul_f32 v[0:1], v[10:11], v[22:23]
	s_nop 0
	v_pk_mul_f32 v[0:1], v[0:1], v[2:3]
	s_nop 0
	v_cvt_pk_f16_f32 v7, v0, v1
	v_add_u32_e32 v0, 0xb0, v140
	v_mad_i64_i32 v[0:1], s[10:11], v0, s3, v[114:115]
	v_lshl_add_u64 v[0:1], v[0:1], 0, v[116:117]
	global_store_dwordx4 v[0:1], v[4:7], off
	s_cmp_lg_u32 s34, 1
	s_cbranch_scc1 .Lups_skip
	s_and_b32 s0, s91, 63
	s_cmp_gt_u32 s0, 5
	s_cbranch_scc1 .Lups_skip
	s_cmp_gt_u32 s91, 196
	s_cbranch_scc1 .Lups_skip
	s_waitcnt vmcnt(0)
	s_barrier
	v_readlane_b32 s0, v251, 36
	s_cmp_lg_u32 s0, 0
	s_cbranch_scc1 .Lups_skip
	buffer_wbl2 sc1
	s_waitcnt vmcnt(0)
	v_readlane_b32 s2, v255, 45
	v_readlane_b32 s3, v254, 25
	s_lshl_b32 s2, s2, 1
	s_cmp_eq_u32 s3, 0
	s_cselect_b32 s3, 1, 0
	s_add_i32 s2, s2, s3
	s_lshl_b32 s2, s2, 2
	s_add_i32 s2, s2, 14016
	v_readlane_b32 s0, v251, 32
	v_readlane_b32 s1, v251, 33
	s_add_u32 s0, s0, s2
	s_addc_u32 s1, s1, 0
	s_mov_b64 s[2:3], exec
	s_mov_b64 exec, 1
	global_atomic_add v33, v248, s[0:1]
	s_mov_b64 exec, s[2:3]

.LBB0_1365:
	s_add_i32 s46, s14, 2
	s_add_u32 s12, s10, 0x100
	s_addc_u32 s13, s11, 0
	s_add_i32 s47, 0, 0x10000
	v_add_u32_e32 v134, s47, v230
	ds_read_b128 v[106:109], v134
	ds_read_b128 v[114:117], v134 offset:2048
	ds_read_b128 v[110:113], v134 offset:1024
	ds_read_b128 v[134:137], v134 offset:3072
	s_cmp_eq_u32 s43, s14
	s_cselect_b32 s14, s8, s44
	s_cselect_b32 s17, s7, s13
	s_cselect_b32 s16, s6, s12
	s_cselect_b32 s15, s9, s45
	v_lshl_add_u64 v[178:179], s[10:11], 0, v[184:185]
	s_add_i32 m0, s24, 0xc000
	ds_read_b128 v[138:141], v232
	ds_read_b128 v[154:157], v232 offset:2048
	ds_read_b128 v[162:165], v232 offset:4096
	ds_read_b128 v[170:173], v232 offset:6144
	ds_read_b128 v[150:153], v232 offset:1024
	ds_read_b128 v[158:161], v232 offset:3072
	ds_read_b128 v[166:169], v232 offset:5120
	ds_read_b128 v[174:177], v232 offset:7168
	global_load_lds_dwordx4 v[178:179], off
	v_lshl_add_u64 v[178:179], s[10:11], 0, v[186:187]
	s_add_i32 m0, s24, 0xe000
	s_nop 0
	global_load_lds_dwordx4 v[178:179], off
	s_waitcnt lgkmcnt(8)
	s_barrier
	s_waitcnt lgkmcnt(7)
	s_setprio 1
	v_mfma_f32_16x16x32_f16 v[146:149], v[106:109], v[138:141], v[146:149]
	v_mfma_f32_16x16x32_f16 v[142:145], v[114:117], v[138:141], v[142:145]
	s_waitcnt lgkmcnt(6)
	v_mfma_f32_16x16x32_f16 v[130:133], v[106:109], v[154:157], v[130:133]
	v_mfma_f32_16x16x32_f16 v[122:125], v[114:117], v[154:157], v[122:125]
	s_waitcnt lgkmcnt(5)
	v_mfma_f32_16x16x32_f16 v[94:97], v[106:109], v[162:165], v[94:97]
	v_mfma_f32_16x16x32_f16 v[90:93], v[114:117], v[162:165], v[90:93]
	s_waitcnt lgkmcnt(4)
	v_mfma_f32_16x16x32_f16 v[78:81], v[106:109], v[170:173], v[78:81]
	v_mfma_f32_16x16x32_f16 v[74:77], v[114:117], v[170:173], v[74:77]
	s_waitcnt lgkmcnt(3)
	v_mfma_f32_16x16x32_f16 v[146:149], v[110:113], v[150:153], v[146:149]
	v_mfma_f32_16x16x32_f16 v[142:145], v[134:137], v[150:153], v[142:145]
	s_waitcnt lgkmcnt(2)
	v_mfma_f32_16x16x32_f16 v[130:133], v[110:113], v[158:161], v[130:133]
	v_mfma_f32_16x16x32_f16 v[122:125], v[134:137], v[158:161], v[122:125]
	s_waitcnt lgkmcnt(1)
	v_mfma_f32_16x16x32_f16 v[94:97], v[110:113], v[166:169], v[94:97]
	v_mfma_f32_16x16x32_f16 v[90:93], v[134:137], v[166:169], v[90:93]
	s_waitcnt lgkmcnt(0)
	v_mfma_f32_16x16x32_f16 v[78:81], v[110:113], v[174:177], v[78:81]
	v_mfma_f32_16x16x32_f16 v[74:77], v[134:137], v[174:177], v[74:77]
	s_setprio 0
	s_barrier
	s_add_i32 s48, 0, 0x14000
	s_add_i32 s10, s47, s23
	v_add_u32_e32 v196, s48, v230
	v_lshl_add_u64 v[200:201], s[14:15], 0, v[32:33]
	s_mov_b32 m0, s10
	ds_read_b128 v[178:181], v196
	ds_read_b128 v[192:195], v196 offset:2048
	ds_read_b128 v[188:191], v196 offset:1024
	ds_read_b128 v[196:199], v196 offset:3072
	global_load_lds_dwordx4 v[200:201], off
	v_lshl_add_u64 v[202:203], s[14:15], 0, v[182:183]
	s_add_i32 m0, s10, 0x2000
	s_nop 0
	global_load_lds_dwordx4 v[202:203], off
	s_barrier
	s_waitcnt lgkmcnt(2)
	s_setprio 1
	v_mfma_f32_16x16x32_f16 v[126:129], v[178:181], v[138:141], v[126:129]
	v_mfma_f32_16x16x32_f16 v[118:121], v[192:195], v[138:141], v[118:121]
	v_mfma_f32_16x16x32_f16 v[102:105], v[178:181], v[154:157], v[102:105]
	v_mfma_f32_16x16x32_f16 v[98:101], v[192:195], v[154:157], v[98:101]
	v_mfma_f32_16x16x32_f16 v[86:89], v[178:181], v[162:165], v[86:89]
	v_mfma_f32_16x16x32_f16 v[82:85], v[192:195], v[162:165], v[82:85]
	v_mfma_f32_16x16x32_f16 v[70:73], v[178:181], v[170:173], v[70:73]
	v_mfma_f32_16x16x32_f16 v[66:69], v[192:195], v[170:173], v[66:69]
	s_waitcnt lgkmcnt(0)
	v_mfma_f32_16x16x32_f16 v[126:129], v[188:191], v[150:153], v[126:129]
	v_mfma_f32_16x16x32_f16 v[118:121], v[196:199], v[150:153], v[118:121]
	v_mfma_f32_16x16x32_f16 v[102:105], v[188:191], v[158:161], v[102:105]
	v_mfma_f32_16x16x32_f16 v[98:101], v[196:199], v[158:161], v[98:101]
	v_mfma_f32_16x16x32_f16 v[86:89], v[188:191], v[166:169], v[86:89]
	v_mfma_f32_16x16x32_f16 v[82:85], v[196:199], v[166:169], v[82:85]
	v_mfma_f32_16x16x32_f16 v[70:73], v[188:191], v[174:177], v[70:73]
	v_mfma_f32_16x16x32_f16 v[66:69], v[196:199], v[174:177], v[66:69]
	s_setprio 0
	s_mov_b32 m0, s24
	v_lshl_add_u64 v[204:205], s[16:17], 0, v[32:33]
	s_barrier
	ds_read_b128 v[138:141], v232 offset:16384
	ds_read_b128 v[154:157], v232 offset:18432
	ds_read_b128 v[162:165], v232 offset:20480
	ds_read_b128 v[170:173], v232 offset:22528
	ds_read_b128 v[150:153], v232 offset:17408
	ds_read_b128 v[158:161], v232 offset:19456
	ds_read_b128 v[166:169], v232 offset:21504
	ds_read_b128 v[174:177], v232 offset:23552
	global_load_lds_dwordx4 v[204:205], off
	v_lshl_add_u64 v[206:207], s[16:17], 0, v[182:183]
	s_mov_b32 m0, s25
	s_nop 0
	global_load_lds_dwordx4 v[206:207], off
	s_waitcnt vmcnt(10)
	s_barrier
	s_waitcnt lgkmcnt(7)
	s_setprio 1
	v_mfma_f32_16x16x32_f16 v[62:65], v[106:109], v[138:141], v[62:65]
	v_mfma_f32_16x16x32_f16 v[58:61], v[114:117], v[138:141], v[58:61]
	s_waitcnt lgkmcnt(6)
	v_mfma_f32_16x16x32_f16 v[46:49], v[106:109], v[154:157], v[46:49]
	v_mfma_f32_16x16x32_f16 v[42:45], v[114:117], v[154:157], v[42:45]
	s_waitcnt lgkmcnt(5)
	v_mfma_f32_16x16x32_f16 v[28:31], v[106:109], v[162:165], v[28:31]
	v_mfma_f32_16x16x32_f16 v[24:27], v[114:117], v[162:165], v[24:27]
	s_waitcnt lgkmcnt(4)
	v_mfma_f32_16x16x32_f16 v[12:15], v[106:109], v[170:173], v[12:15]
	v_mfma_f32_16x16x32_f16 v[8:11], v[114:117], v[170:173], v[8:11]
	s_waitcnt lgkmcnt(3)
	v_mfma_f32_16x16x32_f16 v[62:65], v[110:113], v[150:153], v[62:65]
	v_mfma_f32_16x16x32_f16 v[58:61], v[134:137], v[150:153], v[58:61]
	s_waitcnt lgkmcnt(2)
	v_mfma_f32_16x16x32_f16 v[46:49], v[110:113], v[158:161], v[46:49]
	v_mfma_f32_16x16x32_f16 v[42:45], v[134:137], v[158:161], v[42:45]
	s_waitcnt lgkmcnt(1)
	v_mfma_f32_16x16x32_f16 v[28:31], v[110:113], v[166:169], v[28:31]
	v_mfma_f32_16x16x32_f16 v[24:27], v[134:137], v[166:169], v[24:27]
	s_waitcnt lgkmcnt(0)
	v_mfma_f32_16x16x32_f16 v[12:15], v[110:113], v[174:177], v[12:15]
	v_mfma_f32_16x16x32_f16 v[8:11], v[134:137], v[174:177], v[8:11]
	s_setprio 0
	s_barrier
	s_add_u32 s10, s14, 0xb0000
	s_addc_u32 s11, s15, 0
	s_add_i32 s47, s48, s23
	v_lshl_add_u64 v[106:107], s[10:11], 0, v[32:33]
	s_mov_b32 m0, s47
	s_nop 0
	global_load_lds_dwordx4 v[106:107], off
	v_lshl_add_u64 v[106:107], s[10:11], 0, v[182:183]
	s_add_i32 m0, s47, 0x2000
	s_nop 0
	global_load_lds_dwordx4 v[106:107], off
	v_add_u32_e32 v134, 0x18000, v230
	ds_read_b128 v[106:109], v134
	ds_read_b128 v[114:117], v134 offset:2048
	ds_read_b128 v[110:113], v134 offset:1024
	ds_read_b128 v[134:137], v134 offset:3072
	s_waitcnt vmcnt(6)
	s_barrier
	s_setprio 1
	v_mfma_f32_16x16x32_f16 v[54:57], v[178:181], v[138:141], v[54:57]
	v_mfma_f32_16x16x32_f16 v[50:53], v[192:195], v[138:141], v[50:53]
	v_mfma_f32_16x16x32_f16 v[38:41], v[178:181], v[154:157], v[38:41]
	v_mfma_f32_16x16x32_f16 v[34:37], v[192:195], v[154:157], v[34:37]
	v_mfma_f32_16x16x32_f16 v[20:23], v[178:181], v[162:165], v[20:23]
	v_mfma_f32_16x16x32_f16 v[16:19], v[192:195], v[162:165], v[16:19]
	v_mfma_f32_16x16x32_f16 v[4:7], v[178:181], v[170:173], v[4:7]
	v_mfma_f32_16x16x32_f16 v[0:3], v[192:195], v[170:173], v[0:3]
	v_mfma_f32_16x16x32_f16 v[54:57], v[188:191], v[150:153], v[54:57]
	v_mfma_f32_16x16x32_f16 v[50:53], v[196:199], v[150:153], v[50:53]
	v_mfma_f32_16x16x32_f16 v[38:41], v[188:191], v[158:161], v[38:41]
	v_mfma_f32_16x16x32_f16 v[34:37], v[196:199], v[158:161], v[34:37]
	v_mfma_f32_16x16x32_f16 v[20:23], v[188:191], v[166:169], v[20:23]
	v_mfma_f32_16x16x32_f16 v[16:19], v[196:199], v[166:169], v[16:19]
	v_mfma_f32_16x16x32_f16 v[4:7], v[188:191], v[174:177], v[4:7]
	v_mfma_f32_16x16x32_f16 v[0:3], v[196:199], v[174:177], v[0:3]
	s_setprio 0
	s_add_i32 s47, 0, 0x18000
	s_barrier
	s_add_u32 s10, s16, 0xb0000
	s_addc_u32 s11, s17, 0
	s_mov_b32 m0, s26
	v_lshl_add_u64 v[178:179], s[10:11], 0, v[32:33]
	ds_read_b128 v[138:141], v232 offset:32768
	ds_read_b128 v[154:157], v232 offset:34816
	ds_read_b128 v[162:165], v232 offset:36864
	ds_read_b128 v[170:173], v232 offset:38912
	ds_read_b128 v[150:153], v232 offset:33792
	ds_read_b128 v[158:161], v232 offset:35840
	ds_read_b128 v[166:169], v232 offset:37888
	ds_read_b128 v[174:177], v232 offset:39936
	global_load_lds_dwordx4 v[178:179], off
	v_lshl_add_u64 v[178:179], s[10:11], 0, v[182:183]
	s_mov_b32 m0, s27
	s_nop 0
	global_load_lds_dwordx4 v[178:179], off
	s_waitcnt lgkmcnt(8)
	s_barrier
	s_waitcnt lgkmcnt(7)
	s_setprio 1
	v_mfma_f32_16x16x32_f16 v[146:149], v[106:109], v[138:141], v[146:149]
	v_mfma_f32_16x16x32_f16 v[142:145], v[114:117], v[138:141], v[142:145]
	s_waitcnt lgkmcnt(6)
	v_mfma_f32_16x16x32_f16 v[130:133], v[106:109], v[154:157], v[130:133]
	v_mfma_f32_16x16x32_f16 v[122:125], v[114:117], v[154:157], v[122:125]
	s_waitcnt lgkmcnt(5)
	v_mfma_f32_16x16x32_f16 v[94:97], v[106:109], v[162:165], v[94:97]
	v_mfma_f32_16x16x32_f16 v[90:93], v[114:117], v[162:165], v[90:93]
	s_waitcnt lgkmcnt(4)
	v_mfma_f32_16x16x32_f16 v[78:81], v[106:109], v[170:173], v[78:81]
	v_mfma_f32_16x16x32_f16 v[74:77], v[114:117], v[170:173], v[74:77]
	s_waitcnt lgkmcnt(3)
	v_mfma_f32_16x16x32_f16 v[146:149], v[110:113], v[150:153], v[146:149]
	v_mfma_f32_16x16x32_f16 v[142:145], v[134:137], v[150:153], v[142:145]
	s_waitcnt lgkmcnt(2)
	v_mfma_f32_16x16x32_f16 v[130:133], v[110:113], v[158:161], v[130:133]
	v_mfma_f32_16x16x32_f16 v[122:125], v[134:137], v[158:161], v[122:125]
	s_waitcnt lgkmcnt(1)
	v_mfma_f32_16x16x32_f16 v[94:97], v[110:113], v[166:169], v[94:97]
	v_mfma_f32_16x16x32_f16 v[90:93], v[134:137], v[166:169], v[90:93]
	s_waitcnt lgkmcnt(0)
	v_mfma_f32_16x16x32_f16 v[78:81], v[110:113], v[174:177], v[78:81]
	v_mfma_f32_16x16x32_f16 v[74:77], v[134:137], v[174:177], v[74:77]
	s_setprio 0
	s_barrier
	s_add_i32 s16, 0, 0x1c000
	s_add_i32 s10, s47, s23
	v_add_u32_e32 v196, s16, v230
	v_lshl_add_u64 v[200:201], v[200:201], 0, s[84:85]
	s_mov_b32 m0, s10
	ds_read_b128 v[178:181], v196
	ds_read_b128 v[192:195], v196 offset:2048
	ds_read_b128 v[188:191], v196 offset:1024
	ds_read_b128 v[196:199], v196 offset:3072
	global_load_lds_dwordx4 v[200:201], off
	v_lshl_add_u64 v[200:201], v[202:203], 0, s[84:85]
	s_add_i32 m0, s10, 0x2000
	s_nop 0
	global_load_lds_dwordx4 v[200:201], off
	s_barrier
	s_waitcnt lgkmcnt(2)
	s_setprio 1
	v_mfma_f32_16x16x32_f16 v[126:129], v[178:181], v[138:141], v[126:129]
	v_mfma_f32_16x16x32_f16 v[118:121], v[192:195], v[138:141], v[118:121]
	v_mfma_f32_16x16x32_f16 v[102:105], v[178:181], v[154:157], v[102:105]
	v_mfma_f32_16x16x32_f16 v[98:101], v[192:195], v[154:157], v[98:101]
	v_mfma_f32_16x16x32_f16 v[86:89], v[178:181], v[162:165], v[86:89]
	v_mfma_f32_16x16x32_f16 v[82:85], v[192:195], v[162:165], v[82:85]
	v_mfma_f32_16x16x32_f16 v[70:73], v[178:181], v[170:173], v[70:73]
	v_mfma_f32_16x16x32_f16 v[66:69], v[192:195], v[170:173], v[66:69]
	s_waitcnt lgkmcnt(0)
	v_mfma_f32_16x16x32_f16 v[126:129], v[188:191], v[150:153], v[126:129]
	v_mfma_f32_16x16x32_f16 v[118:121], v[196:199], v[150:153], v[118:121]
	v_mfma_f32_16x16x32_f16 v[102:105], v[188:191], v[158:161], v[102:105]
	v_mfma_f32_16x16x32_f16 v[98:101], v[196:199], v[158:161], v[98:101]
	v_mfma_f32_16x16x32_f16 v[86:89], v[188:191], v[166:169], v[86:89]
	v_mfma_f32_16x16x32_f16 v[82:85], v[196:199], v[166:169], v[82:85]
	v_mfma_f32_16x16x32_f16 v[70:73], v[188:191], v[174:177], v[70:73]
	v_mfma_f32_16x16x32_f16 v[66:69], v[196:199], v[174:177], v[66:69]
	s_setprio 0
	s_mov_b32 m0, s29
	v_lshl_add_u64 v[200:201], v[204:205], 0, s[84:85]
	s_barrier
	ds_read_b128 v[138:141], v232 offset:49152
	ds_read_b128 v[154:157], v232 offset:51200
	ds_read_b128 v[162:165], v232 offset:53248
	ds_read_b128 v[170:173], v232 offset:55296
	ds_read_b128 v[150:153], v232 offset:50176
	ds_read_b128 v[158:161], v232 offset:52224
	ds_read_b128 v[166:169], v232 offset:54272
	ds_read_b128 v[174:177], v232 offset:56320
	global_load_lds_dwordx4 v[200:201], off
	v_lshl_add_u64 v[200:201], v[206:207], 0, s[84:85]
	s_mov_b32 m0, s30
	s_nop 0
	global_load_lds_dwordx4 v[200:201], off
	s_barrier
	s_waitcnt lgkmcnt(7)
	s_setprio 1
	v_mfma_f32_16x16x32_f16 v[62:65], v[106:109], v[138:141], v[62:65]
	v_mfma_f32_16x16x32_f16 v[58:61], v[114:117], v[138:141], v[58:61]
	s_waitcnt lgkmcnt(6)
	v_mfma_f32_16x16x32_f16 v[46:49], v[106:109], v[154:157], v[46:49]
	v_mfma_f32_16x16x32_f16 v[42:45], v[114:117], v[154:157], v[42:45]
	s_waitcnt lgkmcnt(5)
	v_mfma_f32_16x16x32_f16 v[28:31], v[106:109], v[162:165], v[28:31]
	v_mfma_f32_16x16x32_f16 v[24:27], v[114:117], v[162:165], v[24:27]
	s_waitcnt lgkmcnt(4)
	v_mfma_f32_16x16x32_f16 v[12:15], v[106:109], v[170:173], v[12:15]
	v_mfma_f32_16x16x32_f16 v[8:11], v[114:117], v[170:173], v[8:11]
	s_waitcnt lgkmcnt(3)
	v_mfma_f32_16x16x32_f16 v[62:65], v[110:113], v[150:153], v[62:65]
	v_mfma_f32_16x16x32_f16 v[58:61], v[134:137], v[150:153], v[58:61]
	s_waitcnt lgkmcnt(2)
	v_mfma_f32_16x16x32_f16 v[46:49], v[110:113], v[158:161], v[46:49]
	v_mfma_f32_16x16x32_f16 v[42:45], v[134:137], v[158:161], v[42:45]
	s_waitcnt lgkmcnt(1)
	v_mfma_f32_16x16x32_f16 v[28:31], v[110:113], v[166:169], v[28:31]
	v_mfma_f32_16x16x32_f16 v[24:27], v[134:137], v[166:169], v[24:27]
	s_waitcnt lgkmcnt(0)
	v_mfma_f32_16x16x32_f16 v[12:15], v[110:113], v[174:177], v[12:15]
	v_mfma_f32_16x16x32_f16 v[8:11], v[134:137], v[174:177], v[8:11]
	s_setprio 0
	s_barrier
	s_add_u32 s10, s14, 0xb0080
	s_addc_u32 s11, s15, 0
	s_add_i32 s14, s16, s23
	v_lshl_add_u64 v[106:107], s[10:11], 0, v[32:33]
	s_mov_b32 m0, s14
	s_nop 0
	global_load_lds_dwordx4 v[106:107], off
	v_lshl_add_u64 v[106:107], s[10:11], 0, v[182:183]
	s_add_i32 m0, s14, 0x2000
	s_nop 0
	global_load_lds_dwordx4 v[106:107], off
	s_waitcnt vmcnt(6)
	s_barrier
	s_setprio 1
	v_mfma_f32_16x16x32_f16 v[54:57], v[178:181], v[138:141], v[54:57]
	v_mfma_f32_16x16x32_f16 v[50:53], v[192:195], v[138:141], v[50:53]
	v_mfma_f32_16x16x32_f16 v[38:41], v[178:181], v[154:157], v[38:41]
	v_mfma_f32_16x16x32_f16 v[34:37], v[192:195], v[154:157], v[34:37]
	v_mfma_f32_16x16x32_f16 v[20:23], v[178:181], v[162:165], v[20:23]
	v_mfma_f32_16x16x32_f16 v[16:19], v[192:195], v[162:165], v[16:19]
	v_mfma_f32_16x16x32_f16 v[4:7], v[178:181], v[170:173], v[4:7]
	v_mfma_f32_16x16x32_f16 v[0:3], v[192:195], v[170:173], v[0:3]
	v_mfma_f32_16x16x32_f16 v[54:57], v[188:191], v[150:153], v[54:57]
	v_mfma_f32_16x16x32_f16 v[50:53], v[196:199], v[150:153], v[50:53]
	v_mfma_f32_16x16x32_f16 v[38:41], v[188:191], v[158:161], v[38:41]
	v_mfma_f32_16x16x32_f16 v[34:37], v[196:199], v[158:161], v[34:37]
	v_mfma_f32_16x16x32_f16 v[20:23], v[188:191], v[166:169], v[20:23]
	v_mfma_f32_16x16x32_f16 v[16:19], v[196:199], v[166:169], v[16:19]
	v_mfma_f32_16x16x32_f16 v[4:7], v[188:191], v[174:177], v[4:7]
	v_mfma_f32_16x16x32_f16 v[0:3], v[196:199], v[174:177], v[0:3]
	s_setprio 0
	s_add_u32 s44, s44, 0x100
	s_addc_u32 s45, s45, 0
	s_cmp_ge_u32 s46, s42
	s_mov_b64 s[10:11], s[12:13]
	s_mov_b32 s14, s46
	s_barrier
	s_cbranch_scc0 .LBB0_1365
	s_cmp_eq_u32 s40, 0
	s_cselect_b32 s6, 0x9000, 0
	v_lshl_or_b32 v106, s41, 8, v231
	s_add_u32 s6, s31, s6
	s_addc_u32 s7, s34, 0
	v_ashrrev_i32_e32 v107, 31, v106
	v_lshl_add_u64 v[116:117], v[106:107], 2, s[6:7]
	global_load_dwordx4 v[108:111], v[116:117], off offset:16
	global_load_dwordx4 v[112:115], v[116:117], off
	s_cmp_eq_u32 s39, 0
	s_waitcnt vmcnt(0)
	v_pk_mul_f32 v[194:195], v[110:111], 0.5 op_sel_hi:[1,0]
	v_pk_mul_f32 v[198:199], v[114:115], 0.5 op_sel_hi:[1,0]
	v_pk_mul_f32 v[202:203], v[112:113], 0.5 op_sel_hi:[1,0]
	v_pk_mul_f32 v[200:201], v[108:109], 0.5 op_sel_hi:[1,0]
	global_load_dwordx4 v[108:111], v[116:117], off offset:528
	global_load_dwordx4 v[112:115], v[116:117], off offset:512
	s_waitcnt vmcnt(0)
	v_pk_mul_f32 v[188:189], v[110:111], 0.5 op_sel_hi:[1,0]
	v_pk_mul_f32 v[196:197], v[112:113], 0.5 op_sel_hi:[1,0]
	v_lshl_add_u32 v112, s40, 8, v229
	v_pk_mul_f32 v[190:191], v[114:115], 0.5 op_sel_hi:[1,0]
	v_pk_mul_f32 v[192:193], v[108:109], 0.5 op_sel_hi:[1,0]
	v_or_b32_e32 v114, 16, v112
	v_or_b32_e32 v110, 32, v112
	v_or_b32_e32 v108, 48, v112
	v_ashrrev_i32_e32 v113, 31, v112
	v_ashrrev_i32_e32 v115, 31, v114
	v_ashrrev_i32_e32 v111, 31, v110
	v_ashrrev_i32_e32 v109, 31, v108
	s_cbranch_scc1 .LBB0_1368
	s_add_i32 s96, s39, -1
	s_lshl_b64 s[6:7], s[96:97], 20
	v_readlane_b32 s8, v252, 11
	v_readlane_b32 s9, v252, 12
	s_add_u32 s6, s8, s6
	s_addc_u32 s7, s9, s7
	v_lshlrev_b64 v[138:139], 2, v[106:107]
	v_lshrrev_b32_e32 v150, 5, v220
	v_mul_u32_u24_e32 v150, 48, v150
	s_nop 0
	v_sub_co_u32_e32 v138, vcc, v138, v150
	s_nop 1
	v_subbrev_co_u32_e32 v139, vcc, 0, v139, vcc
	v_lshl_add_u64 v[138:139], s[6:7], 0, v[138:139]
	s_mov_b64 s[6:7], 0x80000
	v_lshlrev_b64 v[204:205], 12, v[112:113]
	v_lshl_add_u64 v[204:205], v[204:205], 0, v[138:139]
	v_lshl_add_u64 v[212:213], v[204:205], 0, s[6:7]
	v_lshlrev_b64 v[206:207], 12, v[114:115]
	v_lshl_add_u64 v[206:207], v[206:207], 0, v[138:139]
	v_lshl_add_u64 v[214:215], v[206:207], 0, s[6:7]
	v_lshlrev_b64 v[208:209], 12, v[110:111]
	v_lshl_add_u64 v[208:209], v[208:209], 0, v[138:139]
	v_lshl_add_u64 v[216:217], v[208:209], 0, s[6:7]
	v_lshlrev_b64 v[210:211], 12, v[108:109]
	v_lshl_add_u64 v[210:211], v[210:211], 0, v[138:139]
	v_lshl_add_u64 v[218:219], v[210:211], 0, s[6:7]
	s_waitcnt vmcnt(0)
	v_pk_mul_f32 v[152:153], v[146:147], v[202:203]
	v_pk_mul_f32 v[154:155], v[148:149], v[198:199]
	v_pk_mul_f32 v[156:157], v[142:143], v[200:201]
	v_pk_mul_f32 v[158:159], v[144:145], v[194:195]
	s_nop 1
	v_permlane32_swap_b32_e32 v152, v156
	v_permlane32_swap_b32_e32 v153, v157
	v_permlane32_swap_b32_e32 v154, v158
	v_permlane32_swap_b32_e32 v155, v159
	s_nop 0
	global_store_dwordx4 v[204:205], v[152:155], off
	global_store_dwordx4 v[204:205], v[156:159], off offset:64
	v_pk_mul_f32 v[160:161], v[126:127], v[196:197]
	v_pk_mul_f32 v[162:163], v[128:129], v[190:191]
	v_pk_mul_f32 v[164:165], v[118:119], v[192:193]
	v_pk_mul_f32 v[166:167], v[120:121], v[188:189]
	s_nop 1
	v_permlane32_swap_b32_e32 v160, v164
	v_permlane32_swap_b32_e32 v161, v165
	v_permlane32_swap_b32_e32 v162, v166
	v_permlane32_swap_b32_e32 v163, v167
	s_nop 0
	global_store_dwordx4 v[204:205], v[160:163], off offset:512
	global_store_dwordx4 v[204:205], v[164:167], off offset:576
	v_pk_mul_f32 v[168:169], v[130:131], v[202:203]
	v_pk_mul_f32 v[170:171], v[132:133], v[198:199]
	v_pk_mul_f32 v[172:173], v[122:123], v[200:201]
	v_pk_mul_f32 v[174:175], v[124:125], v[194:195]
	s_nop 1
	v_permlane32_swap_b32_e32 v168, v172
	v_permlane32_swap_b32_e32 v169, v173
	v_permlane32_swap_b32_e32 v170, v174
	v_permlane32_swap_b32_e32 v171, v175
	s_nop 0
	global_store_dwordx4 v[206:207], v[168:171], off
	global_store_dwordx4 v[206:207], v[172:175], off offset:64
	v_pk_mul_f32 v[176:177], v[102:103], v[196:197]
	v_pk_mul_f32 v[178:179], v[104:105], v[190:191]
	v_pk_mul_f32 v[180:181], v[98:99], v[192:193]
	v_pk_mul_f32 v[182:183], v[100:101], v[188:189]
	s_nop 1
	v_permlane32_swap_b32_e32 v176, v180
	v_permlane32_swap_b32_e32 v177, v181
	v_permlane32_swap_b32_e32 v178, v182
	v_permlane32_swap_b32_e32 v179, v183
	s_nop 0
	global_store_dwordx4 v[206:207], v[176:179], off offset:512
	global_store_dwordx4 v[206:207], v[180:183], off offset:576
	v_pk_mul_f32 v[152:153], v[94:95], v[202:203]
	v_pk_mul_f32 v[154:155], v[96:97], v[198:199]
	v_pk_mul_f32 v[156:157], v[90:91], v[200:201]
	v_pk_mul_f32 v[158:159], v[92:93], v[194:195]
	s_nop 1
	v_permlane32_swap_b32_e32 v152, v156
	v_permlane32_swap_b32_e32 v153, v157
	v_permlane32_swap_b32_e32 v154, v158
	v_permlane32_swap_b32_e32 v155, v159
	s_nop 0
	global_store_dwordx4 v[208:209], v[152:155], off
	global_store_dwordx4 v[208:209], v[156:159], off offset:64
	v_pk_mul_f32 v[160:161], v[86:87], v[196:197]
	v_pk_mul_f32 v[162:163], v[88:89], v[190:191]
	v_pk_mul_f32 v[164:165], v[82:83], v[192:193]
	v_pk_mul_f32 v[166:167], v[84:85], v[188:189]
	s_nop 1
	v_permlane32_swap_b32_e32 v160, v164
	v_permlane32_swap_b32_e32 v161, v165
	v_permlane32_swap_b32_e32 v162, v166
	v_permlane32_swap_b32_e32 v163, v167
	s_nop 0
	global_store_dwordx4 v[208:209], v[160:163], off offset:512
	global_store_dwordx4 v[208:209], v[164:167], off offset:576
	v_pk_mul_f32 v[168:169], v[78:79], v[202:203]
	v_pk_mul_f32 v[170:171], v[80:81], v[198:199]
	v_pk_mul_f32 v[172:173], v[74:75], v[200:201]
	v_pk_mul_f32 v[174:175], v[76:77], v[194:195]
	s_nop 1
	v_permlane32_swap_b32_e32 v168, v172
	v_permlane32_swap_b32_e32 v169, v173
	v_permlane32_swap_b32_e32 v170, v174
	v_permlane32_swap_b32_e32 v171, v175
	s_nop 0
	global_store_dwordx4 v[210:211], v[168:171], off
	global_store_dwordx4 v[210:211], v[172:175], off offset:64
	v_pk_mul_f32 v[176:177], v[70:71], v[196:197]
	v_pk_mul_f32 v[178:179], v[72:73], v[190:191]
	v_pk_mul_f32 v[180:181], v[66:67], v[192:193]
	v_pk_mul_f32 v[182:183], v[68:69], v[188:189]
	s_nop 1
	v_permlane32_swap_b32_e32 v176, v180
	v_permlane32_swap_b32_e32 v177, v181
	v_permlane32_swap_b32_e32 v178, v182
	v_permlane32_swap_b32_e32 v179, v183
	s_nop 0
	global_store_dwordx4 v[210:211], v[176:179], off offset:512
	global_store_dwordx4 v[210:211], v[180:183], off offset:576
	v_pk_mul_f32 v[152:153], v[62:63], v[202:203]
	v_pk_mul_f32 v[154:155], v[64:65], v[198:199]
	v_pk_mul_f32 v[156:157], v[58:59], v[200:201]
	v_pk_mul_f32 v[158:159], v[60:61], v[194:195]
	s_nop 1
	v_permlane32_swap_b32_e32 v152, v156
	v_permlane32_swap_b32_e32 v153, v157
	v_permlane32_swap_b32_e32 v154, v158
	v_permlane32_swap_b32_e32 v155, v159
	s_nop 0
	global_store_dwordx4 v[212:213], v[152:155], off
	global_store_dwordx4 v[212:213], v[156:159], off offset:64
	v_pk_mul_f32 v[160:161], v[54:55], v[196:197]
	v_pk_mul_f32 v[162:163], v[56:57], v[190:191]
	v_pk_mul_f32 v[164:165], v[50:51], v[192:193]
	v_pk_mul_f32 v[166:167], v[52:53], v[188:189]
	s_nop 1
	v_permlane32_swap_b32_e32 v160, v164
	v_permlane32_swap_b32_e32 v161, v165
	v_permlane32_swap_b32_e32 v162, v166
	v_permlane32_swap_b32_e32 v163, v167
	s_nop 0
	global_store_dwordx4 v[212:213], v[160:163], off offset:512
	global_store_dwordx4 v[212:213], v[164:167], off offset:576
	v_pk_mul_f32 v[168:169], v[46:47], v[202:203]
	v_pk_mul_f32 v[170:171], v[48:49], v[198:199]
	v_pk_mul_f32 v[172:173], v[42:43], v[200:201]
	v_pk_mul_f32 v[174:175], v[44:45], v[194:195]
	s_nop 1
	v_permlane32_swap_b32_e32 v168, v172
	v_permlane32_swap_b32_e32 v169, v173
	v_permlane32_swap_b32_e32 v170, v174
	v_permlane32_swap_b32_e32 v171, v175
	s_nop 0
	global_store_dwordx4 v[214:215], v[168:171], off
	global_store_dwordx4 v[214:215], v[172:175], off offset:64
	v_pk_mul_f32 v[176:177], v[38:39], v[196:197]
	v_pk_mul_f32 v[178:179], v[40:41], v[190:191]
	v_pk_mul_f32 v[180:181], v[34:35], v[192:193]
	v_pk_mul_f32 v[182:183], v[36:37], v[188:189]
	s_nop 1
	v_permlane32_swap_b32_e32 v176, v180
	v_permlane32_swap_b32_e32 v177, v181
	v_permlane32_swap_b32_e32 v178, v182
	v_permlane32_swap_b32_e32 v179, v183
	s_nop 0
	global_store_dwordx4 v[214:215], v[176:179], off offset:512
	global_store_dwordx4 v[214:215], v[180:183], off offset:576
	v_pk_mul_f32 v[152:153], v[28:29], v[202:203]
	v_pk_mul_f32 v[154:155], v[30:31], v[198:199]
	v_pk_mul_f32 v[156:157], v[24:25], v[200:201]
	v_pk_mul_f32 v[158:159], v[26:27], v[194:195]
	s_nop 1
	v_permlane32_swap_b32_e32 v152, v156
	v_permlane32_swap_b32_e32 v153, v157
	v_permlane32_swap_b32_e32 v154, v158
	v_permlane32_swap_b32_e32 v155, v159
	s_nop 0
	global_store_dwordx4 v[216:217], v[152:155], off
	global_store_dwordx4 v[216:217], v[156:159], off offset:64
	v_pk_mul_f32 v[160:161], v[20:21], v[196:197]
	v_pk_mul_f32 v[162:163], v[22:23], v[190:191]
	v_pk_mul_f32 v[164:165], v[16:17], v[192:193]
	v_pk_mul_f32 v[166:167], v[18:19], v[188:189]
	s_nop 1
	v_permlane32_swap_b32_e32 v160, v164
	v_permlane32_swap_b32_e32 v161, v165
	v_permlane32_swap_b32_e32 v162, v166
	v_permlane32_swap_b32_e32 v163, v167
	s_nop 0
	global_store_dwordx4 v[216:217], v[160:163], off offset:512
	global_store_dwordx4 v[216:217], v[164:167], off offset:576
	v_pk_mul_f32 v[168:169], v[12:13], v[202:203]
	v_pk_mul_f32 v[170:171], v[14:15], v[198:199]
	v_pk_mul_f32 v[172:173], v[8:9], v[200:201]
	v_pk_mul_f32 v[174:175], v[10:11], v[194:195]
	s_nop 1
	v_permlane32_swap_b32_e32 v168, v172
	v_permlane32_swap_b32_e32 v169, v173
	v_permlane32_swap_b32_e32 v170, v174
	v_permlane32_swap_b32_e32 v171, v175
	s_nop 0
	global_store_dwordx4 v[218:219], v[168:171], off
	global_store_dwordx4 v[218:219], v[172:175], off offset:64
	v_pk_mul_f32 v[176:177], v[4:5], v[196:197]
	v_pk_mul_f32 v[178:179], v[6:7], v[190:191]
	v_pk_mul_f32 v[180:181], v[0:1], v[192:193]
	v_pk_mul_f32 v[182:183], v[2:3], v[188:189]
	s_nop 1
	v_permlane32_swap_b32_e32 v176, v180
	v_permlane32_swap_b32_e32 v177, v181
	v_permlane32_swap_b32_e32 v178, v182
	v_permlane32_swap_b32_e32 v179, v183
	s_nop 0
	global_store_dwordx4 v[218:219], v[176:179], off offset:512
	global_store_dwordx4 v[218:219], v[180:183], off offset:576
	s_cbranch_execnz .LBB0_1352
	s_branch .LBB0_1351
